# v9_pool
# speedup vs baseline: 1.0409x; 1.0005x over previous
; __device__ __forceinline__ u32x4 pack8(const f32x4 v0, const f32x4 v1) { u32x4 w; w.x = cvt_pk_bf16(v0[0], v0[1]); w.y = cvt_pk_bf16(v0[2], v0[3]); w.z = cvt_pk_bf16(v1[0], v1[1]); w.w = cvt_pk_bf16(v1[2], v1[3]); return w; }
; __device__ __forceinline__ void unpack8(const u32x4 w, f32x4& lo, f32x4& hi) { lo = (f32x4){bf_lo(w.x), bf_hi(w.x), bf_lo(w.y), bf_hi(w.y)}; hi = (f32x4){bf_lo(w.z), bf_hi(w.z), bf_lo(w.w), bf_hi(w.w)}; }
; __device__ __forceinline__ void phase_pool(const bf16_t* PROJ, bf16_t* Z, int gw, int NGW, int lane) {
;     for (int it = gw; it < 2048; it += NGW) {
;         const int b = it >> 9, rem = it & 511, tseg = rem >> 2, gi = rem & 3, win = 2 << gi;
;         const bf16_t* vb = PROJ + (size_t)(b * SEQ) * DIN + 2048 + gi * 512 + lane * 8;
;         bf16_t* zb = Z + (size_t)(b * SEQ) * DSS + gi * 512 + lane * 8;
;         f32x4 s0 = {0.f, 0.f, 0.f, 0.f}, s1 = {0.f, 0.f, 0.f, 0.f};
;         const int t0 = tseg * 16;
;         for (int tau = (t0 - win + 1 > 0 ? t0 - win + 1 : 0); tau < t0; ++tau) { f32x4 a, c; unpack8(*(const u32x4*)(vb + (size_t)tau * DIN), a, c); s0 += a; s1 += c; }
;         for (int t = t0; t < t0 + 16; ++t) {
;             f32x4 v0, v1; unpack8(*(const u32x4*)(vb + (size_t)t * DIN), v0, v1); s0 += v0; s1 += v1;
;             if (t > t0 && t - win >= 0) { f32x4 a, c; unpack8(*(const u32x4*)(vb + (size_t)(t - win) * DIN), a, c); s0 -= a; s1 -= c; }
;             const float inv = 1.f / (float)((t + 1) < win ? (t + 1) : win);
;             *(u32x4*)(zb + (size_t)t * DSS) = pack8(s0 * inv - v0, s1 * inv - v1);
;         }
.LBB0_301:
	v_and_b32_e32 v39, 63, v254
	v_lshlrev_b32_e32 v39, 4, v39
	s_lshr_b32 s64, s63, 9
	s_bfe_u32 s65, s63, 0x70002
	s_and_b32 s66, s63, 3
	s_lshl_b32 s65, s65, 4
	s_lshl_b32 s64, s64, 11
	s_add_i32 s64, s64, s65
	s_mul_i32 s68, s64, 0x6000
	s_lshl_b32 s69, s66, 10
	s_add_u32 s68, s68, s69
	s_add_u32 s68, s68, 0x1f115000
	s_add_u32 s70, s58, s68
	s_addc_u32 s71, s59, 0
	s_lshl_b32 s36, s64, 12
	s_add_u32 s36, s36, s69
	s_add_u32 s36, s36, 0x2d114000
	s_add_u32 s36, s58, s36
	s_addc_u32 s37, s59, 0
	s_cmp_eq_u32 s66, 0
	s_cbranch_scc1 .Lpool_w2
	s_cmp_eq_u32 s66, 1
	s_cbranch_scc1 .Lpool_w4
	s_cmp_eq_u32 s66, 2
	s_cbranch_scc1 .Lpool_w8
.Lpool_w16:
	s_mov_b32 s72, 0x3d800000
	s_cmp_eq_u32 s65, 0
	s_cbranch_scc1 .Lpool_w16_zero
	s_sub_u32 s38, s70, 0x5a000
	s_subb_u32 s39, s71, 0
	global_load_dwordx4 v[160:163], v39, s[38:39]
	s_add_u32 s38, s38, 0x6000
	s_addc_u32 s39, s39, 0
	global_load_dwordx4 v[156:159], v39, s[38:39]
	s_add_u32 s38, s38, 0x6000
	s_addc_u32 s39, s39, 0
	global_load_dwordx4 v[152:155], v39, s[38:39]
	s_add_u32 s38, s38, 0x6000
	s_addc_u32 s39, s39, 0
	global_load_dwordx4 v[148:151], v39, s[38:39]
	s_add_u32 s38, s38, 0x6000
	s_addc_u32 s39, s39, 0
	global_load_dwordx4 v[144:147], v39, s[38:39]
	s_add_u32 s38, s38, 0x6000
	s_addc_u32 s39, s39, 0
	global_load_dwordx4 v[140:143], v39, s[38:39]
	s_add_u32 s38, s38, 0x6000
	s_addc_u32 s39, s39, 0
	global_load_dwordx4 v[136:139], v39, s[38:39]
	s_add_u32 s38, s38, 0x6000
	s_addc_u32 s39, s39, 0
	global_load_dwordx4 v[132:135], v39, s[38:39]
	s_add_u32 s38, s38, 0x6000
	s_addc_u32 s39, s39, 0
	global_load_dwordx4 v[128:131], v39, s[38:39]
	s_add_u32 s38, s38, 0x6000
	s_addc_u32 s39, s39, 0
	global_load_dwordx4 v[124:127], v39, s[38:39]
	s_add_u32 s38, s38, 0x6000
	s_addc_u32 s39, s39, 0
	global_load_dwordx4 v[120:123], v39, s[38:39]
	s_add_u32 s38, s38, 0x6000
	s_addc_u32 s39, s39, 0
	global_load_dwordx4 v[116:119], v39, s[38:39]
	s_add_u32 s38, s38, 0x6000
	s_addc_u32 s39, s39, 0
	global_load_dwordx4 v[112:115], v39, s[38:39]
	s_add_u32 s38, s38, 0x6000
	s_addc_u32 s39, s39, 0
	global_load_dwordx4 v[108:111], v39, s[38:39]
	s_add_u32 s38, s38, 0x6000
	s_addc_u32 s39, s39, 0
	global_load_dwordx4 v[104:107], v39, s[38:39]
	s_branch .Lpool_w16_a
.Lpool_w16_zero:
	v_mov_b32_e32 v104, 0
	v_mov_b32_e32 v105, 0
	v_mov_b32_e32 v106, 0
	v_mov_b32_e32 v107, 0
	v_mov_b32_e32 v108, 0
	v_mov_b32_e32 v109, 0
	v_mov_b32_e32 v110, 0
	v_mov_b32_e32 v111, 0
	v_mov_b32_e32 v112, 0
	v_mov_b32_e32 v113, 0
	v_mov_b32_e32 v114, 0
	v_mov_b32_e32 v115, 0
	v_mov_b32_e32 v116, 0
	v_mov_b32_e32 v117, 0
	v_mov_b32_e32 v118, 0
	v_mov_b32_e32 v119, 0
	v_mov_b32_e32 v120, 0
	v_mov_b32_e32 v121, 0
	v_mov_b32_e32 v122, 0
	v_mov_b32_e32 v123, 0
	v_mov_b32_e32 v124, 0
	v_mov_b32_e32 v125, 0
	v_mov_b32_e32 v126, 0
	v_mov_b32_e32 v127, 0
	v_mov_b32_e32 v128, 0
	v_mov_b32_e32 v129, 0
	v_mov_b32_e32 v130, 0
	v_mov_b32_e32 v131, 0
	v_mov_b32_e32 v132, 0
	v_mov_b32_e32 v133, 0
	v_mov_b32_e32 v134, 0
	v_mov_b32_e32 v135, 0
	v_mov_b32_e32 v136, 0
	v_mov_b32_e32 v137, 0
	v_mov_b32_e32 v138, 0
	v_mov_b32_e32 v139, 0
	v_mov_b32_e32 v140, 0
	v_mov_b32_e32 v141, 0
	v_mov_b32_e32 v142, 0
	v_mov_b32_e32 v143, 0
	v_mov_b32_e32 v144, 0
	v_mov_b32_e32 v145, 0
	v_mov_b32_e32 v146, 0
	v_mov_b32_e32 v147, 0
	v_mov_b32_e32 v148, 0
	v_mov_b32_e32 v149, 0
	v_mov_b32_e32 v150, 0
	v_mov_b32_e32 v151, 0
	v_mov_b32_e32 v152, 0
	v_mov_b32_e32 v153, 0
	v_mov_b32_e32 v154, 0
	v_mov_b32_e32 v155, 0
	v_mov_b32_e32 v156, 0
	v_mov_b32_e32 v157, 0
	v_mov_b32_e32 v158, 0
	v_mov_b32_e32 v159, 0
	v_mov_b32_e32 v160, 0
	v_mov_b32_e32 v161, 0
	v_mov_b32_e32 v162, 0
	v_mov_b32_e32 v163, 0
.Lpool_w16_a:
	global_load_dwordx4 v[40:43], v39, s[70:71]
	s_add_u32 s70, s70, 0x6000
	s_addc_u32 s71, s71, 0
	global_load_dwordx4 v[44:47], v39, s[70:71]
	s_add_u32 s70, s70, 0x6000
	s_addc_u32 s71, s71, 0
	global_load_dwordx4 v[48:51], v39, s[70:71]
	s_add_u32 s70, s70, 0x6000
	s_addc_u32 s71, s71, 0
	global_load_dwordx4 v[52:55], v39, s[70:71]
	s_add_u32 s70, s70, 0x6000
	s_addc_u32 s71, s71, 0
	global_load_dwordx4 v[56:59], v39, s[70:71]
	s_add_u32 s70, s70, 0x6000
	s_addc_u32 s71, s71, 0
	global_load_dwordx4 v[60:63], v39, s[70:71]
	s_add_u32 s70, s70, 0x6000
	s_addc_u32 s71, s71, 0
	global_load_dwordx4 v[64:67], v39, s[70:71]
	s_add_u32 s70, s70, 0x6000
	s_addc_u32 s71, s71, 0
	global_load_dwordx4 v[68:71], v39, s[70:71]
	s_add_u32 s70, s70, 0x6000
	s_addc_u32 s71, s71, 0
	global_load_dwordx4 v[72:75], v39, s[70:71]
	s_add_u32 s70, s70, 0x6000
	s_addc_u32 s71, s71, 0
	global_load_dwordx4 v[76:79], v39, s[70:71]
	s_add_u32 s70, s70, 0x6000
	s_addc_u32 s71, s71, 0
	global_load_dwordx4 v[80:83], v39, s[70:71]
	s_add_u32 s70, s70, 0x6000
	s_addc_u32 s71, s71, 0
	global_load_dwordx4 v[84:87], v39, s[70:71]
	s_add_u32 s70, s70, 0x6000
	s_addc_u32 s71, s71, 0
	global_load_dwordx4 v[88:91], v39, s[70:71]
	s_add_u32 s70, s70, 0x6000
	s_addc_u32 s71, s71, 0
	global_load_dwordx4 v[92:95], v39, s[70:71]
	s_add_u32 s70, s70, 0x6000
	s_addc_u32 s71, s71, 0
	global_load_dwordx4 v[96:99], v39, s[70:71]
	s_add_u32 s70, s70, 0x6000
	s_addc_u32 s71, s71, 0
	global_load_dwordx4 v[100:103], v39, s[70:71]
	s_waitcnt vmcnt(15)
; __device__ __forceinline__ void unpack8(const u32x4 w, f32x4& lo, f32x4& hi) { lo = (f32x4){bf_lo(w.x), bf_hi(w.x), bf_lo(w.y), bf_hi(w.y)}; hi = (f32x4){bf_lo(w.z), bf_hi(w.z), bf_lo(w.w), bf_hi(w.w)}; }
; __device__ __forceinline__ void phase_pool(const bf16_t* PROJ, bf16_t* Z, int gw, int NGW, int lane) {
;     ...
;         const int t0 = tseg * 16;
;         for (int tau = (t0 - win + 1 > 0 ? t0 - win + 1 : 0); tau < t0; ++tau) { f32x4 a, c; unpack8(*(const u32x4*)(vb + (size_t)tau * DIN), a, c); s0 += a; s1 += c; }
	v_lshlrev_b32_e32 v164, 16, v160
	v_and_b32_e32 v165, 0xffff0000, v160
	v_lshlrev_b32_e32 v166, 16, v161
	v_and_b32_e32 v167, 0xffff0000, v161
	v_lshlrev_b32_e32 v168, 16, v162
	v_and_b32_e32 v169, 0xffff0000, v162
	v_lshlrev_b32_e32 v170, 16, v163
	v_and_b32_e32 v171, 0xffff0000, v163
	v_lshlrev_b32_e32 v172, 16, v156
	v_and_b32_e32 v173, 0xffff0000, v156
	v_lshlrev_b32_e32 v174, 16, v157
	v_and_b32_e32 v175, 0xffff0000, v157
	v_lshlrev_b32_e32 v176, 16, v158
	v_and_b32_e32 v177, 0xffff0000, v158
	v_lshlrev_b32_e32 v178, 16, v159
	v_and_b32_e32 v179, 0xffff0000, v159
	v_pk_add_f32 v[164:165], v[164:165], v[172:173]
	v_pk_add_f32 v[166:167], v[166:167], v[174:175]
	v_pk_add_f32 v[168:169], v[168:169], v[176:177]
	v_pk_add_f32 v[170:171], v[170:171], v[178:179]
	v_lshlrev_b32_e32 v172, 16, v152
	v_and_b32_e32 v173, 0xffff0000, v152
	v_lshlrev_b32_e32 v174, 16, v153
	v_and_b32_e32 v175, 0xffff0000, v153
	v_lshlrev_b32_e32 v176, 16, v154
	v_and_b32_e32 v177, 0xffff0000, v154
	v_lshlrev_b32_e32 v178, 16, v155
	v_and_b32_e32 v179, 0xffff0000, v155
	v_pk_add_f32 v[164:165], v[164:165], v[172:173]
	v_pk_add_f32 v[166:167], v[166:167], v[174:175]
	v_pk_add_f32 v[168:169], v[168:169], v[176:177]
	v_pk_add_f32 v[170:171], v[170:171], v[178:179]
	v_lshlrev_b32_e32 v172, 16, v148
	v_and_b32_e32 v173, 0xffff0000, v148
	v_lshlrev_b32_e32 v174, 16, v149
	v_and_b32_e32 v175, 0xffff0000, v149
	v_lshlrev_b32_e32 v176, 16, v150
	v_and_b32_e32 v177, 0xffff0000, v150
	v_lshlrev_b32_e32 v178, 16, v151
	v_and_b32_e32 v179, 0xffff0000, v151
	v_pk_add_f32 v[164:165], v[164:165], v[172:173]
	v_pk_add_f32 v[166:167], v[166:167], v[174:175]
	v_pk_add_f32 v[168:169], v[168:169], v[176:177]
	v_pk_add_f32 v[170:171], v[170:171], v[178:179]
	v_lshlrev_b32_e32 v172, 16, v144
	v_and_b32_e32 v173, 0xffff0000, v144
	v_lshlrev_b32_e32 v174, 16, v145
	v_and_b32_e32 v175, 0xffff0000, v145
	v_lshlrev_b32_e32 v176, 16, v146
	v_and_b32_e32 v177, 0xffff0000, v146
	v_lshlrev_b32_e32 v178, 16, v147
	v_and_b32_e32 v179, 0xffff0000, v147
	v_pk_add_f32 v[164:165], v[164:165], v[172:173]
	v_pk_add_f32 v[166:167], v[166:167], v[174:175]
	v_pk_add_f32 v[168:169], v[168:169], v[176:177]
	v_pk_add_f32 v[170:171], v[170:171], v[178:179]
	v_lshlrev_b32_e32 v172, 16, v140
	v_and_b32_e32 v173, 0xffff0000, v140
	v_lshlrev_b32_e32 v174, 16, v141
	v_and_b32_e32 v175, 0xffff0000, v141
	v_lshlrev_b32_e32 v176, 16, v142
	v_and_b32_e32 v177, 0xffff0000, v142
	v_lshlrev_b32_e32 v178, 16, v143
	v_and_b32_e32 v179, 0xffff0000, v143
	v_pk_add_f32 v[164:165], v[164:165], v[172:173]
	v_pk_add_f32 v[166:167], v[166:167], v[174:175]
	v_pk_add_f32 v[168:169], v[168:169], v[176:177]
	v_pk_add_f32 v[170:171], v[170:171], v[178:179]
	v_lshlrev_b32_e32 v172, 16, v136
	v_and_b32_e32 v173, 0xffff0000, v136
	v_lshlrev_b32_e32 v174, 16, v137
	v_and_b32_e32 v175, 0xffff0000, v137
	v_lshlrev_b32_e32 v176, 16, v138
	v_and_b32_e32 v177, 0xffff0000, v138
	v_lshlrev_b32_e32 v178, 16, v139
	v_and_b32_e32 v179, 0xffff0000, v139
	v_pk_add_f32 v[164:165], v[164:165], v[172:173]
	v_pk_add_f32 v[166:167], v[166:167], v[174:175]
	v_pk_add_f32 v[168:169], v[168:169], v[176:177]
	v_pk_add_f32 v[170:171], v[170:171], v[178:179]
	v_lshlrev_b32_e32 v172, 16, v132
	v_and_b32_e32 v173, 0xffff0000, v132
	v_lshlrev_b32_e32 v174, 16, v133
	v_and_b32_e32 v175, 0xffff0000, v133
	v_lshlrev_b32_e32 v176, 16, v134
	v_and_b32_e32 v177, 0xffff0000, v134
	v_lshlrev_b32_e32 v178, 16, v135
	v_and_b32_e32 v179, 0xffff0000, v135
	v_pk_add_f32 v[164:165], v[164:165], v[172:173]
	v_pk_add_f32 v[166:167], v[166:167], v[174:175]
	v_pk_add_f32 v[168:169], v[168:169], v[176:177]
	v_pk_add_f32 v[170:171], v[170:171], v[178:179]
	v_lshlrev_b32_e32 v172, 16, v128
	v_and_b32_e32 v173, 0xffff0000, v128
	v_lshlrev_b32_e32 v174, 16, v129
	v_and_b32_e32 v175, 0xffff0000, v129
	v_lshlrev_b32_e32 v176, 16, v130
	v_and_b32_e32 v177, 0xffff0000, v130
	v_lshlrev_b32_e32 v178, 16, v131
	v_and_b32_e32 v179, 0xffff0000, v131
	v_pk_add_f32 v[164:165], v[164:165], v[172:173]
	v_pk_add_f32 v[166:167], v[166:167], v[174:175]
	v_pk_add_f32 v[168:169], v[168:169], v[176:177]
	v_pk_add_f32 v[170:171], v[170:171], v[178:179]
	v_lshlrev_b32_e32 v172, 16, v124
	v_and_b32_e32 v173, 0xffff0000, v124
	v_lshlrev_b32_e32 v174, 16, v125
	v_and_b32_e32 v175, 0xffff0000, v125
	v_lshlrev_b32_e32 v176, 16, v126
	v_and_b32_e32 v177, 0xffff0000, v126
	v_lshlrev_b32_e32 v178, 16, v127
	v_and_b32_e32 v179, 0xffff0000, v127
	v_pk_add_f32 v[164:165], v[164:165], v[172:173]
	v_pk_add_f32 v[166:167], v[166:167], v[174:175]
	v_pk_add_f32 v[168:169], v[168:169], v[176:177]
	v_pk_add_f32 v[170:171], v[170:171], v[178:179]
	v_lshlrev_b32_e32 v172, 16, v120
	v_and_b32_e32 v173, 0xffff0000, v120
	v_lshlrev_b32_e32 v174, 16, v121
	v_and_b32_e32 v175, 0xffff0000, v121
	v_lshlrev_b32_e32 v176, 16, v122
	v_and_b32_e32 v177, 0xffff0000, v122
	v_lshlrev_b32_e32 v178, 16, v123
	v_and_b32_e32 v179, 0xffff0000, v123
	v_pk_add_f32 v[164:165], v[164:165], v[172:173]
	v_pk_add_f32 v[166:167], v[166:167], v[174:175]
	v_pk_add_f32 v[168:169], v[168:169], v[176:177]
	v_pk_add_f32 v[170:171], v[170:171], v[178:179]
	v_lshlrev_b32_e32 v172, 16, v116
	v_and_b32_e32 v173, 0xffff0000, v116
	v_lshlrev_b32_e32 v174, 16, v117
	v_and_b32_e32 v175, 0xffff0000, v117
	v_lshlrev_b32_e32 v176, 16, v118
	v_and_b32_e32 v177, 0xffff0000, v118
	v_lshlrev_b32_e32 v178, 16, v119
	v_and_b32_e32 v179, 0xffff0000, v119
	v_pk_add_f32 v[164:165], v[164:165], v[172:173]
	v_pk_add_f32 v[166:167], v[166:167], v[174:175]
	v_pk_add_f32 v[168:169], v[168:169], v[176:177]
	v_pk_add_f32 v[170:171], v[170:171], v[178:179]
	v_lshlrev_b32_e32 v172, 16, v112
; __device__ __forceinline__ u32x4 pack8(const f32x4 v0, const f32x4 v1) { u32x4 w; w.x = cvt_pk_bf16(v0[0], v0[1]); w.y = cvt_pk_bf16(v0[2], v0[3]); w.z = cvt_pk_bf16(v1[0], v1[1]); w.w = cvt_pk_bf16(v1[2], v1[3]); return w; }
; __device__ __forceinline__ void unpack8(const u32x4 w, f32x4& lo, f32x4& hi) { lo = (f32x4){bf_lo(w.x), bf_hi(w.x), bf_lo(w.y), bf_hi(w.y)}; hi = (f32x4){bf_lo(w.z), bf_hi(w.z), bf_lo(w.w), bf_hi(w.w)}; }
; __device__ __forceinline__ void phase_pool(const bf16_t* PROJ, bf16_t* Z, int gw, int NGW, int lane) {
;     ...
;         const int t0 = tseg * 16;
;         for (int tau = (t0 - win + 1 > 0 ? t0 - win + 1 : 0); tau < t0; ++tau) { f32x4 a, c; unpack8(*(const u32x4*)(vb + (size_t)tau * DIN), a, c); s0 += a; s1 += c; }
;         for (int t = t0; t < t0 + 16; ++t) {
;             f32x4 v0, v1; unpack8(*(const u32x4*)(vb + (size_t)t * DIN), v0, v1); s0 += v0; s1 += v1;
;             if (t > t0 && t - win >= 0) { f32x4 a, c; unpack8(*(const u32x4*)(vb + (size_t)(t - win) * DIN), a, c); s0 -= a; s1 -= c; }
;             const float inv = 1.f / (float)((t + 1) < win ? (t + 1) : win);
;             *(u32x4*)(zb + (size_t)t * DSS) = pack8(s0 * inv - v0, s1 * inv - v1);
	v_and_b32_e32 v173, 0xffff0000, v112
	v_lshlrev_b32_e32 v174, 16, v113
	v_and_b32_e32 v175, 0xffff0000, v113
	v_lshlrev_b32_e32 v176, 16, v114
	v_and_b32_e32 v177, 0xffff0000, v114
	v_lshlrev_b32_e32 v178, 16, v115
	v_and_b32_e32 v179, 0xffff0000, v115
	v_pk_add_f32 v[164:165], v[164:165], v[172:173]
	v_pk_add_f32 v[166:167], v[166:167], v[174:175]
	v_pk_add_f32 v[168:169], v[168:169], v[176:177]
	v_pk_add_f32 v[170:171], v[170:171], v[178:179]
	v_lshlrev_b32_e32 v172, 16, v108
	v_and_b32_e32 v173, 0xffff0000, v108
	v_lshlrev_b32_e32 v174, 16, v109
	v_and_b32_e32 v175, 0xffff0000, v109
	v_lshlrev_b32_e32 v176, 16, v110
	v_and_b32_e32 v177, 0xffff0000, v110
	v_lshlrev_b32_e32 v178, 16, v111
	v_and_b32_e32 v179, 0xffff0000, v111
	v_pk_add_f32 v[164:165], v[164:165], v[172:173]
	v_pk_add_f32 v[166:167], v[166:167], v[174:175]
	v_pk_add_f32 v[168:169], v[168:169], v[176:177]
	v_pk_add_f32 v[170:171], v[170:171], v[178:179]
	v_lshlrev_b32_e32 v172, 16, v104
	v_and_b32_e32 v173, 0xffff0000, v104
	v_lshlrev_b32_e32 v174, 16, v105
	v_and_b32_e32 v175, 0xffff0000, v105
	v_lshlrev_b32_e32 v176, 16, v106
	v_and_b32_e32 v177, 0xffff0000, v106
	v_lshlrev_b32_e32 v178, 16, v107
	v_and_b32_e32 v179, 0xffff0000, v107
	v_pk_add_f32 v[164:165], v[164:165], v[172:173]
	v_pk_add_f32 v[166:167], v[166:167], v[174:175]
	v_pk_add_f32 v[168:169], v[168:169], v[176:177]
	v_pk_add_f32 v[170:171], v[170:171], v[178:179]
	v_lshlrev_b32_e32 v172, 16, v40
	v_and_b32_e32 v173, 0xffff0000, v40
	v_lshlrev_b32_e32 v174, 16, v41
	v_and_b32_e32 v175, 0xffff0000, v41
	v_lshlrev_b32_e32 v176, 16, v42
	v_and_b32_e32 v177, 0xffff0000, v42
	v_lshlrev_b32_e32 v178, 16, v43
	v_and_b32_e32 v179, 0xffff0000, v43
	v_pk_add_f32 v[164:165], v[164:165], v[172:173]
	v_pk_add_f32 v[166:167], v[166:167], v[174:175]
	v_pk_add_f32 v[168:169], v[168:169], v[176:177]
	v_pk_add_f32 v[170:171], v[170:171], v[178:179]
	s_cmp_eq_u32 s65, 0
	s_cselect_b32 s4, 0x3f800000, s72
	v_fma_f32 v188, v164, s4, -v172
	v_fma_f32 v189, v165, s4, -v173
	v_fma_f32 v190, v166, s4, -v174
	v_fma_f32 v191, v167, s4, -v175
	v_fma_f32 v192, v168, s4, -v176
	v_fma_f32 v193, v169, s4, -v177
	v_fma_f32 v194, v170, s4, -v178
	v_fma_f32 v195, v171, s4, -v179
	v_cvt_pk_bf16_f32 v196, v188, v189
	v_cvt_pk_bf16_f32 v197, v190, v191
	v_cvt_pk_bf16_f32 v198, v192, v193
	v_cvt_pk_bf16_f32 v199, v194, v195
	global_store_dwordx4 v39, v[196:199], s[36:37]
	s_add_u32 s36, s36, 0x1000
	s_addc_u32 s37, s37, 0
	s_waitcnt vmcnt(15)
	v_lshlrev_b32_e32 v172, 16, v44
	v_and_b32_e32 v173, 0xffff0000, v44
	v_lshlrev_b32_e32 v174, 16, v45
	v_and_b32_e32 v175, 0xffff0000, v45
	v_lshlrev_b32_e32 v176, 16, v46
	v_and_b32_e32 v177, 0xffff0000, v46
	v_lshlrev_b32_e32 v178, 16, v47
	v_and_b32_e32 v179, 0xffff0000, v47
	v_pk_add_f32 v[164:165], v[164:165], v[172:173]
	v_pk_add_f32 v[166:167], v[166:167], v[174:175]
	v_pk_add_f32 v[168:169], v[168:169], v[176:177]
	v_pk_add_f32 v[170:171], v[170:171], v[178:179]
	v_lshlrev_b32_e32 v180, 16, v160
	v_and_b32_e32 v181, 0xffff0000, v160
	v_lshlrev_b32_e32 v182, 16, v161
	v_and_b32_e32 v183, 0xffff0000, v161
	v_lshlrev_b32_e32 v184, 16, v162
	v_and_b32_e32 v185, 0xffff0000, v162
	v_lshlrev_b32_e32 v186, 16, v163
	v_and_b32_e32 v187, 0xffff0000, v163
	v_sub_f32_e32 v164, v164, v180
	v_sub_f32_e32 v165, v165, v181
	v_sub_f32_e32 v166, v166, v182
	v_sub_f32_e32 v167, v167, v183
	v_sub_f32_e32 v168, v168, v184
	v_sub_f32_e32 v169, v169, v185
	v_sub_f32_e32 v170, v170, v186
	v_sub_f32_e32 v171, v171, v187
	s_cmp_eq_u32 s65, 0
	s_cselect_b32 s4, 0x3f000000, s72
	v_fma_f32 v188, v164, s4, -v172
	v_fma_f32 v189, v165, s4, -v173
	v_fma_f32 v190, v166, s4, -v174
	v_fma_f32 v191, v167, s4, -v175
	v_fma_f32 v192, v168, s4, -v176
	v_fma_f32 v193, v169, s4, -v177
	v_fma_f32 v194, v170, s4, -v178
	v_fma_f32 v195, v171, s4, -v179
	v_cvt_pk_bf16_f32 v196, v188, v189
	v_cvt_pk_bf16_f32 v197, v190, v191
	v_cvt_pk_bf16_f32 v198, v192, v193
	v_cvt_pk_bf16_f32 v199, v194, v195
	global_store_dwordx4 v39, v[196:199], s[36:37]
	s_add_u32 s36, s36, 0x1000
	s_addc_u32 s37, s37, 0
	s_waitcnt vmcnt(15)
	v_lshlrev_b32_e32 v172, 16, v48
	v_and_b32_e32 v173, 0xffff0000, v48
	v_lshlrev_b32_e32 v174, 16, v49
	v_and_b32_e32 v175, 0xffff0000, v49
	v_lshlrev_b32_e32 v176, 16, v50
	v_and_b32_e32 v177, 0xffff0000, v50
	v_lshlrev_b32_e32 v178, 16, v51
	v_and_b32_e32 v179, 0xffff0000, v51
	v_pk_add_f32 v[164:165], v[164:165], v[172:173]
	v_pk_add_f32 v[166:167], v[166:167], v[174:175]
	v_pk_add_f32 v[168:169], v[168:169], v[176:177]
	v_pk_add_f32 v[170:171], v[170:171], v[178:179]
	v_lshlrev_b32_e32 v180, 16, v156
	v_and_b32_e32 v181, 0xffff0000, v156
	v_lshlrev_b32_e32 v182, 16, v157
	v_and_b32_e32 v183, 0xffff0000, v157
	v_lshlrev_b32_e32 v184, 16, v158
	v_and_b32_e32 v185, 0xffff0000, v158
	v_lshlrev_b32_e32 v186, 16, v159
	v_and_b32_e32 v187, 0xffff0000, v159
	v_sub_f32_e32 v164, v164, v180
	v_sub_f32_e32 v165, v165, v181
	v_sub_f32_e32 v166, v166, v182
	v_sub_f32_e32 v167, v167, v183
	v_sub_f32_e32 v168, v168, v184
	v_sub_f32_e32 v169, v169, v185
	v_sub_f32_e32 v170, v170, v186
	v_sub_f32_e32 v171, v171, v187
	s_cmp_eq_u32 s65, 0
	s_cselect_b32 s4, 0x3eaaaaab, s72
	v_fma_f32 v188, v164, s4, -v172
	v_fma_f32 v189, v165, s4, -v173
	v_fma_f32 v190, v166, s4, -v174
	v_fma_f32 v191, v167, s4, -v175
	v_fma_f32 v192, v168, s4, -v176
	v_fma_f32 v193, v169, s4, -v177
	v_fma_f32 v194, v170, s4, -v178
	v_fma_f32 v195, v171, s4, -v179
	v_cvt_pk_bf16_f32 v196, v188, v189
	v_cvt_pk_bf16_f32 v197, v190, v191
	v_cvt_pk_bf16_f32 v198, v192, v193
	v_cvt_pk_bf16_f32 v199, v194, v195
	global_store_dwordx4 v39, v[196:199], s[36:37]
	s_add_u32 s36, s36, 0x1000
	s_addc_u32 s37, s37, 0
	s_waitcnt vmcnt(15)
; __device__ __forceinline__ u32x4 pack8(const f32x4 v0, const f32x4 v1) { u32x4 w; w.x = cvt_pk_bf16(v0[0], v0[1]); w.y = cvt_pk_bf16(v0[2], v0[3]); w.z = cvt_pk_bf16(v1[0], v1[1]); w.w = cvt_pk_bf16(v1[2], v1[3]); return w; }
; __device__ __forceinline__ void unpack8(const u32x4 w, f32x4& lo, f32x4& hi) { lo = (f32x4){bf_lo(w.x), bf_hi(w.x), bf_lo(w.y), bf_hi(w.y)}; hi = (f32x4){bf_lo(w.z), bf_hi(w.z), bf_lo(w.w), bf_hi(w.w)}; }
; __device__ __forceinline__ void phase_pool(const bf16_t* PROJ, bf16_t* Z, int gw, int NGW, int lane) {
;     ...
;         for (int t = t0; t < t0 + 16; ++t) {
;             f32x4 v0, v1; unpack8(*(const u32x4*)(vb + (size_t)t * DIN), v0, v1); s0 += v0; s1 += v1;
;             if (t > t0 && t - win >= 0) { f32x4 a, c; unpack8(*(const u32x4*)(vb + (size_t)(t - win) * DIN), a, c); s0 -= a; s1 -= c; }
;             const float inv = 1.f / (float)((t + 1) < win ? (t + 1) : win);
;             *(u32x4*)(zb + (size_t)t * DSS) = pack8(s0 * inv - v0, s1 * inv - v1);
	v_lshlrev_b32_e32 v172, 16, v52
	v_and_b32_e32 v173, 0xffff0000, v52
	v_lshlrev_b32_e32 v174, 16, v53
	v_and_b32_e32 v175, 0xffff0000, v53
	v_lshlrev_b32_e32 v176, 16, v54
	v_and_b32_e32 v177, 0xffff0000, v54
	v_lshlrev_b32_e32 v178, 16, v55
	v_and_b32_e32 v179, 0xffff0000, v55
	v_pk_add_f32 v[164:165], v[164:165], v[172:173]
	v_pk_add_f32 v[166:167], v[166:167], v[174:175]
	v_pk_add_f32 v[168:169], v[168:169], v[176:177]
	v_pk_add_f32 v[170:171], v[170:171], v[178:179]
	v_lshlrev_b32_e32 v180, 16, v152
	v_and_b32_e32 v181, 0xffff0000, v152
	v_lshlrev_b32_e32 v182, 16, v153
	v_and_b32_e32 v183, 0xffff0000, v153
	v_lshlrev_b32_e32 v184, 16, v154
	v_and_b32_e32 v185, 0xffff0000, v154
	v_lshlrev_b32_e32 v186, 16, v155
	v_and_b32_e32 v187, 0xffff0000, v155
	v_sub_f32_e32 v164, v164, v180
	v_sub_f32_e32 v165, v165, v181
	v_sub_f32_e32 v166, v166, v182
	v_sub_f32_e32 v167, v167, v183
	v_sub_f32_e32 v168, v168, v184
	v_sub_f32_e32 v169, v169, v185
	v_sub_f32_e32 v170, v170, v186
	v_sub_f32_e32 v171, v171, v187
	s_cmp_eq_u32 s65, 0
	s_cselect_b32 s4, 0x3e800000, s72
	v_fma_f32 v188, v164, s4, -v172
	v_fma_f32 v189, v165, s4, -v173
	v_fma_f32 v190, v166, s4, -v174
	v_fma_f32 v191, v167, s4, -v175
	v_fma_f32 v192, v168, s4, -v176
	v_fma_f32 v193, v169, s4, -v177
	v_fma_f32 v194, v170, s4, -v178
	v_fma_f32 v195, v171, s4, -v179
	v_cvt_pk_bf16_f32 v196, v188, v189
	v_cvt_pk_bf16_f32 v197, v190, v191
	v_cvt_pk_bf16_f32 v198, v192, v193
	v_cvt_pk_bf16_f32 v199, v194, v195
	global_store_dwordx4 v39, v[196:199], s[36:37]
	s_add_u32 s36, s36, 0x1000
	s_addc_u32 s37, s37, 0
	s_waitcnt vmcnt(15)
	v_lshlrev_b32_e32 v172, 16, v56
	v_and_b32_e32 v173, 0xffff0000, v56
	v_lshlrev_b32_e32 v174, 16, v57
	v_and_b32_e32 v175, 0xffff0000, v57
	v_lshlrev_b32_e32 v176, 16, v58
	v_and_b32_e32 v177, 0xffff0000, v58
	v_lshlrev_b32_e32 v178, 16, v59
	v_and_b32_e32 v179, 0xffff0000, v59
	v_pk_add_f32 v[164:165], v[164:165], v[172:173]
	v_pk_add_f32 v[166:167], v[166:167], v[174:175]
	v_pk_add_f32 v[168:169], v[168:169], v[176:177]
	v_pk_add_f32 v[170:171], v[170:171], v[178:179]
	v_lshlrev_b32_e32 v180, 16, v148
	v_and_b32_e32 v181, 0xffff0000, v148
	v_lshlrev_b32_e32 v182, 16, v149
	v_and_b32_e32 v183, 0xffff0000, v149
	v_lshlrev_b32_e32 v184, 16, v150
	v_and_b32_e32 v185, 0xffff0000, v150
	v_lshlrev_b32_e32 v186, 16, v151
	v_and_b32_e32 v187, 0xffff0000, v151
	v_sub_f32_e32 v164, v164, v180
	v_sub_f32_e32 v165, v165, v181
	v_sub_f32_e32 v166, v166, v182
	v_sub_f32_e32 v167, v167, v183
	v_sub_f32_e32 v168, v168, v184
	v_sub_f32_e32 v169, v169, v185
	v_sub_f32_e32 v170, v170, v186
	v_sub_f32_e32 v171, v171, v187
	s_cmp_eq_u32 s65, 0
	s_cselect_b32 s4, 0x3e4ccccd, s72
	v_fma_f32 v188, v164, s4, -v172
	v_fma_f32 v189, v165, s4, -v173
	v_fma_f32 v190, v166, s4, -v174
	v_fma_f32 v191, v167, s4, -v175
	v_fma_f32 v192, v168, s4, -v176
	v_fma_f32 v193, v169, s4, -v177
	v_fma_f32 v194, v170, s4, -v178
	v_fma_f32 v195, v171, s4, -v179
	v_cvt_pk_bf16_f32 v196, v188, v189
	v_cvt_pk_bf16_f32 v197, v190, v191
	v_cvt_pk_bf16_f32 v198, v192, v193
	v_cvt_pk_bf16_f32 v199, v194, v195
	global_store_dwordx4 v39, v[196:199], s[36:37]
	s_add_u32 s36, s36, 0x1000
	s_addc_u32 s37, s37, 0
	s_waitcnt vmcnt(15)
	v_lshlrev_b32_e32 v172, 16, v60
	v_and_b32_e32 v173, 0xffff0000, v60
	v_lshlrev_b32_e32 v174, 16, v61
	v_and_b32_e32 v175, 0xffff0000, v61
	v_lshlrev_b32_e32 v176, 16, v62
	v_and_b32_e32 v177, 0xffff0000, v62
	v_lshlrev_b32_e32 v178, 16, v63
	v_and_b32_e32 v179, 0xffff0000, v63
	v_pk_add_f32 v[164:165], v[164:165], v[172:173]
	v_pk_add_f32 v[166:167], v[166:167], v[174:175]
	v_pk_add_f32 v[168:169], v[168:169], v[176:177]
	v_pk_add_f32 v[170:171], v[170:171], v[178:179]
	v_lshlrev_b32_e32 v180, 16, v144
	v_and_b32_e32 v181, 0xffff0000, v144
	v_lshlrev_b32_e32 v182, 16, v145
	v_and_b32_e32 v183, 0xffff0000, v145
	v_lshlrev_b32_e32 v184, 16, v146
	v_and_b32_e32 v185, 0xffff0000, v146
	v_lshlrev_b32_e32 v186, 16, v147
	v_and_b32_e32 v187, 0xffff0000, v147
	v_sub_f32_e32 v164, v164, v180
	v_sub_f32_e32 v165, v165, v181
	v_sub_f32_e32 v166, v166, v182
	v_sub_f32_e32 v167, v167, v183
	v_sub_f32_e32 v168, v168, v184
	v_sub_f32_e32 v169, v169, v185
	v_sub_f32_e32 v170, v170, v186
	v_sub_f32_e32 v171, v171, v187
	s_cmp_eq_u32 s65, 0
	s_cselect_b32 s4, 0x3e2aaaab, s72
	v_fma_f32 v188, v164, s4, -v172
	v_fma_f32 v189, v165, s4, -v173
	v_fma_f32 v190, v166, s4, -v174
	v_fma_f32 v191, v167, s4, -v175
	v_fma_f32 v192, v168, s4, -v176
	v_fma_f32 v193, v169, s4, -v177
	v_fma_f32 v194, v170, s4, -v178
	v_fma_f32 v195, v171, s4, -v179
	v_cvt_pk_bf16_f32 v196, v188, v189
	v_cvt_pk_bf16_f32 v197, v190, v191
	v_cvt_pk_bf16_f32 v198, v192, v193
	v_cvt_pk_bf16_f32 v199, v194, v195
	global_store_dwordx4 v39, v[196:199], s[36:37]
	s_add_u32 s36, s36, 0x1000
	s_addc_u32 s37, s37, 0
	s_waitcnt vmcnt(15)
	v_lshlrev_b32_e32 v172, 16, v64
	v_and_b32_e32 v173, 0xffff0000, v64
	v_lshlrev_b32_e32 v174, 16, v65
	v_and_b32_e32 v175, 0xffff0000, v65
	v_lshlrev_b32_e32 v176, 16, v66
	v_and_b32_e32 v177, 0xffff0000, v66
	v_lshlrev_b32_e32 v178, 16, v67
	v_and_b32_e32 v179, 0xffff0000, v67
	v_pk_add_f32 v[164:165], v[164:165], v[172:173]
	v_pk_add_f32 v[166:167], v[166:167], v[174:175]
	v_pk_add_f32 v[168:169], v[168:169], v[176:177]
	v_pk_add_f32 v[170:171], v[170:171], v[178:179]
	v_lshlrev_b32_e32 v180, 16, v140
	v_and_b32_e32 v181, 0xffff0000, v140
	v_lshlrev_b32_e32 v182, 16, v141
	v_and_b32_e32 v183, 0xffff0000, v141
	v_lshlrev_b32_e32 v184, 16, v142
	v_and_b32_e32 v185, 0xffff0000, v142
	v_lshlrev_b32_e32 v186, 16, v143
	v_and_b32_e32 v187, 0xffff0000, v143
	v_sub_f32_e32 v164, v164, v180
	v_sub_f32_e32 v165, v165, v181
	v_sub_f32_e32 v166, v166, v182
	v_sub_f32_e32 v167, v167, v183
	v_sub_f32_e32 v168, v168, v184
	v_sub_f32_e32 v169, v169, v185
	v_sub_f32_e32 v170, v170, v186
	v_sub_f32_e32 v171, v171, v187
	s_cmp_eq_u32 s65, 0
	s_cselect_b32 s4, 0x3e124925, s72
	v_fma_f32 v188, v164, s4, -v172
	v_fma_f32 v189, v165, s4, -v173
	v_fma_f32 v190, v166, s4, -v174
	v_fma_f32 v191, v167, s4, -v175
	v_fma_f32 v192, v168, s4, -v176
	v_fma_f32 v193, v169, s4, -v177
	v_fma_f32 v194, v170, s4, -v178
	v_fma_f32 v195, v171, s4, -v179
	v_cvt_pk_bf16_f32 v196, v188, v189
	v_cvt_pk_bf16_f32 v197, v190, v191
	v_cvt_pk_bf16_f32 v198, v192, v193
	v_cvt_pk_bf16_f32 v199, v194, v195
	global_store_dwordx4 v39, v[196:199], s[36:37]
	s_add_u32 s36, s36, 0x1000
	s_addc_u32 s37, s37, 0
	s_waitcnt vmcnt(15)
; __device__ __forceinline__ u32x4 pack8(const f32x4 v0, const f32x4 v1) { u32x4 w; w.x = cvt_pk_bf16(v0[0], v0[1]); w.y = cvt_pk_bf16(v0[2], v0[3]); w.z = cvt_pk_bf16(v1[0], v1[1]); w.w = cvt_pk_bf16(v1[2], v1[3]); return w; }
; __device__ __forceinline__ void unpack8(const u32x4 w, f32x4& lo, f32x4& hi) { lo = (f32x4){bf_lo(w.x), bf_hi(w.x), bf_lo(w.y), bf_hi(w.y)}; hi = (f32x4){bf_lo(w.z), bf_hi(w.z), bf_lo(w.w), bf_hi(w.w)}; }
; __device__ __forceinline__ void phase_pool(const bf16_t* PROJ, bf16_t* Z, int gw, int NGW, int lane) {
;     ...
;         for (int t = t0; t < t0 + 16; ++t) {
;             f32x4 v0, v1; unpack8(*(const u32x4*)(vb + (size_t)t * DIN), v0, v1); s0 += v0; s1 += v1;
;             if (t > t0 && t - win >= 0) { f32x4 a, c; unpack8(*(const u32x4*)(vb + (size_t)(t - win) * DIN), a, c); s0 -= a; s1 -= c; }
;             const float inv = 1.f / (float)((t + 1) < win ? (t + 1) : win);
;             *(u32x4*)(zb + (size_t)t * DSS) = pack8(s0 * inv - v0, s1 * inv - v1);
	v_lshlrev_b32_e32 v172, 16, v68
	v_and_b32_e32 v173, 0xffff0000, v68
	v_lshlrev_b32_e32 v174, 16, v69
	v_and_b32_e32 v175, 0xffff0000, v69
	v_lshlrev_b32_e32 v176, 16, v70
	v_and_b32_e32 v177, 0xffff0000, v70
	v_lshlrev_b32_e32 v178, 16, v71
	v_and_b32_e32 v179, 0xffff0000, v71
	v_pk_add_f32 v[164:165], v[164:165], v[172:173]
	v_pk_add_f32 v[166:167], v[166:167], v[174:175]
	v_pk_add_f32 v[168:169], v[168:169], v[176:177]
	v_pk_add_f32 v[170:171], v[170:171], v[178:179]
	v_lshlrev_b32_e32 v180, 16, v136
	v_and_b32_e32 v181, 0xffff0000, v136
	v_lshlrev_b32_e32 v182, 16, v137
	v_and_b32_e32 v183, 0xffff0000, v137
	v_lshlrev_b32_e32 v184, 16, v138
	v_and_b32_e32 v185, 0xffff0000, v138
	v_lshlrev_b32_e32 v186, 16, v139
	v_and_b32_e32 v187, 0xffff0000, v139
	v_sub_f32_e32 v164, v164, v180
	v_sub_f32_e32 v165, v165, v181
	v_sub_f32_e32 v166, v166, v182
	v_sub_f32_e32 v167, v167, v183
	v_sub_f32_e32 v168, v168, v184
	v_sub_f32_e32 v169, v169, v185
	v_sub_f32_e32 v170, v170, v186
	v_sub_f32_e32 v171, v171, v187
	s_cmp_eq_u32 s65, 0
	s_cselect_b32 s4, 0x3e000000, s72
	v_fma_f32 v188, v164, s4, -v172
	v_fma_f32 v189, v165, s4, -v173
	v_fma_f32 v190, v166, s4, -v174
	v_fma_f32 v191, v167, s4, -v175
	v_fma_f32 v192, v168, s4, -v176
	v_fma_f32 v193, v169, s4, -v177
	v_fma_f32 v194, v170, s4, -v178
	v_fma_f32 v195, v171, s4, -v179
	v_cvt_pk_bf16_f32 v196, v188, v189
	v_cvt_pk_bf16_f32 v197, v190, v191
	v_cvt_pk_bf16_f32 v198, v192, v193
	v_cvt_pk_bf16_f32 v199, v194, v195
	global_store_dwordx4 v39, v[196:199], s[36:37]
	s_add_u32 s36, s36, 0x1000
	s_addc_u32 s37, s37, 0
	s_waitcnt vmcnt(15)
	v_lshlrev_b32_e32 v172, 16, v72
	v_and_b32_e32 v173, 0xffff0000, v72
	v_lshlrev_b32_e32 v174, 16, v73
	v_and_b32_e32 v175, 0xffff0000, v73
	v_lshlrev_b32_e32 v176, 16, v74
	v_and_b32_e32 v177, 0xffff0000, v74
	v_lshlrev_b32_e32 v178, 16, v75
	v_and_b32_e32 v179, 0xffff0000, v75
	v_pk_add_f32 v[164:165], v[164:165], v[172:173]
	v_pk_add_f32 v[166:167], v[166:167], v[174:175]
	v_pk_add_f32 v[168:169], v[168:169], v[176:177]
	v_pk_add_f32 v[170:171], v[170:171], v[178:179]
	v_lshlrev_b32_e32 v180, 16, v132
	v_and_b32_e32 v181, 0xffff0000, v132
	v_lshlrev_b32_e32 v182, 16, v133
	v_and_b32_e32 v183, 0xffff0000, v133
	v_lshlrev_b32_e32 v184, 16, v134
	v_and_b32_e32 v185, 0xffff0000, v134
	v_lshlrev_b32_e32 v186, 16, v135
	v_and_b32_e32 v187, 0xffff0000, v135
	v_sub_f32_e32 v164, v164, v180
	v_sub_f32_e32 v165, v165, v181
	v_sub_f32_e32 v166, v166, v182
	v_sub_f32_e32 v167, v167, v183
	v_sub_f32_e32 v168, v168, v184
	v_sub_f32_e32 v169, v169, v185
	v_sub_f32_e32 v170, v170, v186
	v_sub_f32_e32 v171, v171, v187
	s_cmp_eq_u32 s65, 0
	s_cselect_b32 s4, 0x3de38e39, s72
	v_fma_f32 v188, v164, s4, -v172
	v_fma_f32 v189, v165, s4, -v173
	v_fma_f32 v190, v166, s4, -v174
	v_fma_f32 v191, v167, s4, -v175
	v_fma_f32 v192, v168, s4, -v176
	v_fma_f32 v193, v169, s4, -v177
	v_fma_f32 v194, v170, s4, -v178
	v_fma_f32 v195, v171, s4, -v179
	v_cvt_pk_bf16_f32 v196, v188, v189
	v_cvt_pk_bf16_f32 v197, v190, v191
	v_cvt_pk_bf16_f32 v198, v192, v193
	v_cvt_pk_bf16_f32 v199, v194, v195
	global_store_dwordx4 v39, v[196:199], s[36:37]
	s_add_u32 s36, s36, 0x1000
	s_addc_u32 s37, s37, 0
	s_waitcnt vmcnt(15)
	v_lshlrev_b32_e32 v172, 16, v76
	v_and_b32_e32 v173, 0xffff0000, v76
	v_lshlrev_b32_e32 v174, 16, v77
	v_and_b32_e32 v175, 0xffff0000, v77
	v_lshlrev_b32_e32 v176, 16, v78
	v_and_b32_e32 v177, 0xffff0000, v78
	v_lshlrev_b32_e32 v178, 16, v79
	v_and_b32_e32 v179, 0xffff0000, v79
	v_pk_add_f32 v[164:165], v[164:165], v[172:173]
	v_pk_add_f32 v[166:167], v[166:167], v[174:175]
	v_pk_add_f32 v[168:169], v[168:169], v[176:177]
	v_pk_add_f32 v[170:171], v[170:171], v[178:179]
	v_lshlrev_b32_e32 v180, 16, v128
	v_and_b32_e32 v181, 0xffff0000, v128
	v_lshlrev_b32_e32 v182, 16, v129
	v_and_b32_e32 v183, 0xffff0000, v129
	v_lshlrev_b32_e32 v184, 16, v130
	v_and_b32_e32 v185, 0xffff0000, v130
	v_lshlrev_b32_e32 v186, 16, v131
	v_and_b32_e32 v187, 0xffff0000, v131
	v_sub_f32_e32 v164, v164, v180
	v_sub_f32_e32 v165, v165, v181
	v_sub_f32_e32 v166, v166, v182
	v_sub_f32_e32 v167, v167, v183
	v_sub_f32_e32 v168, v168, v184
	v_sub_f32_e32 v169, v169, v185
	v_sub_f32_e32 v170, v170, v186
	v_sub_f32_e32 v171, v171, v187
	s_cmp_eq_u32 s65, 0
	s_cselect_b32 s4, 0x3dcccccd, s72
	v_fma_f32 v188, v164, s4, -v172
	v_fma_f32 v189, v165, s4, -v173
	v_fma_f32 v190, v166, s4, -v174
	v_fma_f32 v191, v167, s4, -v175
	v_fma_f32 v192, v168, s4, -v176
	v_fma_f32 v193, v169, s4, -v177
	v_fma_f32 v194, v170, s4, -v178
	v_fma_f32 v195, v171, s4, -v179
	v_cvt_pk_bf16_f32 v196, v188, v189
	v_cvt_pk_bf16_f32 v197, v190, v191
	v_cvt_pk_bf16_f32 v198, v192, v193
	v_cvt_pk_bf16_f32 v199, v194, v195
	global_store_dwordx4 v39, v[196:199], s[36:37]
	s_add_u32 s36, s36, 0x1000
	s_addc_u32 s37, s37, 0
	s_waitcnt vmcnt(15)
	v_lshlrev_b32_e32 v172, 16, v80
	v_and_b32_e32 v173, 0xffff0000, v80
	v_lshlrev_b32_e32 v174, 16, v81
	v_and_b32_e32 v175, 0xffff0000, v81
	v_lshlrev_b32_e32 v176, 16, v82
	v_and_b32_e32 v177, 0xffff0000, v82
	v_lshlrev_b32_e32 v178, 16, v83
	v_and_b32_e32 v179, 0xffff0000, v83
	v_pk_add_f32 v[164:165], v[164:165], v[172:173]
	v_pk_add_f32 v[166:167], v[166:167], v[174:175]
	v_pk_add_f32 v[168:169], v[168:169], v[176:177]
	v_pk_add_f32 v[170:171], v[170:171], v[178:179]
	v_lshlrev_b32_e32 v180, 16, v124
	v_and_b32_e32 v181, 0xffff0000, v124
	v_lshlrev_b32_e32 v182, 16, v125
	v_and_b32_e32 v183, 0xffff0000, v125
	v_lshlrev_b32_e32 v184, 16, v126
	v_and_b32_e32 v185, 0xffff0000, v126
	v_lshlrev_b32_e32 v186, 16, v127
	v_and_b32_e32 v187, 0xffff0000, v127
	v_sub_f32_e32 v164, v164, v180
	v_sub_f32_e32 v165, v165, v181
	v_sub_f32_e32 v166, v166, v182
	v_sub_f32_e32 v167, v167, v183
	v_sub_f32_e32 v168, v168, v184
	v_sub_f32_e32 v169, v169, v185
	v_sub_f32_e32 v170, v170, v186
	v_sub_f32_e32 v171, v171, v187
	s_cmp_eq_u32 s65, 0
	s_cselect_b32 s4, 0x3dba2e8c, s72
	v_fma_f32 v188, v164, s4, -v172
	v_fma_f32 v189, v165, s4, -v173
	v_fma_f32 v190, v166, s4, -v174
	v_fma_f32 v191, v167, s4, -v175
	v_fma_f32 v192, v168, s4, -v176
	v_fma_f32 v193, v169, s4, -v177
	v_fma_f32 v194, v170, s4, -v178
	v_fma_f32 v195, v171, s4, -v179
	v_cvt_pk_bf16_f32 v196, v188, v189
	v_cvt_pk_bf16_f32 v197, v190, v191
	v_cvt_pk_bf16_f32 v198, v192, v193
	v_cvt_pk_bf16_f32 v199, v194, v195
	global_store_dwordx4 v39, v[196:199], s[36:37]
	s_add_u32 s36, s36, 0x1000
	s_addc_u32 s37, s37, 0
	s_waitcnt vmcnt(15)
; __device__ __forceinline__ u32x4 pack8(const f32x4 v0, const f32x4 v1) { u32x4 w; w.x = cvt_pk_bf16(v0[0], v0[1]); w.y = cvt_pk_bf16(v0[2], v0[3]); w.z = cvt_pk_bf16(v1[0], v1[1]); w.w = cvt_pk_bf16(v1[2], v1[3]); return w; }
; __device__ __forceinline__ void unpack8(const u32x4 w, f32x4& lo, f32x4& hi) { lo = (f32x4){bf_lo(w.x), bf_hi(w.x), bf_lo(w.y), bf_hi(w.y)}; hi = (f32x4){bf_lo(w.z), bf_hi(w.z), bf_lo(w.w), bf_hi(w.w)}; }
; __device__ __forceinline__ void phase_pool(const bf16_t* PROJ, bf16_t* Z, int gw, int NGW, int lane) {
;     ...
;         for (int t = t0; t < t0 + 16; ++t) {
;             f32x4 v0, v1; unpack8(*(const u32x4*)(vb + (size_t)t * DIN), v0, v1); s0 += v0; s1 += v1;
;             if (t > t0 && t - win >= 0) { f32x4 a, c; unpack8(*(const u32x4*)(vb + (size_t)(t - win) * DIN), a, c); s0 -= a; s1 -= c; }
;             const float inv = 1.f / (float)((t + 1) < win ? (t + 1) : win);
;             *(u32x4*)(zb + (size_t)t * DSS) = pack8(s0 * inv - v0, s1 * inv - v1);
	v_lshlrev_b32_e32 v172, 16, v84
	v_and_b32_e32 v173, 0xffff0000, v84
	v_lshlrev_b32_e32 v174, 16, v85
	v_and_b32_e32 v175, 0xffff0000, v85
	v_lshlrev_b32_e32 v176, 16, v86
	v_and_b32_e32 v177, 0xffff0000, v86
	v_lshlrev_b32_e32 v178, 16, v87
	v_and_b32_e32 v179, 0xffff0000, v87
	v_pk_add_f32 v[164:165], v[164:165], v[172:173]
	v_pk_add_f32 v[166:167], v[166:167], v[174:175]
	v_pk_add_f32 v[168:169], v[168:169], v[176:177]
	v_pk_add_f32 v[170:171], v[170:171], v[178:179]
	v_lshlrev_b32_e32 v180, 16, v120
	v_and_b32_e32 v181, 0xffff0000, v120
	v_lshlrev_b32_e32 v182, 16, v121
	v_and_b32_e32 v183, 0xffff0000, v121
	v_lshlrev_b32_e32 v184, 16, v122
	v_and_b32_e32 v185, 0xffff0000, v122
	v_lshlrev_b32_e32 v186, 16, v123
	v_and_b32_e32 v187, 0xffff0000, v123
	v_sub_f32_e32 v164, v164, v180
	v_sub_f32_e32 v165, v165, v181
	v_sub_f32_e32 v166, v166, v182
	v_sub_f32_e32 v167, v167, v183
	v_sub_f32_e32 v168, v168, v184
	v_sub_f32_e32 v169, v169, v185
	v_sub_f32_e32 v170, v170, v186
	v_sub_f32_e32 v171, v171, v187
	s_cmp_eq_u32 s65, 0
	s_cselect_b32 s4, 0x3daaaaab, s72
	v_fma_f32 v188, v164, s4, -v172
	v_fma_f32 v189, v165, s4, -v173
	v_fma_f32 v190, v166, s4, -v174
	v_fma_f32 v191, v167, s4, -v175
	v_fma_f32 v192, v168, s4, -v176
	v_fma_f32 v193, v169, s4, -v177
	v_fma_f32 v194, v170, s4, -v178
	v_fma_f32 v195, v171, s4, -v179
	v_cvt_pk_bf16_f32 v196, v188, v189
	v_cvt_pk_bf16_f32 v197, v190, v191
	v_cvt_pk_bf16_f32 v198, v192, v193
	v_cvt_pk_bf16_f32 v199, v194, v195
	global_store_dwordx4 v39, v[196:199], s[36:37]
	s_add_u32 s36, s36, 0x1000
	s_addc_u32 s37, s37, 0
	s_waitcnt vmcnt(15)
	v_lshlrev_b32_e32 v172, 16, v88
	v_and_b32_e32 v173, 0xffff0000, v88
	v_lshlrev_b32_e32 v174, 16, v89
	v_and_b32_e32 v175, 0xffff0000, v89
	v_lshlrev_b32_e32 v176, 16, v90
	v_and_b32_e32 v177, 0xffff0000, v90
	v_lshlrev_b32_e32 v178, 16, v91
	v_and_b32_e32 v179, 0xffff0000, v91
	v_pk_add_f32 v[164:165], v[164:165], v[172:173]
	v_pk_add_f32 v[166:167], v[166:167], v[174:175]
	v_pk_add_f32 v[168:169], v[168:169], v[176:177]
	v_pk_add_f32 v[170:171], v[170:171], v[178:179]
	v_lshlrev_b32_e32 v180, 16, v116
	v_and_b32_e32 v181, 0xffff0000, v116
	v_lshlrev_b32_e32 v182, 16, v117
	v_and_b32_e32 v183, 0xffff0000, v117
	v_lshlrev_b32_e32 v184, 16, v118
	v_and_b32_e32 v185, 0xffff0000, v118
	v_lshlrev_b32_e32 v186, 16, v119
	v_and_b32_e32 v187, 0xffff0000, v119
	v_sub_f32_e32 v164, v164, v180
	v_sub_f32_e32 v165, v165, v181
	v_sub_f32_e32 v166, v166, v182
	v_sub_f32_e32 v167, v167, v183
	v_sub_f32_e32 v168, v168, v184
	v_sub_f32_e32 v169, v169, v185
	v_sub_f32_e32 v170, v170, v186
	v_sub_f32_e32 v171, v171, v187
	s_cmp_eq_u32 s65, 0
	s_cselect_b32 s4, 0x3d9d89d9, s72
	v_fma_f32 v188, v164, s4, -v172
	v_fma_f32 v189, v165, s4, -v173
	v_fma_f32 v190, v166, s4, -v174
	v_fma_f32 v191, v167, s4, -v175
	v_fma_f32 v192, v168, s4, -v176
	v_fma_f32 v193, v169, s4, -v177
	v_fma_f32 v194, v170, s4, -v178
	v_fma_f32 v195, v171, s4, -v179
	v_cvt_pk_bf16_f32 v196, v188, v189
	v_cvt_pk_bf16_f32 v197, v190, v191
	v_cvt_pk_bf16_f32 v198, v192, v193
	v_cvt_pk_bf16_f32 v199, v194, v195
	global_store_dwordx4 v39, v[196:199], s[36:37]
	s_add_u32 s36, s36, 0x1000
	s_addc_u32 s37, s37, 0
	s_waitcnt vmcnt(15)
	v_lshlrev_b32_e32 v172, 16, v92
	v_and_b32_e32 v173, 0xffff0000, v92
	v_lshlrev_b32_e32 v174, 16, v93
	v_and_b32_e32 v175, 0xffff0000, v93
	v_lshlrev_b32_e32 v176, 16, v94
	v_and_b32_e32 v177, 0xffff0000, v94
	v_lshlrev_b32_e32 v178, 16, v95
	v_and_b32_e32 v179, 0xffff0000, v95
	v_pk_add_f32 v[164:165], v[164:165], v[172:173]
	v_pk_add_f32 v[166:167], v[166:167], v[174:175]
	v_pk_add_f32 v[168:169], v[168:169], v[176:177]
	v_pk_add_f32 v[170:171], v[170:171], v[178:179]
	v_lshlrev_b32_e32 v180, 16, v112
	v_and_b32_e32 v181, 0xffff0000, v112
	v_lshlrev_b32_e32 v182, 16, v113
	v_and_b32_e32 v183, 0xffff0000, v113
	v_lshlrev_b32_e32 v184, 16, v114
	v_and_b32_e32 v185, 0xffff0000, v114
	v_lshlrev_b32_e32 v186, 16, v115
	v_and_b32_e32 v187, 0xffff0000, v115
	v_sub_f32_e32 v164, v164, v180
	v_sub_f32_e32 v165, v165, v181
	v_sub_f32_e32 v166, v166, v182
	v_sub_f32_e32 v167, v167, v183
	v_sub_f32_e32 v168, v168, v184
	v_sub_f32_e32 v169, v169, v185
	v_sub_f32_e32 v170, v170, v186
	v_sub_f32_e32 v171, v171, v187
	s_cmp_eq_u32 s65, 0
	s_cselect_b32 s4, 0x3d924925, s72
	v_fma_f32 v188, v164, s4, -v172
	v_fma_f32 v189, v165, s4, -v173
	v_fma_f32 v190, v166, s4, -v174
	v_fma_f32 v191, v167, s4, -v175
	v_fma_f32 v192, v168, s4, -v176
	v_fma_f32 v193, v169, s4, -v177
	v_fma_f32 v194, v170, s4, -v178
	v_fma_f32 v195, v171, s4, -v179
	v_cvt_pk_bf16_f32 v196, v188, v189
	v_cvt_pk_bf16_f32 v197, v190, v191
	v_cvt_pk_bf16_f32 v198, v192, v193
	v_cvt_pk_bf16_f32 v199, v194, v195
	global_store_dwordx4 v39, v[196:199], s[36:37]
	s_add_u32 s36, s36, 0x1000
	s_addc_u32 s37, s37, 0
	s_waitcnt vmcnt(15)
	v_lshlrev_b32_e32 v172, 16, v96
	v_and_b32_e32 v173, 0xffff0000, v96
	v_lshlrev_b32_e32 v174, 16, v97
	v_and_b32_e32 v175, 0xffff0000, v97
	v_lshlrev_b32_e32 v176, 16, v98
	v_and_b32_e32 v177, 0xffff0000, v98
	v_lshlrev_b32_e32 v178, 16, v99
	v_and_b32_e32 v179, 0xffff0000, v99
	v_pk_add_f32 v[164:165], v[164:165], v[172:173]
	v_pk_add_f32 v[166:167], v[166:167], v[174:175]
	v_pk_add_f32 v[168:169], v[168:169], v[176:177]
	v_pk_add_f32 v[170:171], v[170:171], v[178:179]
	v_lshlrev_b32_e32 v180, 16, v108
	v_and_b32_e32 v181, 0xffff0000, v108
	v_lshlrev_b32_e32 v182, 16, v109
	v_and_b32_e32 v183, 0xffff0000, v109
	v_lshlrev_b32_e32 v184, 16, v110
	v_and_b32_e32 v185, 0xffff0000, v110
	v_lshlrev_b32_e32 v186, 16, v111
	v_and_b32_e32 v187, 0xffff0000, v111
	v_sub_f32_e32 v164, v164, v180
	v_sub_f32_e32 v165, v165, v181
	v_sub_f32_e32 v166, v166, v182
	v_sub_f32_e32 v167, v167, v183
	v_sub_f32_e32 v168, v168, v184
	v_sub_f32_e32 v169, v169, v185
	v_sub_f32_e32 v170, v170, v186
	v_sub_f32_e32 v171, v171, v187
	s_cmp_eq_u32 s65, 0
	s_cselect_b32 s4, 0x3d888889, s72
	v_fma_f32 v188, v164, s4, -v172
	v_fma_f32 v189, v165, s4, -v173
	v_fma_f32 v190, v166, s4, -v174
	v_fma_f32 v191, v167, s4, -v175
	v_fma_f32 v192, v168, s4, -v176
	v_fma_f32 v193, v169, s4, -v177
	v_fma_f32 v194, v170, s4, -v178
	v_fma_f32 v195, v171, s4, -v179
	v_cvt_pk_bf16_f32 v196, v188, v189
	v_cvt_pk_bf16_f32 v197, v190, v191
	v_cvt_pk_bf16_f32 v198, v192, v193
	v_cvt_pk_bf16_f32 v199, v194, v195
	global_store_dwordx4 v39, v[196:199], s[36:37]
	s_add_u32 s36, s36, 0x1000
	s_addc_u32 s37, s37, 0
	s_waitcnt vmcnt(15)
; __device__ __forceinline__ u32x4 pack8(const f32x4 v0, const f32x4 v1) { u32x4 w; w.x = cvt_pk_bf16(v0[0], v0[1]); w.y = cvt_pk_bf16(v0[2], v0[3]); w.z = cvt_pk_bf16(v1[0], v1[1]); w.w = cvt_pk_bf16(v1[2], v1[3]); return w; }
; __device__ __forceinline__ void unpack8(const u32x4 w, f32x4& lo, f32x4& hi) { lo = (f32x4){bf_lo(w.x), bf_hi(w.x), bf_lo(w.y), bf_hi(w.y)}; hi = (f32x4){bf_lo(w.z), bf_hi(w.z), bf_lo(w.w), bf_hi(w.w)}; }
; __device__ __forceinline__ void phase_pool(const bf16_t* PROJ, bf16_t* Z, int gw, int NGW, int lane) {
;     ...
;         const int t0 = tseg * 16;
;         for (int tau = (t0 - win + 1 > 0 ? t0 - win + 1 : 0); tau < t0; ++tau) { f32x4 a, c; unpack8(*(const u32x4*)(vb + (size_t)tau * DIN), a, c); s0 += a; s1 += c; }
;         for (int t = t0; t < t0 + 16; ++t) {
;             f32x4 v0, v1; unpack8(*(const u32x4*)(vb + (size_t)t * DIN), v0, v1); s0 += v0; s1 += v1;
;             if (t > t0 && t - win >= 0) { f32x4 a, c; unpack8(*(const u32x4*)(vb + (size_t)(t - win) * DIN), a, c); s0 -= a; s1 -= c; }
;             const float inv = 1.f / (float)((t + 1) < win ? (t + 1) : win);
;             *(u32x4*)(zb + (size_t)t * DSS) = pack8(s0 * inv - v0, s1 * inv - v1);
	v_lshlrev_b32_e32 v172, 16, v100
	v_and_b32_e32 v173, 0xffff0000, v100
	v_lshlrev_b32_e32 v174, 16, v101
	v_and_b32_e32 v175, 0xffff0000, v101
	v_lshlrev_b32_e32 v176, 16, v102
	v_and_b32_e32 v177, 0xffff0000, v102
	v_lshlrev_b32_e32 v178, 16, v103
	v_and_b32_e32 v179, 0xffff0000, v103
	v_pk_add_f32 v[164:165], v[164:165], v[172:173]
	v_pk_add_f32 v[166:167], v[166:167], v[174:175]
	v_pk_add_f32 v[168:169], v[168:169], v[176:177]
	v_pk_add_f32 v[170:171], v[170:171], v[178:179]
	v_lshlrev_b32_e32 v180, 16, v104
	v_and_b32_e32 v181, 0xffff0000, v104
	v_lshlrev_b32_e32 v182, 16, v105
	v_and_b32_e32 v183, 0xffff0000, v105
	v_lshlrev_b32_e32 v184, 16, v106
	v_and_b32_e32 v185, 0xffff0000, v106
	v_lshlrev_b32_e32 v186, 16, v107
	v_and_b32_e32 v187, 0xffff0000, v107
	v_sub_f32_e32 v164, v164, v180
	v_sub_f32_e32 v165, v165, v181
	v_sub_f32_e32 v166, v166, v182
	v_sub_f32_e32 v167, v167, v183
	v_sub_f32_e32 v168, v168, v184
	v_sub_f32_e32 v169, v169, v185
	v_sub_f32_e32 v170, v170, v186
	v_sub_f32_e32 v171, v171, v187
	v_fma_f32 v188, v164, s72, -v172
	v_fma_f32 v189, v165, s72, -v173
	v_fma_f32 v190, v166, s72, -v174
	v_fma_f32 v191, v167, s72, -v175
	v_fma_f32 v192, v168, s72, -v176
	v_fma_f32 v193, v169, s72, -v177
	v_fma_f32 v194, v170, s72, -v178
	v_fma_f32 v195, v171, s72, -v179
	v_cvt_pk_bf16_f32 v196, v188, v189
	v_cvt_pk_bf16_f32 v197, v190, v191
	v_cvt_pk_bf16_f32 v198, v192, v193
	v_cvt_pk_bf16_f32 v199, v194, v195
	global_store_dwordx4 v39, v[196:199], s[36:37]
	s_branch .LBB0_300
.Lpool_w8:
	s_mov_b32 s72, 0x3e000000
	s_cmp_eq_u32 s65, 0
	s_cbranch_scc1 .Lpool_w8_zero
	s_sub_u32 s38, s70, 0x2a000
	s_subb_u32 s39, s71, 0
	global_load_dwordx4 v[128:131], v39, s[38:39]
	s_add_u32 s38, s38, 0x6000
	s_addc_u32 s39, s39, 0
	global_load_dwordx4 v[124:127], v39, s[38:39]
	s_add_u32 s38, s38, 0x6000
	s_addc_u32 s39, s39, 0
	global_load_dwordx4 v[120:123], v39, s[38:39]
	s_add_u32 s38, s38, 0x6000
	s_addc_u32 s39, s39, 0
	global_load_dwordx4 v[116:119], v39, s[38:39]
	s_add_u32 s38, s38, 0x6000
	s_addc_u32 s39, s39, 0
	global_load_dwordx4 v[112:115], v39, s[38:39]
	s_add_u32 s38, s38, 0x6000
	s_addc_u32 s39, s39, 0
	global_load_dwordx4 v[108:111], v39, s[38:39]
	s_add_u32 s38, s38, 0x6000
	s_addc_u32 s39, s39, 0
	global_load_dwordx4 v[104:107], v39, s[38:39]
	s_branch .Lpool_w8_a
.Lpool_w8_zero:
	v_mov_b32_e32 v104, 0
	v_mov_b32_e32 v105, 0
	v_mov_b32_e32 v106, 0
	v_mov_b32_e32 v107, 0
	v_mov_b32_e32 v108, 0
	v_mov_b32_e32 v109, 0
	v_mov_b32_e32 v110, 0
	v_mov_b32_e32 v111, 0
	v_mov_b32_e32 v112, 0
	v_mov_b32_e32 v113, 0
	v_mov_b32_e32 v114, 0
	v_mov_b32_e32 v115, 0
	v_mov_b32_e32 v116, 0
	v_mov_b32_e32 v117, 0
	v_mov_b32_e32 v118, 0
	v_mov_b32_e32 v119, 0
	v_mov_b32_e32 v120, 0
	v_mov_b32_e32 v121, 0
	v_mov_b32_e32 v122, 0
	v_mov_b32_e32 v123, 0
	v_mov_b32_e32 v124, 0
	v_mov_b32_e32 v125, 0
	v_mov_b32_e32 v126, 0
	v_mov_b32_e32 v127, 0
	v_mov_b32_e32 v128, 0
	v_mov_b32_e32 v129, 0
	v_mov_b32_e32 v130, 0
	v_mov_b32_e32 v131, 0
.Lpool_w8_a:
	global_load_dwordx4 v[40:43], v39, s[70:71]
	s_add_u32 s70, s70, 0x6000
	s_addc_u32 s71, s71, 0
	global_load_dwordx4 v[44:47], v39, s[70:71]
	s_add_u32 s70, s70, 0x6000
	s_addc_u32 s71, s71, 0
	global_load_dwordx4 v[48:51], v39, s[70:71]
	s_add_u32 s70, s70, 0x6000
	s_addc_u32 s71, s71, 0
	global_load_dwordx4 v[52:55], v39, s[70:71]
	s_add_u32 s70, s70, 0x6000
	s_addc_u32 s71, s71, 0
	global_load_dwordx4 v[56:59], v39, s[70:71]
	s_add_u32 s70, s70, 0x6000
	s_addc_u32 s71, s71, 0
	global_load_dwordx4 v[60:63], v39, s[70:71]
	s_add_u32 s70, s70, 0x6000
	s_addc_u32 s71, s71, 0
	global_load_dwordx4 v[64:67], v39, s[70:71]
	s_add_u32 s70, s70, 0x6000
	s_addc_u32 s71, s71, 0
	global_load_dwordx4 v[68:71], v39, s[70:71]
	s_add_u32 s70, s70, 0x6000
	s_addc_u32 s71, s71, 0
	global_load_dwordx4 v[72:75], v39, s[70:71]
	s_add_u32 s70, s70, 0x6000
	s_addc_u32 s71, s71, 0
	global_load_dwordx4 v[76:79], v39, s[70:71]
	s_add_u32 s70, s70, 0x6000
	s_addc_u32 s71, s71, 0
	global_load_dwordx4 v[80:83], v39, s[70:71]
	s_add_u32 s70, s70, 0x6000
	s_addc_u32 s71, s71, 0
	global_load_dwordx4 v[84:87], v39, s[70:71]
	s_add_u32 s70, s70, 0x6000
	s_addc_u32 s71, s71, 0
	global_load_dwordx4 v[88:91], v39, s[70:71]
	s_add_u32 s70, s70, 0x6000
	s_addc_u32 s71, s71, 0
	global_load_dwordx4 v[92:95], v39, s[70:71]
	s_add_u32 s70, s70, 0x6000
	s_addc_u32 s71, s71, 0
	global_load_dwordx4 v[96:99], v39, s[70:71]
	s_add_u32 s70, s70, 0x6000
	s_addc_u32 s71, s71, 0
	global_load_dwordx4 v[100:103], v39, s[70:71]
	s_waitcnt vmcnt(15)
; __device__ __forceinline__ u32x4 pack8(const f32x4 v0, const f32x4 v1) { u32x4 w; w.x = cvt_pk_bf16(v0[0], v0[1]); w.y = cvt_pk_bf16(v0[2], v0[3]); w.z = cvt_pk_bf16(v1[0], v1[1]); w.w = cvt_pk_bf16(v1[2], v1[3]); return w; }
; __device__ __forceinline__ void unpack8(const u32x4 w, f32x4& lo, f32x4& hi) { lo = (f32x4){bf_lo(w.x), bf_hi(w.x), bf_lo(w.y), bf_hi(w.y)}; hi = (f32x4){bf_lo(w.z), bf_hi(w.z), bf_lo(w.w), bf_hi(w.w)}; }
; __device__ __forceinline__ void phase_pool(const bf16_t* PROJ, bf16_t* Z, int gw, int NGW, int lane) {
;     ...
;         const int t0 = tseg * 16;
;         for (int tau = (t0 - win + 1 > 0 ? t0 - win + 1 : 0); tau < t0; ++tau) { f32x4 a, c; unpack8(*(const u32x4*)(vb + (size_t)tau * DIN), a, c); s0 += a; s1 += c; }
;         for (int t = t0; t < t0 + 16; ++t) {
;             f32x4 v0, v1; unpack8(*(const u32x4*)(vb + (size_t)t * DIN), v0, v1); s0 += v0; s1 += v1;
;             if (t > t0 && t - win >= 0) { f32x4 a, c; unpack8(*(const u32x4*)(vb + (size_t)(t - win) * DIN), a, c); s0 -= a; s1 -= c; }
;             const float inv = 1.f / (float)((t + 1) < win ? (t + 1) : win);
;             *(u32x4*)(zb + (size_t)t * DSS) = pack8(s0 * inv - v0, s1 * inv - v1);
	v_lshlrev_b32_e32 v164, 16, v128
	v_and_b32_e32 v165, 0xffff0000, v128
	v_lshlrev_b32_e32 v166, 16, v129
	v_and_b32_e32 v167, 0xffff0000, v129
	v_lshlrev_b32_e32 v168, 16, v130
	v_and_b32_e32 v169, 0xffff0000, v130
	v_lshlrev_b32_e32 v170, 16, v131
	v_and_b32_e32 v171, 0xffff0000, v131
	v_lshlrev_b32_e32 v172, 16, v124
	v_and_b32_e32 v173, 0xffff0000, v124
	v_lshlrev_b32_e32 v174, 16, v125
	v_and_b32_e32 v175, 0xffff0000, v125
	v_lshlrev_b32_e32 v176, 16, v126
	v_and_b32_e32 v177, 0xffff0000, v126
	v_lshlrev_b32_e32 v178, 16, v127
	v_and_b32_e32 v179, 0xffff0000, v127
	v_pk_add_f32 v[164:165], v[164:165], v[172:173]
	v_pk_add_f32 v[166:167], v[166:167], v[174:175]
	v_pk_add_f32 v[168:169], v[168:169], v[176:177]
	v_pk_add_f32 v[170:171], v[170:171], v[178:179]
	v_lshlrev_b32_e32 v172, 16, v120
	v_and_b32_e32 v173, 0xffff0000, v120
	v_lshlrev_b32_e32 v174, 16, v121
	v_and_b32_e32 v175, 0xffff0000, v121
	v_lshlrev_b32_e32 v176, 16, v122
	v_and_b32_e32 v177, 0xffff0000, v122
	v_lshlrev_b32_e32 v178, 16, v123
	v_and_b32_e32 v179, 0xffff0000, v123
	v_pk_add_f32 v[164:165], v[164:165], v[172:173]
	v_pk_add_f32 v[166:167], v[166:167], v[174:175]
	v_pk_add_f32 v[168:169], v[168:169], v[176:177]
	v_pk_add_f32 v[170:171], v[170:171], v[178:179]
	v_lshlrev_b32_e32 v172, 16, v116
	v_and_b32_e32 v173, 0xffff0000, v116
	v_lshlrev_b32_e32 v174, 16, v117
	v_and_b32_e32 v175, 0xffff0000, v117
	v_lshlrev_b32_e32 v176, 16, v118
	v_and_b32_e32 v177, 0xffff0000, v118
	v_lshlrev_b32_e32 v178, 16, v119
	v_and_b32_e32 v179, 0xffff0000, v119
	v_pk_add_f32 v[164:165], v[164:165], v[172:173]
	v_pk_add_f32 v[166:167], v[166:167], v[174:175]
	v_pk_add_f32 v[168:169], v[168:169], v[176:177]
	v_pk_add_f32 v[170:171], v[170:171], v[178:179]
	v_lshlrev_b32_e32 v172, 16, v112
	v_and_b32_e32 v173, 0xffff0000, v112
	v_lshlrev_b32_e32 v174, 16, v113
	v_and_b32_e32 v175, 0xffff0000, v113
	v_lshlrev_b32_e32 v176, 16, v114
	v_and_b32_e32 v177, 0xffff0000, v114
	v_lshlrev_b32_e32 v178, 16, v115
	v_and_b32_e32 v179, 0xffff0000, v115
	v_pk_add_f32 v[164:165], v[164:165], v[172:173]
	v_pk_add_f32 v[166:167], v[166:167], v[174:175]
	v_pk_add_f32 v[168:169], v[168:169], v[176:177]
	v_pk_add_f32 v[170:171], v[170:171], v[178:179]
	v_lshlrev_b32_e32 v172, 16, v108
	v_and_b32_e32 v173, 0xffff0000, v108
	v_lshlrev_b32_e32 v174, 16, v109
	v_and_b32_e32 v175, 0xffff0000, v109
	v_lshlrev_b32_e32 v176, 16, v110
	v_and_b32_e32 v177, 0xffff0000, v110
	v_lshlrev_b32_e32 v178, 16, v111
	v_and_b32_e32 v179, 0xffff0000, v111
	v_pk_add_f32 v[164:165], v[164:165], v[172:173]
	v_pk_add_f32 v[166:167], v[166:167], v[174:175]
	v_pk_add_f32 v[168:169], v[168:169], v[176:177]
	v_pk_add_f32 v[170:171], v[170:171], v[178:179]
	v_lshlrev_b32_e32 v172, 16, v104
	v_and_b32_e32 v173, 0xffff0000, v104
	v_lshlrev_b32_e32 v174, 16, v105
	v_and_b32_e32 v175, 0xffff0000, v105
	v_lshlrev_b32_e32 v176, 16, v106
	v_and_b32_e32 v177, 0xffff0000, v106
	v_lshlrev_b32_e32 v178, 16, v107
	v_and_b32_e32 v179, 0xffff0000, v107
	v_pk_add_f32 v[164:165], v[164:165], v[172:173]
	v_pk_add_f32 v[166:167], v[166:167], v[174:175]
	v_pk_add_f32 v[168:169], v[168:169], v[176:177]
	v_pk_add_f32 v[170:171], v[170:171], v[178:179]
	v_lshlrev_b32_e32 v172, 16, v40
	v_and_b32_e32 v173, 0xffff0000, v40
	v_lshlrev_b32_e32 v174, 16, v41
	v_and_b32_e32 v175, 0xffff0000, v41
	v_lshlrev_b32_e32 v176, 16, v42
	v_and_b32_e32 v177, 0xffff0000, v42
	v_lshlrev_b32_e32 v178, 16, v43
	v_and_b32_e32 v179, 0xffff0000, v43
	v_pk_add_f32 v[164:165], v[164:165], v[172:173]
	v_pk_add_f32 v[166:167], v[166:167], v[174:175]
	v_pk_add_f32 v[168:169], v[168:169], v[176:177]
	v_pk_add_f32 v[170:171], v[170:171], v[178:179]
	s_cmp_eq_u32 s65, 0
	s_cselect_b32 s4, 0x3f800000, s72
	v_fma_f32 v188, v164, s4, -v172
	v_fma_f32 v189, v165, s4, -v173
	v_fma_f32 v190, v166, s4, -v174
	v_fma_f32 v191, v167, s4, -v175
	v_fma_f32 v192, v168, s4, -v176
	v_fma_f32 v193, v169, s4, -v177
	v_fma_f32 v194, v170, s4, -v178
	v_fma_f32 v195, v171, s4, -v179
	v_cvt_pk_bf16_f32 v196, v188, v189
	v_cvt_pk_bf16_f32 v197, v190, v191
	v_cvt_pk_bf16_f32 v198, v192, v193
	v_cvt_pk_bf16_f32 v199, v194, v195
	global_store_dwordx4 v39, v[196:199], s[36:37]
	s_add_u32 s36, s36, 0x1000
	s_addc_u32 s37, s37, 0
	s_waitcnt vmcnt(15)
	v_lshlrev_b32_e32 v172, 16, v44
	v_and_b32_e32 v173, 0xffff0000, v44
	v_lshlrev_b32_e32 v174, 16, v45
	v_and_b32_e32 v175, 0xffff0000, v45
	v_lshlrev_b32_e32 v176, 16, v46
	v_and_b32_e32 v177, 0xffff0000, v46
	v_lshlrev_b32_e32 v178, 16, v47
	v_and_b32_e32 v179, 0xffff0000, v47
	v_pk_add_f32 v[164:165], v[164:165], v[172:173]
	v_pk_add_f32 v[166:167], v[166:167], v[174:175]
	v_pk_add_f32 v[168:169], v[168:169], v[176:177]
	v_pk_add_f32 v[170:171], v[170:171], v[178:179]
	v_lshlrev_b32_e32 v180, 16, v128
	v_and_b32_e32 v181, 0xffff0000, v128
	v_lshlrev_b32_e32 v182, 16, v129
	v_and_b32_e32 v183, 0xffff0000, v129
	v_lshlrev_b32_e32 v184, 16, v130
	v_and_b32_e32 v185, 0xffff0000, v130
	v_lshlrev_b32_e32 v186, 16, v131
	v_and_b32_e32 v187, 0xffff0000, v131
	v_sub_f32_e32 v164, v164, v180
	v_sub_f32_e32 v165, v165, v181
	v_sub_f32_e32 v166, v166, v182
	v_sub_f32_e32 v167, v167, v183
	v_sub_f32_e32 v168, v168, v184
	v_sub_f32_e32 v169, v169, v185
	v_sub_f32_e32 v170, v170, v186
	v_sub_f32_e32 v171, v171, v187
	s_cmp_eq_u32 s65, 0
	s_cselect_b32 s4, 0x3f000000, s72
	v_fma_f32 v188, v164, s4, -v172
	v_fma_f32 v189, v165, s4, -v173
	v_fma_f32 v190, v166, s4, -v174
	v_fma_f32 v191, v167, s4, -v175
	v_fma_f32 v192, v168, s4, -v176
	v_fma_f32 v193, v169, s4, -v177
	v_fma_f32 v194, v170, s4, -v178
	v_fma_f32 v195, v171, s4, -v179
	v_cvt_pk_bf16_f32 v196, v188, v189
	v_cvt_pk_bf16_f32 v197, v190, v191
	v_cvt_pk_bf16_f32 v198, v192, v193
	v_cvt_pk_bf16_f32 v199, v194, v195
	global_store_dwordx4 v39, v[196:199], s[36:37]
	s_add_u32 s36, s36, 0x1000
	s_addc_u32 s37, s37, 0
	s_waitcnt vmcnt(15)
; __device__ __forceinline__ u32x4 pack8(const f32x4 v0, const f32x4 v1) { u32x4 w; w.x = cvt_pk_bf16(v0[0], v0[1]); w.y = cvt_pk_bf16(v0[2], v0[3]); w.z = cvt_pk_bf16(v1[0], v1[1]); w.w = cvt_pk_bf16(v1[2], v1[3]); return w; }
; __device__ __forceinline__ void unpack8(const u32x4 w, f32x4& lo, f32x4& hi) { lo = (f32x4){bf_lo(w.x), bf_hi(w.x), bf_lo(w.y), bf_hi(w.y)}; hi = (f32x4){bf_lo(w.z), bf_hi(w.z), bf_lo(w.w), bf_hi(w.w)}; }
; __device__ __forceinline__ void phase_pool(const bf16_t* PROJ, bf16_t* Z, int gw, int NGW, int lane) {
;     ...
;         for (int t = t0; t < t0 + 16; ++t) {
;             f32x4 v0, v1; unpack8(*(const u32x4*)(vb + (size_t)t * DIN), v0, v1); s0 += v0; s1 += v1;
;             if (t > t0 && t - win >= 0) { f32x4 a, c; unpack8(*(const u32x4*)(vb + (size_t)(t - win) * DIN), a, c); s0 -= a; s1 -= c; }
;             const float inv = 1.f / (float)((t + 1) < win ? (t + 1) : win);
;             *(u32x4*)(zb + (size_t)t * DSS) = pack8(s0 * inv - v0, s1 * inv - v1);
	v_lshlrev_b32_e32 v172, 16, v48
	v_and_b32_e32 v173, 0xffff0000, v48
	v_lshlrev_b32_e32 v174, 16, v49
	v_and_b32_e32 v175, 0xffff0000, v49
	v_lshlrev_b32_e32 v176, 16, v50
	v_and_b32_e32 v177, 0xffff0000, v50
	v_lshlrev_b32_e32 v178, 16, v51
	v_and_b32_e32 v179, 0xffff0000, v51
	v_pk_add_f32 v[164:165], v[164:165], v[172:173]
	v_pk_add_f32 v[166:167], v[166:167], v[174:175]
	v_pk_add_f32 v[168:169], v[168:169], v[176:177]
	v_pk_add_f32 v[170:171], v[170:171], v[178:179]
	v_lshlrev_b32_e32 v180, 16, v124
	v_and_b32_e32 v181, 0xffff0000, v124
	v_lshlrev_b32_e32 v182, 16, v125
	v_and_b32_e32 v183, 0xffff0000, v125
	v_lshlrev_b32_e32 v184, 16, v126
	v_and_b32_e32 v185, 0xffff0000, v126
	v_lshlrev_b32_e32 v186, 16, v127
	v_and_b32_e32 v187, 0xffff0000, v127
	v_sub_f32_e32 v164, v164, v180
	v_sub_f32_e32 v165, v165, v181
	v_sub_f32_e32 v166, v166, v182
	v_sub_f32_e32 v167, v167, v183
	v_sub_f32_e32 v168, v168, v184
	v_sub_f32_e32 v169, v169, v185
	v_sub_f32_e32 v170, v170, v186
	v_sub_f32_e32 v171, v171, v187
	s_cmp_eq_u32 s65, 0
	s_cselect_b32 s4, 0x3eaaaaab, s72
	v_fma_f32 v188, v164, s4, -v172
	v_fma_f32 v189, v165, s4, -v173
	v_fma_f32 v190, v166, s4, -v174
	v_fma_f32 v191, v167, s4, -v175
	v_fma_f32 v192, v168, s4, -v176
	v_fma_f32 v193, v169, s4, -v177
	v_fma_f32 v194, v170, s4, -v178
	v_fma_f32 v195, v171, s4, -v179
	v_cvt_pk_bf16_f32 v196, v188, v189
	v_cvt_pk_bf16_f32 v197, v190, v191
	v_cvt_pk_bf16_f32 v198, v192, v193
	v_cvt_pk_bf16_f32 v199, v194, v195
	global_store_dwordx4 v39, v[196:199], s[36:37]
	s_add_u32 s36, s36, 0x1000
	s_addc_u32 s37, s37, 0
	s_waitcnt vmcnt(15)
	v_lshlrev_b32_e32 v172, 16, v52
	v_and_b32_e32 v173, 0xffff0000, v52
	v_lshlrev_b32_e32 v174, 16, v53
	v_and_b32_e32 v175, 0xffff0000, v53
	v_lshlrev_b32_e32 v176, 16, v54
	v_and_b32_e32 v177, 0xffff0000, v54
	v_lshlrev_b32_e32 v178, 16, v55
	v_and_b32_e32 v179, 0xffff0000, v55
	v_pk_add_f32 v[164:165], v[164:165], v[172:173]
	v_pk_add_f32 v[166:167], v[166:167], v[174:175]
	v_pk_add_f32 v[168:169], v[168:169], v[176:177]
	v_pk_add_f32 v[170:171], v[170:171], v[178:179]
	v_lshlrev_b32_e32 v180, 16, v120
	v_and_b32_e32 v181, 0xffff0000, v120
	v_lshlrev_b32_e32 v182, 16, v121
	v_and_b32_e32 v183, 0xffff0000, v121
	v_lshlrev_b32_e32 v184, 16, v122
	v_and_b32_e32 v185, 0xffff0000, v122
	v_lshlrev_b32_e32 v186, 16, v123
	v_and_b32_e32 v187, 0xffff0000, v123
	v_sub_f32_e32 v164, v164, v180
	v_sub_f32_e32 v165, v165, v181
	v_sub_f32_e32 v166, v166, v182
	v_sub_f32_e32 v167, v167, v183
	v_sub_f32_e32 v168, v168, v184
	v_sub_f32_e32 v169, v169, v185
	v_sub_f32_e32 v170, v170, v186
	v_sub_f32_e32 v171, v171, v187
	s_cmp_eq_u32 s65, 0
	s_cselect_b32 s4, 0x3e800000, s72
	v_fma_f32 v188, v164, s4, -v172
	v_fma_f32 v189, v165, s4, -v173
	v_fma_f32 v190, v166, s4, -v174
	v_fma_f32 v191, v167, s4, -v175
	v_fma_f32 v192, v168, s4, -v176
	v_fma_f32 v193, v169, s4, -v177
	v_fma_f32 v194, v170, s4, -v178
	v_fma_f32 v195, v171, s4, -v179
	v_cvt_pk_bf16_f32 v196, v188, v189
	v_cvt_pk_bf16_f32 v197, v190, v191
	v_cvt_pk_bf16_f32 v198, v192, v193
	v_cvt_pk_bf16_f32 v199, v194, v195
	global_store_dwordx4 v39, v[196:199], s[36:37]
	s_add_u32 s36, s36, 0x1000
	s_addc_u32 s37, s37, 0
	s_waitcnt vmcnt(15)
	v_lshlrev_b32_e32 v172, 16, v56
	v_and_b32_e32 v173, 0xffff0000, v56
	v_lshlrev_b32_e32 v174, 16, v57
	v_and_b32_e32 v175, 0xffff0000, v57
	v_lshlrev_b32_e32 v176, 16, v58
	v_and_b32_e32 v177, 0xffff0000, v58
	v_lshlrev_b32_e32 v178, 16, v59
	v_and_b32_e32 v179, 0xffff0000, v59
	v_pk_add_f32 v[164:165], v[164:165], v[172:173]
	v_pk_add_f32 v[166:167], v[166:167], v[174:175]
	v_pk_add_f32 v[168:169], v[168:169], v[176:177]
	v_pk_add_f32 v[170:171], v[170:171], v[178:179]
	v_lshlrev_b32_e32 v180, 16, v116
	v_and_b32_e32 v181, 0xffff0000, v116
	v_lshlrev_b32_e32 v182, 16, v117
	v_and_b32_e32 v183, 0xffff0000, v117
	v_lshlrev_b32_e32 v184, 16, v118
	v_and_b32_e32 v185, 0xffff0000, v118
	v_lshlrev_b32_e32 v186, 16, v119
	v_and_b32_e32 v187, 0xffff0000, v119
	v_sub_f32_e32 v164, v164, v180
	v_sub_f32_e32 v165, v165, v181
	v_sub_f32_e32 v166, v166, v182
	v_sub_f32_e32 v167, v167, v183
	v_sub_f32_e32 v168, v168, v184
	v_sub_f32_e32 v169, v169, v185
	v_sub_f32_e32 v170, v170, v186
	v_sub_f32_e32 v171, v171, v187
	s_cmp_eq_u32 s65, 0
	s_cselect_b32 s4, 0x3e4ccccd, s72
	v_fma_f32 v188, v164, s4, -v172
	v_fma_f32 v189, v165, s4, -v173
	v_fma_f32 v190, v166, s4, -v174
	v_fma_f32 v191, v167, s4, -v175
	v_fma_f32 v192, v168, s4, -v176
	v_fma_f32 v193, v169, s4, -v177
	v_fma_f32 v194, v170, s4, -v178
	v_fma_f32 v195, v171, s4, -v179
	v_cvt_pk_bf16_f32 v196, v188, v189
	v_cvt_pk_bf16_f32 v197, v190, v191
	v_cvt_pk_bf16_f32 v198, v192, v193
	v_cvt_pk_bf16_f32 v199, v194, v195
	global_store_dwordx4 v39, v[196:199], s[36:37]
	s_add_u32 s36, s36, 0x1000
	s_addc_u32 s37, s37, 0
	s_waitcnt vmcnt(15)
	v_lshlrev_b32_e32 v172, 16, v60
	v_and_b32_e32 v173, 0xffff0000, v60
	v_lshlrev_b32_e32 v174, 16, v61
	v_and_b32_e32 v175, 0xffff0000, v61
	v_lshlrev_b32_e32 v176, 16, v62
	v_and_b32_e32 v177, 0xffff0000, v62
	v_lshlrev_b32_e32 v178, 16, v63
	v_and_b32_e32 v179, 0xffff0000, v63
	v_pk_add_f32 v[164:165], v[164:165], v[172:173]
	v_pk_add_f32 v[166:167], v[166:167], v[174:175]
	v_pk_add_f32 v[168:169], v[168:169], v[176:177]
	v_pk_add_f32 v[170:171], v[170:171], v[178:179]
	v_lshlrev_b32_e32 v180, 16, v112
	v_and_b32_e32 v181, 0xffff0000, v112
	v_lshlrev_b32_e32 v182, 16, v113
	v_and_b32_e32 v183, 0xffff0000, v113
	v_lshlrev_b32_e32 v184, 16, v114
	v_and_b32_e32 v185, 0xffff0000, v114
	v_lshlrev_b32_e32 v186, 16, v115
	v_and_b32_e32 v187, 0xffff0000, v115
	v_sub_f32_e32 v164, v164, v180
	v_sub_f32_e32 v165, v165, v181
	v_sub_f32_e32 v166, v166, v182
	v_sub_f32_e32 v167, v167, v183
	v_sub_f32_e32 v168, v168, v184
	v_sub_f32_e32 v169, v169, v185
	v_sub_f32_e32 v170, v170, v186
	v_sub_f32_e32 v171, v171, v187
	s_cmp_eq_u32 s65, 0
	s_cselect_b32 s4, 0x3e2aaaab, s72
	v_fma_f32 v188, v164, s4, -v172
	v_fma_f32 v189, v165, s4, -v173
	v_fma_f32 v190, v166, s4, -v174
	v_fma_f32 v191, v167, s4, -v175
	v_fma_f32 v192, v168, s4, -v176
	v_fma_f32 v193, v169, s4, -v177
	v_fma_f32 v194, v170, s4, -v178
	v_fma_f32 v195, v171, s4, -v179
	v_cvt_pk_bf16_f32 v196, v188, v189
	v_cvt_pk_bf16_f32 v197, v190, v191
	v_cvt_pk_bf16_f32 v198, v192, v193
	v_cvt_pk_bf16_f32 v199, v194, v195
	global_store_dwordx4 v39, v[196:199], s[36:37]
	s_add_u32 s36, s36, 0x1000
	s_addc_u32 s37, s37, 0
	s_waitcnt vmcnt(15)
; __device__ __forceinline__ u32x4 pack8(const f32x4 v0, const f32x4 v1) { u32x4 w; w.x = cvt_pk_bf16(v0[0], v0[1]); w.y = cvt_pk_bf16(v0[2], v0[3]); w.z = cvt_pk_bf16(v1[0], v1[1]); w.w = cvt_pk_bf16(v1[2], v1[3]); return w; }
; __device__ __forceinline__ void unpack8(const u32x4 w, f32x4& lo, f32x4& hi) { lo = (f32x4){bf_lo(w.x), bf_hi(w.x), bf_lo(w.y), bf_hi(w.y)}; hi = (f32x4){bf_lo(w.z), bf_hi(w.z), bf_lo(w.w), bf_hi(w.w)}; }
; __device__ __forceinline__ void phase_pool(const bf16_t* PROJ, bf16_t* Z, int gw, int NGW, int lane) {
;     ...
;         for (int t = t0; t < t0 + 16; ++t) {
;             f32x4 v0, v1; unpack8(*(const u32x4*)(vb + (size_t)t * DIN), v0, v1); s0 += v0; s1 += v1;
;             if (t > t0 && t - win >= 0) { f32x4 a, c; unpack8(*(const u32x4*)(vb + (size_t)(t - win) * DIN), a, c); s0 -= a; s1 -= c; }
;             const float inv = 1.f / (float)((t + 1) < win ? (t + 1) : win);
;             *(u32x4*)(zb + (size_t)t * DSS) = pack8(s0 * inv - v0, s1 * inv - v1);
	v_lshlrev_b32_e32 v172, 16, v64
	v_and_b32_e32 v173, 0xffff0000, v64
	v_lshlrev_b32_e32 v174, 16, v65
	v_and_b32_e32 v175, 0xffff0000, v65
	v_lshlrev_b32_e32 v176, 16, v66
	v_and_b32_e32 v177, 0xffff0000, v66
	v_lshlrev_b32_e32 v178, 16, v67
	v_and_b32_e32 v179, 0xffff0000, v67
	v_pk_add_f32 v[164:165], v[164:165], v[172:173]
	v_pk_add_f32 v[166:167], v[166:167], v[174:175]
	v_pk_add_f32 v[168:169], v[168:169], v[176:177]
	v_pk_add_f32 v[170:171], v[170:171], v[178:179]
	v_lshlrev_b32_e32 v180, 16, v108
	v_and_b32_e32 v181, 0xffff0000, v108
	v_lshlrev_b32_e32 v182, 16, v109
	v_and_b32_e32 v183, 0xffff0000, v109
	v_lshlrev_b32_e32 v184, 16, v110
	v_and_b32_e32 v185, 0xffff0000, v110
	v_lshlrev_b32_e32 v186, 16, v111
	v_and_b32_e32 v187, 0xffff0000, v111
	v_sub_f32_e32 v164, v164, v180
	v_sub_f32_e32 v165, v165, v181
	v_sub_f32_e32 v166, v166, v182
	v_sub_f32_e32 v167, v167, v183
	v_sub_f32_e32 v168, v168, v184
	v_sub_f32_e32 v169, v169, v185
	v_sub_f32_e32 v170, v170, v186
	v_sub_f32_e32 v171, v171, v187
	s_cmp_eq_u32 s65, 0
	s_cselect_b32 s4, 0x3e124925, s72
	v_fma_f32 v188, v164, s4, -v172
	v_fma_f32 v189, v165, s4, -v173
	v_fma_f32 v190, v166, s4, -v174
	v_fma_f32 v191, v167, s4, -v175
	v_fma_f32 v192, v168, s4, -v176
	v_fma_f32 v193, v169, s4, -v177
	v_fma_f32 v194, v170, s4, -v178
	v_fma_f32 v195, v171, s4, -v179
	v_cvt_pk_bf16_f32 v196, v188, v189
	v_cvt_pk_bf16_f32 v197, v190, v191
	v_cvt_pk_bf16_f32 v198, v192, v193
	v_cvt_pk_bf16_f32 v199, v194, v195
	global_store_dwordx4 v39, v[196:199], s[36:37]
	s_add_u32 s36, s36, 0x1000
	s_addc_u32 s37, s37, 0
	s_waitcnt vmcnt(15)
	v_lshlrev_b32_e32 v172, 16, v68
	v_and_b32_e32 v173, 0xffff0000, v68
	v_lshlrev_b32_e32 v174, 16, v69
	v_and_b32_e32 v175, 0xffff0000, v69
	v_lshlrev_b32_e32 v176, 16, v70
	v_and_b32_e32 v177, 0xffff0000, v70
	v_lshlrev_b32_e32 v178, 16, v71
	v_and_b32_e32 v179, 0xffff0000, v71
	v_pk_add_f32 v[164:165], v[164:165], v[172:173]
	v_pk_add_f32 v[166:167], v[166:167], v[174:175]
	v_pk_add_f32 v[168:169], v[168:169], v[176:177]
	v_pk_add_f32 v[170:171], v[170:171], v[178:179]
	v_lshlrev_b32_e32 v180, 16, v104
	v_and_b32_e32 v181, 0xffff0000, v104
	v_lshlrev_b32_e32 v182, 16, v105
	v_and_b32_e32 v183, 0xffff0000, v105
	v_lshlrev_b32_e32 v184, 16, v106
	v_and_b32_e32 v185, 0xffff0000, v106
	v_lshlrev_b32_e32 v186, 16, v107
	v_and_b32_e32 v187, 0xffff0000, v107
	v_sub_f32_e32 v164, v164, v180
	v_sub_f32_e32 v165, v165, v181
	v_sub_f32_e32 v166, v166, v182
	v_sub_f32_e32 v167, v167, v183
	v_sub_f32_e32 v168, v168, v184
	v_sub_f32_e32 v169, v169, v185
	v_sub_f32_e32 v170, v170, v186
	v_sub_f32_e32 v171, v171, v187
	v_fma_f32 v188, v164, s72, -v172
	v_fma_f32 v189, v165, s72, -v173
	v_fma_f32 v190, v166, s72, -v174
	v_fma_f32 v191, v167, s72, -v175
	v_fma_f32 v192, v168, s72, -v176
	v_fma_f32 v193, v169, s72, -v177
	v_fma_f32 v194, v170, s72, -v178
	v_fma_f32 v195, v171, s72, -v179
	v_cvt_pk_bf16_f32 v196, v188, v189
	v_cvt_pk_bf16_f32 v197, v190, v191
	v_cvt_pk_bf16_f32 v198, v192, v193
	v_cvt_pk_bf16_f32 v199, v194, v195
	global_store_dwordx4 v39, v[196:199], s[36:37]
	s_add_u32 s36, s36, 0x1000
	s_addc_u32 s37, s37, 0
	s_waitcnt vmcnt(15)
	v_lshlrev_b32_e32 v172, 16, v72
	v_and_b32_e32 v173, 0xffff0000, v72
	v_lshlrev_b32_e32 v174, 16, v73
	v_and_b32_e32 v175, 0xffff0000, v73
	v_lshlrev_b32_e32 v176, 16, v74
	v_and_b32_e32 v177, 0xffff0000, v74
	v_lshlrev_b32_e32 v178, 16, v75
	v_and_b32_e32 v179, 0xffff0000, v75
	v_pk_add_f32 v[164:165], v[164:165], v[172:173]
	v_pk_add_f32 v[166:167], v[166:167], v[174:175]
	v_pk_add_f32 v[168:169], v[168:169], v[176:177]
	v_pk_add_f32 v[170:171], v[170:171], v[178:179]
	v_lshlrev_b32_e32 v180, 16, v40
	v_and_b32_e32 v181, 0xffff0000, v40
	v_lshlrev_b32_e32 v182, 16, v41
	v_and_b32_e32 v183, 0xffff0000, v41
	v_lshlrev_b32_e32 v184, 16, v42
	v_and_b32_e32 v185, 0xffff0000, v42
	v_lshlrev_b32_e32 v186, 16, v43
	v_and_b32_e32 v187, 0xffff0000, v43
	v_sub_f32_e32 v164, v164, v180
	v_sub_f32_e32 v165, v165, v181
	v_sub_f32_e32 v166, v166, v182
	v_sub_f32_e32 v167, v167, v183
	v_sub_f32_e32 v168, v168, v184
	v_sub_f32_e32 v169, v169, v185
	v_sub_f32_e32 v170, v170, v186
	v_sub_f32_e32 v171, v171, v187
	v_fma_f32 v188, v164, s72, -v172
	v_fma_f32 v189, v165, s72, -v173
	v_fma_f32 v190, v166, s72, -v174
	v_fma_f32 v191, v167, s72, -v175
	v_fma_f32 v192, v168, s72, -v176
	v_fma_f32 v193, v169, s72, -v177
	v_fma_f32 v194, v170, s72, -v178
	v_fma_f32 v195, v171, s72, -v179
	v_cvt_pk_bf16_f32 v196, v188, v189
	v_cvt_pk_bf16_f32 v197, v190, v191
	v_cvt_pk_bf16_f32 v198, v192, v193
	v_cvt_pk_bf16_f32 v199, v194, v195
	global_store_dwordx4 v39, v[196:199], s[36:37]
	s_add_u32 s36, s36, 0x1000
	s_addc_u32 s37, s37, 0
	s_waitcnt vmcnt(15)
	v_lshlrev_b32_e32 v172, 16, v76
	v_and_b32_e32 v173, 0xffff0000, v76
	v_lshlrev_b32_e32 v174, 16, v77
	v_and_b32_e32 v175, 0xffff0000, v77
	v_lshlrev_b32_e32 v176, 16, v78
	v_and_b32_e32 v177, 0xffff0000, v78
	v_lshlrev_b32_e32 v178, 16, v79
	v_and_b32_e32 v179, 0xffff0000, v79
	v_pk_add_f32 v[164:165], v[164:165], v[172:173]
	v_pk_add_f32 v[166:167], v[166:167], v[174:175]
	v_pk_add_f32 v[168:169], v[168:169], v[176:177]
	v_pk_add_f32 v[170:171], v[170:171], v[178:179]
	v_lshlrev_b32_e32 v180, 16, v44
	v_and_b32_e32 v181, 0xffff0000, v44
	v_lshlrev_b32_e32 v182, 16, v45
	v_and_b32_e32 v183, 0xffff0000, v45
	v_lshlrev_b32_e32 v184, 16, v46
	v_and_b32_e32 v185, 0xffff0000, v46
	v_lshlrev_b32_e32 v186, 16, v47
	v_and_b32_e32 v187, 0xffff0000, v47
	v_sub_f32_e32 v164, v164, v180
	v_sub_f32_e32 v165, v165, v181
	v_sub_f32_e32 v166, v166, v182
	v_sub_f32_e32 v167, v167, v183
	v_sub_f32_e32 v168, v168, v184
	v_sub_f32_e32 v169, v169, v185
	v_sub_f32_e32 v170, v170, v186
	v_sub_f32_e32 v171, v171, v187
	v_fma_f32 v188, v164, s72, -v172
	v_fma_f32 v189, v165, s72, -v173
	v_fma_f32 v190, v166, s72, -v174
	v_fma_f32 v191, v167, s72, -v175
	v_fma_f32 v192, v168, s72, -v176
	v_fma_f32 v193, v169, s72, -v177
	v_fma_f32 v194, v170, s72, -v178
	v_fma_f32 v195, v171, s72, -v179
	v_cvt_pk_bf16_f32 v196, v188, v189
	v_cvt_pk_bf16_f32 v197, v190, v191
	v_cvt_pk_bf16_f32 v198, v192, v193
	v_cvt_pk_bf16_f32 v199, v194, v195
	global_store_dwordx4 v39, v[196:199], s[36:37]
	s_add_u32 s36, s36, 0x1000
	s_addc_u32 s37, s37, 0
	s_waitcnt vmcnt(15)
; __device__ __forceinline__ u32x4 pack8(const f32x4 v0, const f32x4 v1) { u32x4 w; w.x = cvt_pk_bf16(v0[0], v0[1]); w.y = cvt_pk_bf16(v0[2], v0[3]); w.z = cvt_pk_bf16(v1[0], v1[1]); w.w = cvt_pk_bf16(v1[2], v1[3]); return w; }
; __device__ __forceinline__ void unpack8(const u32x4 w, f32x4& lo, f32x4& hi) { lo = (f32x4){bf_lo(w.x), bf_hi(w.x), bf_lo(w.y), bf_hi(w.y)}; hi = (f32x4){bf_lo(w.z), bf_hi(w.z), bf_lo(w.w), bf_hi(w.w)}; }
; __device__ __forceinline__ void phase_pool(const bf16_t* PROJ, bf16_t* Z, int gw, int NGW, int lane) {
;     ...
;         for (int t = t0; t < t0 + 16; ++t) {
;             f32x4 v0, v1; unpack8(*(const u32x4*)(vb + (size_t)t * DIN), v0, v1); s0 += v0; s1 += v1;
;             if (t > t0 && t - win >= 0) { f32x4 a, c; unpack8(*(const u32x4*)(vb + (size_t)(t - win) * DIN), a, c); s0 -= a; s1 -= c; }
;             const float inv = 1.f / (float)((t + 1) < win ? (t + 1) : win);
;             *(u32x4*)(zb + (size_t)t * DSS) = pack8(s0 * inv - v0, s1 * inv - v1);
	v_lshlrev_b32_e32 v172, 16, v80
	v_and_b32_e32 v173, 0xffff0000, v80
	v_lshlrev_b32_e32 v174, 16, v81
	v_and_b32_e32 v175, 0xffff0000, v81
	v_lshlrev_b32_e32 v176, 16, v82
	v_and_b32_e32 v177, 0xffff0000, v82
	v_lshlrev_b32_e32 v178, 16, v83
	v_and_b32_e32 v179, 0xffff0000, v83
	v_pk_add_f32 v[164:165], v[164:165], v[172:173]
	v_pk_add_f32 v[166:167], v[166:167], v[174:175]
	v_pk_add_f32 v[168:169], v[168:169], v[176:177]
	v_pk_add_f32 v[170:171], v[170:171], v[178:179]
	v_lshlrev_b32_e32 v180, 16, v48
	v_and_b32_e32 v181, 0xffff0000, v48
	v_lshlrev_b32_e32 v182, 16, v49
	v_and_b32_e32 v183, 0xffff0000, v49
	v_lshlrev_b32_e32 v184, 16, v50
	v_and_b32_e32 v185, 0xffff0000, v50
	v_lshlrev_b32_e32 v186, 16, v51
	v_and_b32_e32 v187, 0xffff0000, v51
	v_sub_f32_e32 v164, v164, v180
	v_sub_f32_e32 v165, v165, v181
	v_sub_f32_e32 v166, v166, v182
	v_sub_f32_e32 v167, v167, v183
	v_sub_f32_e32 v168, v168, v184
	v_sub_f32_e32 v169, v169, v185
	v_sub_f32_e32 v170, v170, v186
	v_sub_f32_e32 v171, v171, v187
	v_fma_f32 v188, v164, s72, -v172
	v_fma_f32 v189, v165, s72, -v173
	v_fma_f32 v190, v166, s72, -v174
	v_fma_f32 v191, v167, s72, -v175
	v_fma_f32 v192, v168, s72, -v176
	v_fma_f32 v193, v169, s72, -v177
	v_fma_f32 v194, v170, s72, -v178
	v_fma_f32 v195, v171, s72, -v179
	v_cvt_pk_bf16_f32 v196, v188, v189
	v_cvt_pk_bf16_f32 v197, v190, v191
	v_cvt_pk_bf16_f32 v198, v192, v193
	v_cvt_pk_bf16_f32 v199, v194, v195
	global_store_dwordx4 v39, v[196:199], s[36:37]
	s_add_u32 s36, s36, 0x1000
	s_addc_u32 s37, s37, 0
	s_waitcnt vmcnt(15)
	v_lshlrev_b32_e32 v172, 16, v84
	v_and_b32_e32 v173, 0xffff0000, v84
	v_lshlrev_b32_e32 v174, 16, v85
	v_and_b32_e32 v175, 0xffff0000, v85
	v_lshlrev_b32_e32 v176, 16, v86
	v_and_b32_e32 v177, 0xffff0000, v86
	v_lshlrev_b32_e32 v178, 16, v87
	v_and_b32_e32 v179, 0xffff0000, v87
	v_pk_add_f32 v[164:165], v[164:165], v[172:173]
	v_pk_add_f32 v[166:167], v[166:167], v[174:175]
	v_pk_add_f32 v[168:169], v[168:169], v[176:177]
	v_pk_add_f32 v[170:171], v[170:171], v[178:179]
	v_lshlrev_b32_e32 v180, 16, v52
	v_and_b32_e32 v181, 0xffff0000, v52
	v_lshlrev_b32_e32 v182, 16, v53
	v_and_b32_e32 v183, 0xffff0000, v53
	v_lshlrev_b32_e32 v184, 16, v54
	v_and_b32_e32 v185, 0xffff0000, v54
	v_lshlrev_b32_e32 v186, 16, v55
	v_and_b32_e32 v187, 0xffff0000, v55
	v_sub_f32_e32 v164, v164, v180
	v_sub_f32_e32 v165, v165, v181
	v_sub_f32_e32 v166, v166, v182
	v_sub_f32_e32 v167, v167, v183
	v_sub_f32_e32 v168, v168, v184
	v_sub_f32_e32 v169, v169, v185
	v_sub_f32_e32 v170, v170, v186
	v_sub_f32_e32 v171, v171, v187
	v_fma_f32 v188, v164, s72, -v172
	v_fma_f32 v189, v165, s72, -v173
	v_fma_f32 v190, v166, s72, -v174
	v_fma_f32 v191, v167, s72, -v175
	v_fma_f32 v192, v168, s72, -v176
	v_fma_f32 v193, v169, s72, -v177
	v_fma_f32 v194, v170, s72, -v178
	v_fma_f32 v195, v171, s72, -v179
	v_cvt_pk_bf16_f32 v196, v188, v189
	v_cvt_pk_bf16_f32 v197, v190, v191
	v_cvt_pk_bf16_f32 v198, v192, v193
	v_cvt_pk_bf16_f32 v199, v194, v195
	global_store_dwordx4 v39, v[196:199], s[36:37]
	s_add_u32 s36, s36, 0x1000
	s_addc_u32 s37, s37, 0
	s_waitcnt vmcnt(15)
	v_lshlrev_b32_e32 v172, 16, v88
	v_and_b32_e32 v173, 0xffff0000, v88
	v_lshlrev_b32_e32 v174, 16, v89
	v_and_b32_e32 v175, 0xffff0000, v89
	v_lshlrev_b32_e32 v176, 16, v90
	v_and_b32_e32 v177, 0xffff0000, v90
	v_lshlrev_b32_e32 v178, 16, v91
	v_and_b32_e32 v179, 0xffff0000, v91
	v_pk_add_f32 v[164:165], v[164:165], v[172:173]
	v_pk_add_f32 v[166:167], v[166:167], v[174:175]
	v_pk_add_f32 v[168:169], v[168:169], v[176:177]
	v_pk_add_f32 v[170:171], v[170:171], v[178:179]
	v_lshlrev_b32_e32 v180, 16, v56
	v_and_b32_e32 v181, 0xffff0000, v56
	v_lshlrev_b32_e32 v182, 16, v57
	v_and_b32_e32 v183, 0xffff0000, v57
	v_lshlrev_b32_e32 v184, 16, v58
	v_and_b32_e32 v185, 0xffff0000, v58
	v_lshlrev_b32_e32 v186, 16, v59
	v_and_b32_e32 v187, 0xffff0000, v59
	v_sub_f32_e32 v164, v164, v180
	v_sub_f32_e32 v165, v165, v181
	v_sub_f32_e32 v166, v166, v182
	v_sub_f32_e32 v167, v167, v183
	v_sub_f32_e32 v168, v168, v184
	v_sub_f32_e32 v169, v169, v185
	v_sub_f32_e32 v170, v170, v186
	v_sub_f32_e32 v171, v171, v187
	v_fma_f32 v188, v164, s72, -v172
	v_fma_f32 v189, v165, s72, -v173
	v_fma_f32 v190, v166, s72, -v174
	v_fma_f32 v191, v167, s72, -v175
	v_fma_f32 v192, v168, s72, -v176
	v_fma_f32 v193, v169, s72, -v177
	v_fma_f32 v194, v170, s72, -v178
	v_fma_f32 v195, v171, s72, -v179
	v_cvt_pk_bf16_f32 v196, v188, v189
	v_cvt_pk_bf16_f32 v197, v190, v191
	v_cvt_pk_bf16_f32 v198, v192, v193
	v_cvt_pk_bf16_f32 v199, v194, v195
	global_store_dwordx4 v39, v[196:199], s[36:37]
	s_add_u32 s36, s36, 0x1000
	s_addc_u32 s37, s37, 0
	s_waitcnt vmcnt(15)
	v_lshlrev_b32_e32 v172, 16, v92
	v_and_b32_e32 v173, 0xffff0000, v92
	v_lshlrev_b32_e32 v174, 16, v93
	v_and_b32_e32 v175, 0xffff0000, v93
	v_lshlrev_b32_e32 v176, 16, v94
	v_and_b32_e32 v177, 0xffff0000, v94
	v_lshlrev_b32_e32 v178, 16, v95
	v_and_b32_e32 v179, 0xffff0000, v95
	v_pk_add_f32 v[164:165], v[164:165], v[172:173]
	v_pk_add_f32 v[166:167], v[166:167], v[174:175]
	v_pk_add_f32 v[168:169], v[168:169], v[176:177]
	v_pk_add_f32 v[170:171], v[170:171], v[178:179]
	v_lshlrev_b32_e32 v180, 16, v60
	v_and_b32_e32 v181, 0xffff0000, v60
	v_lshlrev_b32_e32 v182, 16, v61
	v_and_b32_e32 v183, 0xffff0000, v61
	v_lshlrev_b32_e32 v184, 16, v62
	v_and_b32_e32 v185, 0xffff0000, v62
	v_lshlrev_b32_e32 v186, 16, v63
	v_and_b32_e32 v187, 0xffff0000, v63
	v_sub_f32_e32 v164, v164, v180
	v_sub_f32_e32 v165, v165, v181
	v_sub_f32_e32 v166, v166, v182
	v_sub_f32_e32 v167, v167, v183
	v_sub_f32_e32 v168, v168, v184
	v_sub_f32_e32 v169, v169, v185
	v_sub_f32_e32 v170, v170, v186
	v_sub_f32_e32 v171, v171, v187
	v_fma_f32 v188, v164, s72, -v172
	v_fma_f32 v189, v165, s72, -v173
	v_fma_f32 v190, v166, s72, -v174
	v_fma_f32 v191, v167, s72, -v175
	v_fma_f32 v192, v168, s72, -v176
	v_fma_f32 v193, v169, s72, -v177
	v_fma_f32 v194, v170, s72, -v178
	v_fma_f32 v195, v171, s72, -v179
	v_cvt_pk_bf16_f32 v196, v188, v189
	v_cvt_pk_bf16_f32 v197, v190, v191
	v_cvt_pk_bf16_f32 v198, v192, v193
	v_cvt_pk_bf16_f32 v199, v194, v195
	global_store_dwordx4 v39, v[196:199], s[36:37]
	s_add_u32 s36, s36, 0x1000
	s_addc_u32 s37, s37, 0
	s_waitcnt vmcnt(15)
; __device__ __forceinline__ u32x4 pack8(const f32x4 v0, const f32x4 v1) { u32x4 w; w.x = cvt_pk_bf16(v0[0], v0[1]); w.y = cvt_pk_bf16(v0[2], v0[3]); w.z = cvt_pk_bf16(v1[0], v1[1]); w.w = cvt_pk_bf16(v1[2], v1[3]); return w; }
; __device__ __forceinline__ void unpack8(const u32x4 w, f32x4& lo, f32x4& hi) { lo = (f32x4){bf_lo(w.x), bf_hi(w.x), bf_lo(w.y), bf_hi(w.y)}; hi = (f32x4){bf_lo(w.z), bf_hi(w.z), bf_lo(w.w), bf_hi(w.w)}; }
; __device__ __forceinline__ void phase_pool(const bf16_t* PROJ, bf16_t* Z, int gw, int NGW, int lane) {
;     ...
;         const int t0 = tseg * 16;
;         for (int tau = (t0 - win + 1 > 0 ? t0 - win + 1 : 0); tau < t0; ++tau) { f32x4 a, c; unpack8(*(const u32x4*)(vb + (size_t)tau * DIN), a, c); s0 += a; s1 += c; }
;         for (int t = t0; t < t0 + 16; ++t) {
;             f32x4 v0, v1; unpack8(*(const u32x4*)(vb + (size_t)t * DIN), v0, v1); s0 += v0; s1 += v1;
;             if (t > t0 && t - win >= 0) { f32x4 a, c; unpack8(*(const u32x4*)(vb + (size_t)(t - win) * DIN), a, c); s0 -= a; s1 -= c; }
;             const float inv = 1.f / (float)((t + 1) < win ? (t + 1) : win);
;             *(u32x4*)(zb + (size_t)t * DSS) = pack8(s0 * inv - v0, s1 * inv - v1);
	v_lshlrev_b32_e32 v172, 16, v96
	v_and_b32_e32 v173, 0xffff0000, v96
	v_lshlrev_b32_e32 v174, 16, v97
	v_and_b32_e32 v175, 0xffff0000, v97
	v_lshlrev_b32_e32 v176, 16, v98
	v_and_b32_e32 v177, 0xffff0000, v98
	v_lshlrev_b32_e32 v178, 16, v99
	v_and_b32_e32 v179, 0xffff0000, v99
	v_pk_add_f32 v[164:165], v[164:165], v[172:173]
	v_pk_add_f32 v[166:167], v[166:167], v[174:175]
	v_pk_add_f32 v[168:169], v[168:169], v[176:177]
	v_pk_add_f32 v[170:171], v[170:171], v[178:179]
	v_lshlrev_b32_e32 v180, 16, v64
	v_and_b32_e32 v181, 0xffff0000, v64
	v_lshlrev_b32_e32 v182, 16, v65
	v_and_b32_e32 v183, 0xffff0000, v65
	v_lshlrev_b32_e32 v184, 16, v66
	v_and_b32_e32 v185, 0xffff0000, v66
	v_lshlrev_b32_e32 v186, 16, v67
	v_and_b32_e32 v187, 0xffff0000, v67
	v_sub_f32_e32 v164, v164, v180
	v_sub_f32_e32 v165, v165, v181
	v_sub_f32_e32 v166, v166, v182
	v_sub_f32_e32 v167, v167, v183
	v_sub_f32_e32 v168, v168, v184
	v_sub_f32_e32 v169, v169, v185
	v_sub_f32_e32 v170, v170, v186
	v_sub_f32_e32 v171, v171, v187
	v_fma_f32 v188, v164, s72, -v172
	v_fma_f32 v189, v165, s72, -v173
	v_fma_f32 v190, v166, s72, -v174
	v_fma_f32 v191, v167, s72, -v175
	v_fma_f32 v192, v168, s72, -v176
	v_fma_f32 v193, v169, s72, -v177
	v_fma_f32 v194, v170, s72, -v178
	v_fma_f32 v195, v171, s72, -v179
	v_cvt_pk_bf16_f32 v196, v188, v189
	v_cvt_pk_bf16_f32 v197, v190, v191
	v_cvt_pk_bf16_f32 v198, v192, v193
	v_cvt_pk_bf16_f32 v199, v194, v195
	global_store_dwordx4 v39, v[196:199], s[36:37]
	s_add_u32 s36, s36, 0x1000
	s_addc_u32 s37, s37, 0
	s_waitcnt vmcnt(15)
	v_lshlrev_b32_e32 v172, 16, v100
	v_and_b32_e32 v173, 0xffff0000, v100
	v_lshlrev_b32_e32 v174, 16, v101
	v_and_b32_e32 v175, 0xffff0000, v101
	v_lshlrev_b32_e32 v176, 16, v102
	v_and_b32_e32 v177, 0xffff0000, v102
	v_lshlrev_b32_e32 v178, 16, v103
	v_and_b32_e32 v179, 0xffff0000, v103
	v_pk_add_f32 v[164:165], v[164:165], v[172:173]
	v_pk_add_f32 v[166:167], v[166:167], v[174:175]
	v_pk_add_f32 v[168:169], v[168:169], v[176:177]
	v_pk_add_f32 v[170:171], v[170:171], v[178:179]
	v_lshlrev_b32_e32 v180, 16, v68
	v_and_b32_e32 v181, 0xffff0000, v68
	v_lshlrev_b32_e32 v182, 16, v69
	v_and_b32_e32 v183, 0xffff0000, v69
	v_lshlrev_b32_e32 v184, 16, v70
	v_and_b32_e32 v185, 0xffff0000, v70
	v_lshlrev_b32_e32 v186, 16, v71
	v_and_b32_e32 v187, 0xffff0000, v71
	v_sub_f32_e32 v164, v164, v180
	v_sub_f32_e32 v165, v165, v181
	v_sub_f32_e32 v166, v166, v182
	v_sub_f32_e32 v167, v167, v183
	v_sub_f32_e32 v168, v168, v184
	v_sub_f32_e32 v169, v169, v185
	v_sub_f32_e32 v170, v170, v186
	v_sub_f32_e32 v171, v171, v187
	v_fma_f32 v188, v164, s72, -v172
	v_fma_f32 v189, v165, s72, -v173
	v_fma_f32 v190, v166, s72, -v174
	v_fma_f32 v191, v167, s72, -v175
	v_fma_f32 v192, v168, s72, -v176
	v_fma_f32 v193, v169, s72, -v177
	v_fma_f32 v194, v170, s72, -v178
	v_fma_f32 v195, v171, s72, -v179
	v_cvt_pk_bf16_f32 v196, v188, v189
	v_cvt_pk_bf16_f32 v197, v190, v191
	v_cvt_pk_bf16_f32 v198, v192, v193
	v_cvt_pk_bf16_f32 v199, v194, v195
	global_store_dwordx4 v39, v[196:199], s[36:37]
	s_branch .LBB0_300
.Lpool_w4:
	s_mov_b32 s72, 0x3e800000
	s_cmp_eq_u32 s65, 0
	s_cbranch_scc1 .Lpool_w4_zero
	s_sub_u32 s38, s70, 0x12000
	s_subb_u32 s39, s71, 0
	global_load_dwordx4 v[112:115], v39, s[38:39]
	s_add_u32 s38, s38, 0x6000
	s_addc_u32 s39, s39, 0
	global_load_dwordx4 v[108:111], v39, s[38:39]
	s_add_u32 s38, s38, 0x6000
	s_addc_u32 s39, s39, 0
	global_load_dwordx4 v[104:107], v39, s[38:39]
	s_branch .Lpool_w4_a
.Lpool_w4_zero:
	v_mov_b32_e32 v104, 0
	v_mov_b32_e32 v105, 0
	v_mov_b32_e32 v106, 0
	v_mov_b32_e32 v107, 0
	v_mov_b32_e32 v108, 0
	v_mov_b32_e32 v109, 0
	v_mov_b32_e32 v110, 0
	v_mov_b32_e32 v111, 0
	v_mov_b32_e32 v112, 0
	v_mov_b32_e32 v113, 0
	v_mov_b32_e32 v114, 0
	v_mov_b32_e32 v115, 0
.Lpool_w4_a:
	global_load_dwordx4 v[40:43], v39, s[70:71]
	s_add_u32 s70, s70, 0x6000
	s_addc_u32 s71, s71, 0
	global_load_dwordx4 v[44:47], v39, s[70:71]
	s_add_u32 s70, s70, 0x6000
	s_addc_u32 s71, s71, 0
	global_load_dwordx4 v[48:51], v39, s[70:71]
	s_add_u32 s70, s70, 0x6000
	s_addc_u32 s71, s71, 0
	global_load_dwordx4 v[52:55], v39, s[70:71]
	s_add_u32 s70, s70, 0x6000
	s_addc_u32 s71, s71, 0
	global_load_dwordx4 v[56:59], v39, s[70:71]
	s_add_u32 s70, s70, 0x6000
	s_addc_u32 s71, s71, 0
	global_load_dwordx4 v[60:63], v39, s[70:71]
	s_add_u32 s70, s70, 0x6000
	s_addc_u32 s71, s71, 0
	global_load_dwordx4 v[64:67], v39, s[70:71]
	s_add_u32 s70, s70, 0x6000
	s_addc_u32 s71, s71, 0
	global_load_dwordx4 v[68:71], v39, s[70:71]
	s_add_u32 s70, s70, 0x6000
	s_addc_u32 s71, s71, 0
	global_load_dwordx4 v[72:75], v39, s[70:71]
	s_add_u32 s70, s70, 0x6000
	s_addc_u32 s71, s71, 0
	global_load_dwordx4 v[76:79], v39, s[70:71]
	s_add_u32 s70, s70, 0x6000
	s_addc_u32 s71, s71, 0
	global_load_dwordx4 v[80:83], v39, s[70:71]
	s_add_u32 s70, s70, 0x6000
	s_addc_u32 s71, s71, 0
	global_load_dwordx4 v[84:87], v39, s[70:71]
	s_add_u32 s70, s70, 0x6000
	s_addc_u32 s71, s71, 0
	global_load_dwordx4 v[88:91], v39, s[70:71]
	s_add_u32 s70, s70, 0x6000
	s_addc_u32 s71, s71, 0
	global_load_dwordx4 v[92:95], v39, s[70:71]
	s_add_u32 s70, s70, 0x6000
	s_addc_u32 s71, s71, 0
	global_load_dwordx4 v[96:99], v39, s[70:71]
	s_add_u32 s70, s70, 0x6000
	s_addc_u32 s71, s71, 0
	global_load_dwordx4 v[100:103], v39, s[70:71]
	s_waitcnt vmcnt(15)
; __device__ __forceinline__ u32x4 pack8(const f32x4 v0, const f32x4 v1) { u32x4 w; w.x = cvt_pk_bf16(v0[0], v0[1]); w.y = cvt_pk_bf16(v0[2], v0[3]); w.z = cvt_pk_bf16(v1[0], v1[1]); w.w = cvt_pk_bf16(v1[2], v1[3]); return w; }
; __device__ __forceinline__ void unpack8(const u32x4 w, f32x4& lo, f32x4& hi) { lo = (f32x4){bf_lo(w.x), bf_hi(w.x), bf_lo(w.y), bf_hi(w.y)}; hi = (f32x4){bf_lo(w.z), bf_hi(w.z), bf_lo(w.w), bf_hi(w.w)}; }
; __device__ __forceinline__ void phase_pool(const bf16_t* PROJ, bf16_t* Z, int gw, int NGW, int lane) {
;     ...
;         const int t0 = tseg * 16;
;         for (int tau = (t0 - win + 1 > 0 ? t0 - win + 1 : 0); tau < t0; ++tau) { f32x4 a, c; unpack8(*(const u32x4*)(vb + (size_t)tau * DIN), a, c); s0 += a; s1 += c; }
;         for (int t = t0; t < t0 + 16; ++t) {
;             f32x4 v0, v1; unpack8(*(const u32x4*)(vb + (size_t)t * DIN), v0, v1); s0 += v0; s1 += v1;
;             if (t > t0 && t - win >= 0) { f32x4 a, c; unpack8(*(const u32x4*)(vb + (size_t)(t - win) * DIN), a, c); s0 -= a; s1 -= c; }
;             const float inv = 1.f / (float)((t + 1) < win ? (t + 1) : win);
;             *(u32x4*)(zb + (size_t)t * DSS) = pack8(s0 * inv - v0, s1 * inv - v1);
	v_lshlrev_b32_e32 v164, 16, v112
	v_and_b32_e32 v165, 0xffff0000, v112
	v_lshlrev_b32_e32 v166, 16, v113
	v_and_b32_e32 v167, 0xffff0000, v113
	v_lshlrev_b32_e32 v168, 16, v114
	v_and_b32_e32 v169, 0xffff0000, v114
	v_lshlrev_b32_e32 v170, 16, v115
	v_and_b32_e32 v171, 0xffff0000, v115
	v_lshlrev_b32_e32 v172, 16, v108
	v_and_b32_e32 v173, 0xffff0000, v108
	v_lshlrev_b32_e32 v174, 16, v109
	v_and_b32_e32 v175, 0xffff0000, v109
	v_lshlrev_b32_e32 v176, 16, v110
	v_and_b32_e32 v177, 0xffff0000, v110
	v_lshlrev_b32_e32 v178, 16, v111
	v_and_b32_e32 v179, 0xffff0000, v111
	v_pk_add_f32 v[164:165], v[164:165], v[172:173]
	v_pk_add_f32 v[166:167], v[166:167], v[174:175]
	v_pk_add_f32 v[168:169], v[168:169], v[176:177]
	v_pk_add_f32 v[170:171], v[170:171], v[178:179]
	v_lshlrev_b32_e32 v172, 16, v104
	v_and_b32_e32 v173, 0xffff0000, v104
	v_lshlrev_b32_e32 v174, 16, v105
	v_and_b32_e32 v175, 0xffff0000, v105
	v_lshlrev_b32_e32 v176, 16, v106
	v_and_b32_e32 v177, 0xffff0000, v106
	v_lshlrev_b32_e32 v178, 16, v107
	v_and_b32_e32 v179, 0xffff0000, v107
	v_pk_add_f32 v[164:165], v[164:165], v[172:173]
	v_pk_add_f32 v[166:167], v[166:167], v[174:175]
	v_pk_add_f32 v[168:169], v[168:169], v[176:177]
	v_pk_add_f32 v[170:171], v[170:171], v[178:179]
	v_lshlrev_b32_e32 v172, 16, v40
	v_and_b32_e32 v173, 0xffff0000, v40
	v_lshlrev_b32_e32 v174, 16, v41
	v_and_b32_e32 v175, 0xffff0000, v41
	v_lshlrev_b32_e32 v176, 16, v42
	v_and_b32_e32 v177, 0xffff0000, v42
	v_lshlrev_b32_e32 v178, 16, v43
	v_and_b32_e32 v179, 0xffff0000, v43
	v_pk_add_f32 v[164:165], v[164:165], v[172:173]
	v_pk_add_f32 v[166:167], v[166:167], v[174:175]
	v_pk_add_f32 v[168:169], v[168:169], v[176:177]
	v_pk_add_f32 v[170:171], v[170:171], v[178:179]
	s_cmp_eq_u32 s65, 0
	s_cselect_b32 s4, 0x3f800000, s72
	v_fma_f32 v188, v164, s4, -v172
	v_fma_f32 v189, v165, s4, -v173
	v_fma_f32 v190, v166, s4, -v174
	v_fma_f32 v191, v167, s4, -v175
	v_fma_f32 v192, v168, s4, -v176
	v_fma_f32 v193, v169, s4, -v177
	v_fma_f32 v194, v170, s4, -v178
	v_fma_f32 v195, v171, s4, -v179
	v_cvt_pk_bf16_f32 v196, v188, v189
	v_cvt_pk_bf16_f32 v197, v190, v191
	v_cvt_pk_bf16_f32 v198, v192, v193
	v_cvt_pk_bf16_f32 v199, v194, v195
	global_store_dwordx4 v39, v[196:199], s[36:37]
	s_add_u32 s36, s36, 0x1000
	s_addc_u32 s37, s37, 0
	s_waitcnt vmcnt(15)
	v_lshlrev_b32_e32 v172, 16, v44
	v_and_b32_e32 v173, 0xffff0000, v44
	v_lshlrev_b32_e32 v174, 16, v45
	v_and_b32_e32 v175, 0xffff0000, v45
	v_lshlrev_b32_e32 v176, 16, v46
	v_and_b32_e32 v177, 0xffff0000, v46
	v_lshlrev_b32_e32 v178, 16, v47
	v_and_b32_e32 v179, 0xffff0000, v47
	v_pk_add_f32 v[164:165], v[164:165], v[172:173]
	v_pk_add_f32 v[166:167], v[166:167], v[174:175]
	v_pk_add_f32 v[168:169], v[168:169], v[176:177]
	v_pk_add_f32 v[170:171], v[170:171], v[178:179]
	v_lshlrev_b32_e32 v180, 16, v112
	v_and_b32_e32 v181, 0xffff0000, v112
	v_lshlrev_b32_e32 v182, 16, v113
	v_and_b32_e32 v183, 0xffff0000, v113
	v_lshlrev_b32_e32 v184, 16, v114
	v_and_b32_e32 v185, 0xffff0000, v114
	v_lshlrev_b32_e32 v186, 16, v115
	v_and_b32_e32 v187, 0xffff0000, v115
	v_sub_f32_e32 v164, v164, v180
	v_sub_f32_e32 v165, v165, v181
	v_sub_f32_e32 v166, v166, v182
	v_sub_f32_e32 v167, v167, v183
	v_sub_f32_e32 v168, v168, v184
	v_sub_f32_e32 v169, v169, v185
	v_sub_f32_e32 v170, v170, v186
	v_sub_f32_e32 v171, v171, v187
	s_cmp_eq_u32 s65, 0
	s_cselect_b32 s4, 0x3f000000, s72
	v_fma_f32 v188, v164, s4, -v172
	v_fma_f32 v189, v165, s4, -v173
	v_fma_f32 v190, v166, s4, -v174
	v_fma_f32 v191, v167, s4, -v175
	v_fma_f32 v192, v168, s4, -v176
	v_fma_f32 v193, v169, s4, -v177
	v_fma_f32 v194, v170, s4, -v178
	v_fma_f32 v195, v171, s4, -v179
	v_cvt_pk_bf16_f32 v196, v188, v189
	v_cvt_pk_bf16_f32 v197, v190, v191
	v_cvt_pk_bf16_f32 v198, v192, v193
	v_cvt_pk_bf16_f32 v199, v194, v195
	global_store_dwordx4 v39, v[196:199], s[36:37]
	s_add_u32 s36, s36, 0x1000
	s_addc_u32 s37, s37, 0
	s_waitcnt vmcnt(15)
	v_lshlrev_b32_e32 v172, 16, v48
	v_and_b32_e32 v173, 0xffff0000, v48
	v_lshlrev_b32_e32 v174, 16, v49
	v_and_b32_e32 v175, 0xffff0000, v49
	v_lshlrev_b32_e32 v176, 16, v50
	v_and_b32_e32 v177, 0xffff0000, v50
	v_lshlrev_b32_e32 v178, 16, v51
	v_and_b32_e32 v179, 0xffff0000, v51
	v_pk_add_f32 v[164:165], v[164:165], v[172:173]
	v_pk_add_f32 v[166:167], v[166:167], v[174:175]
	v_pk_add_f32 v[168:169], v[168:169], v[176:177]
	v_pk_add_f32 v[170:171], v[170:171], v[178:179]
	v_lshlrev_b32_e32 v180, 16, v108
	v_and_b32_e32 v181, 0xffff0000, v108
	v_lshlrev_b32_e32 v182, 16, v109
	v_and_b32_e32 v183, 0xffff0000, v109
	v_lshlrev_b32_e32 v184, 16, v110
	v_and_b32_e32 v185, 0xffff0000, v110
	v_lshlrev_b32_e32 v186, 16, v111
	v_and_b32_e32 v187, 0xffff0000, v111
	v_sub_f32_e32 v164, v164, v180
	v_sub_f32_e32 v165, v165, v181
	v_sub_f32_e32 v166, v166, v182
	v_sub_f32_e32 v167, v167, v183
	v_sub_f32_e32 v168, v168, v184
	v_sub_f32_e32 v169, v169, v185
	v_sub_f32_e32 v170, v170, v186
	v_sub_f32_e32 v171, v171, v187
	s_cmp_eq_u32 s65, 0
	s_cselect_b32 s4, 0x3eaaaaab, s72
	v_fma_f32 v188, v164, s4, -v172
	v_fma_f32 v189, v165, s4, -v173
	v_fma_f32 v190, v166, s4, -v174
	v_fma_f32 v191, v167, s4, -v175
	v_fma_f32 v192, v168, s4, -v176
	v_fma_f32 v193, v169, s4, -v177
	v_fma_f32 v194, v170, s4, -v178
	v_fma_f32 v195, v171, s4, -v179
	v_cvt_pk_bf16_f32 v196, v188, v189
	v_cvt_pk_bf16_f32 v197, v190, v191
	v_cvt_pk_bf16_f32 v198, v192, v193
	v_cvt_pk_bf16_f32 v199, v194, v195
	global_store_dwordx4 v39, v[196:199], s[36:37]
	s_add_u32 s36, s36, 0x1000
	s_addc_u32 s37, s37, 0
	s_waitcnt vmcnt(15)
; __device__ __forceinline__ u32x4 pack8(const f32x4 v0, const f32x4 v1) { u32x4 w; w.x = cvt_pk_bf16(v0[0], v0[1]); w.y = cvt_pk_bf16(v0[2], v0[3]); w.z = cvt_pk_bf16(v1[0], v1[1]); w.w = cvt_pk_bf16(v1[2], v1[3]); return w; }
; __device__ __forceinline__ void unpack8(const u32x4 w, f32x4& lo, f32x4& hi) { lo = (f32x4){bf_lo(w.x), bf_hi(w.x), bf_lo(w.y), bf_hi(w.y)}; hi = (f32x4){bf_lo(w.z), bf_hi(w.z), bf_lo(w.w), bf_hi(w.w)}; }
; __device__ __forceinline__ void phase_pool(const bf16_t* PROJ, bf16_t* Z, int gw, int NGW, int lane) {
;     ...
;         for (int t = t0; t < t0 + 16; ++t) {
;             f32x4 v0, v1; unpack8(*(const u32x4*)(vb + (size_t)t * DIN), v0, v1); s0 += v0; s1 += v1;
;             if (t > t0 && t - win >= 0) { f32x4 a, c; unpack8(*(const u32x4*)(vb + (size_t)(t - win) * DIN), a, c); s0 -= a; s1 -= c; }
;             const float inv = 1.f / (float)((t + 1) < win ? (t + 1) : win);
;             *(u32x4*)(zb + (size_t)t * DSS) = pack8(s0 * inv - v0, s1 * inv - v1);
	v_lshlrev_b32_e32 v172, 16, v52
	v_and_b32_e32 v173, 0xffff0000, v52
	v_lshlrev_b32_e32 v174, 16, v53
	v_and_b32_e32 v175, 0xffff0000, v53
	v_lshlrev_b32_e32 v176, 16, v54
	v_and_b32_e32 v177, 0xffff0000, v54
	v_lshlrev_b32_e32 v178, 16, v55
	v_and_b32_e32 v179, 0xffff0000, v55
	v_pk_add_f32 v[164:165], v[164:165], v[172:173]
	v_pk_add_f32 v[166:167], v[166:167], v[174:175]
	v_pk_add_f32 v[168:169], v[168:169], v[176:177]
	v_pk_add_f32 v[170:171], v[170:171], v[178:179]
	v_lshlrev_b32_e32 v180, 16, v104
	v_and_b32_e32 v181, 0xffff0000, v104
	v_lshlrev_b32_e32 v182, 16, v105
	v_and_b32_e32 v183, 0xffff0000, v105
	v_lshlrev_b32_e32 v184, 16, v106
	v_and_b32_e32 v185, 0xffff0000, v106
	v_lshlrev_b32_e32 v186, 16, v107
	v_and_b32_e32 v187, 0xffff0000, v107
	v_sub_f32_e32 v164, v164, v180
	v_sub_f32_e32 v165, v165, v181
	v_sub_f32_e32 v166, v166, v182
	v_sub_f32_e32 v167, v167, v183
	v_sub_f32_e32 v168, v168, v184
	v_sub_f32_e32 v169, v169, v185
	v_sub_f32_e32 v170, v170, v186
	v_sub_f32_e32 v171, v171, v187
	v_fma_f32 v188, v164, s72, -v172
	v_fma_f32 v189, v165, s72, -v173
	v_fma_f32 v190, v166, s72, -v174
	v_fma_f32 v191, v167, s72, -v175
	v_fma_f32 v192, v168, s72, -v176
	v_fma_f32 v193, v169, s72, -v177
	v_fma_f32 v194, v170, s72, -v178
	v_fma_f32 v195, v171, s72, -v179
	v_cvt_pk_bf16_f32 v196, v188, v189
	v_cvt_pk_bf16_f32 v197, v190, v191
	v_cvt_pk_bf16_f32 v198, v192, v193
	v_cvt_pk_bf16_f32 v199, v194, v195
	global_store_dwordx4 v39, v[196:199], s[36:37]
	s_add_u32 s36, s36, 0x1000
	s_addc_u32 s37, s37, 0
	s_waitcnt vmcnt(15)
	v_lshlrev_b32_e32 v172, 16, v56
	v_and_b32_e32 v173, 0xffff0000, v56
	v_lshlrev_b32_e32 v174, 16, v57
	v_and_b32_e32 v175, 0xffff0000, v57
	v_lshlrev_b32_e32 v176, 16, v58
	v_and_b32_e32 v177, 0xffff0000, v58
	v_lshlrev_b32_e32 v178, 16, v59
	v_and_b32_e32 v179, 0xffff0000, v59
	v_pk_add_f32 v[164:165], v[164:165], v[172:173]
	v_pk_add_f32 v[166:167], v[166:167], v[174:175]
	v_pk_add_f32 v[168:169], v[168:169], v[176:177]
	v_pk_add_f32 v[170:171], v[170:171], v[178:179]
	v_lshlrev_b32_e32 v180, 16, v40
	v_and_b32_e32 v181, 0xffff0000, v40
	v_lshlrev_b32_e32 v182, 16, v41
	v_and_b32_e32 v183, 0xffff0000, v41
	v_lshlrev_b32_e32 v184, 16, v42
	v_and_b32_e32 v185, 0xffff0000, v42
	v_lshlrev_b32_e32 v186, 16, v43
	v_and_b32_e32 v187, 0xffff0000, v43
	v_sub_f32_e32 v164, v164, v180
	v_sub_f32_e32 v165, v165, v181
	v_sub_f32_e32 v166, v166, v182
	v_sub_f32_e32 v167, v167, v183
	v_sub_f32_e32 v168, v168, v184
	v_sub_f32_e32 v169, v169, v185
	v_sub_f32_e32 v170, v170, v186
	v_sub_f32_e32 v171, v171, v187
	v_fma_f32 v188, v164, s72, -v172
	v_fma_f32 v189, v165, s72, -v173
	v_fma_f32 v190, v166, s72, -v174
	v_fma_f32 v191, v167, s72, -v175
	v_fma_f32 v192, v168, s72, -v176
	v_fma_f32 v193, v169, s72, -v177
	v_fma_f32 v194, v170, s72, -v178
	v_fma_f32 v195, v171, s72, -v179
	v_cvt_pk_bf16_f32 v196, v188, v189
	v_cvt_pk_bf16_f32 v197, v190, v191
	v_cvt_pk_bf16_f32 v198, v192, v193
	v_cvt_pk_bf16_f32 v199, v194, v195
	global_store_dwordx4 v39, v[196:199], s[36:37]
	s_add_u32 s36, s36, 0x1000
	s_addc_u32 s37, s37, 0
	s_waitcnt vmcnt(15)
	v_lshlrev_b32_e32 v172, 16, v60
	v_and_b32_e32 v173, 0xffff0000, v60
	v_lshlrev_b32_e32 v174, 16, v61
	v_and_b32_e32 v175, 0xffff0000, v61
	v_lshlrev_b32_e32 v176, 16, v62
	v_and_b32_e32 v177, 0xffff0000, v62
	v_lshlrev_b32_e32 v178, 16, v63
	v_and_b32_e32 v179, 0xffff0000, v63
	v_pk_add_f32 v[164:165], v[164:165], v[172:173]
	v_pk_add_f32 v[166:167], v[166:167], v[174:175]
	v_pk_add_f32 v[168:169], v[168:169], v[176:177]
	v_pk_add_f32 v[170:171], v[170:171], v[178:179]
	v_lshlrev_b32_e32 v180, 16, v44
	v_and_b32_e32 v181, 0xffff0000, v44
	v_lshlrev_b32_e32 v182, 16, v45
	v_and_b32_e32 v183, 0xffff0000, v45
	v_lshlrev_b32_e32 v184, 16, v46
	v_and_b32_e32 v185, 0xffff0000, v46
	v_lshlrev_b32_e32 v186, 16, v47
	v_and_b32_e32 v187, 0xffff0000, v47
	v_sub_f32_e32 v164, v164, v180
	v_sub_f32_e32 v165, v165, v181
	v_sub_f32_e32 v166, v166, v182
	v_sub_f32_e32 v167, v167, v183
	v_sub_f32_e32 v168, v168, v184
	v_sub_f32_e32 v169, v169, v185
	v_sub_f32_e32 v170, v170, v186
	v_sub_f32_e32 v171, v171, v187
	v_fma_f32 v188, v164, s72, -v172
	v_fma_f32 v189, v165, s72, -v173
	v_fma_f32 v190, v166, s72, -v174
	v_fma_f32 v191, v167, s72, -v175
	v_fma_f32 v192, v168, s72, -v176
	v_fma_f32 v193, v169, s72, -v177
	v_fma_f32 v194, v170, s72, -v178
	v_fma_f32 v195, v171, s72, -v179
	v_cvt_pk_bf16_f32 v196, v188, v189
	v_cvt_pk_bf16_f32 v197, v190, v191
	v_cvt_pk_bf16_f32 v198, v192, v193
	v_cvt_pk_bf16_f32 v199, v194, v195
	global_store_dwordx4 v39, v[196:199], s[36:37]
	s_add_u32 s36, s36, 0x1000
	s_addc_u32 s37, s37, 0
	s_waitcnt vmcnt(15)
	v_lshlrev_b32_e32 v172, 16, v64
	v_and_b32_e32 v173, 0xffff0000, v64
	v_lshlrev_b32_e32 v174, 16, v65
	v_and_b32_e32 v175, 0xffff0000, v65
	v_lshlrev_b32_e32 v176, 16, v66
	v_and_b32_e32 v177, 0xffff0000, v66
	v_lshlrev_b32_e32 v178, 16, v67
	v_and_b32_e32 v179, 0xffff0000, v67
	v_pk_add_f32 v[164:165], v[164:165], v[172:173]
	v_pk_add_f32 v[166:167], v[166:167], v[174:175]
	v_pk_add_f32 v[168:169], v[168:169], v[176:177]
	v_pk_add_f32 v[170:171], v[170:171], v[178:179]
	v_lshlrev_b32_e32 v180, 16, v48
	v_and_b32_e32 v181, 0xffff0000, v48
	v_lshlrev_b32_e32 v182, 16, v49
	v_and_b32_e32 v183, 0xffff0000, v49
	v_lshlrev_b32_e32 v184, 16, v50
	v_and_b32_e32 v185, 0xffff0000, v50
	v_lshlrev_b32_e32 v186, 16, v51
	v_and_b32_e32 v187, 0xffff0000, v51
	v_sub_f32_e32 v164, v164, v180
	v_sub_f32_e32 v165, v165, v181
	v_sub_f32_e32 v166, v166, v182
	v_sub_f32_e32 v167, v167, v183
	v_sub_f32_e32 v168, v168, v184
	v_sub_f32_e32 v169, v169, v185
	v_sub_f32_e32 v170, v170, v186
	v_sub_f32_e32 v171, v171, v187
	v_fma_f32 v188, v164, s72, -v172
	v_fma_f32 v189, v165, s72, -v173
	v_fma_f32 v190, v166, s72, -v174
	v_fma_f32 v191, v167, s72, -v175
	v_fma_f32 v192, v168, s72, -v176
	v_fma_f32 v193, v169, s72, -v177
	v_fma_f32 v194, v170, s72, -v178
	v_fma_f32 v195, v171, s72, -v179
	v_cvt_pk_bf16_f32 v196, v188, v189
	v_cvt_pk_bf16_f32 v197, v190, v191
	v_cvt_pk_bf16_f32 v198, v192, v193
	v_cvt_pk_bf16_f32 v199, v194, v195
	global_store_dwordx4 v39, v[196:199], s[36:37]
	s_add_u32 s36, s36, 0x1000
	s_addc_u32 s37, s37, 0
	s_waitcnt vmcnt(15)
; __device__ __forceinline__ u32x4 pack8(const f32x4 v0, const f32x4 v1) { u32x4 w; w.x = cvt_pk_bf16(v0[0], v0[1]); w.y = cvt_pk_bf16(v0[2], v0[3]); w.z = cvt_pk_bf16(v1[0], v1[1]); w.w = cvt_pk_bf16(v1[2], v1[3]); return w; }
; __device__ __forceinline__ void unpack8(const u32x4 w, f32x4& lo, f32x4& hi) { lo = (f32x4){bf_lo(w.x), bf_hi(w.x), bf_lo(w.y), bf_hi(w.y)}; hi = (f32x4){bf_lo(w.z), bf_hi(w.z), bf_lo(w.w), bf_hi(w.w)}; }
; __device__ __forceinline__ void phase_pool(const bf16_t* PROJ, bf16_t* Z, int gw, int NGW, int lane) {
;     ...
;         for (int t = t0; t < t0 + 16; ++t) {
;             f32x4 v0, v1; unpack8(*(const u32x4*)(vb + (size_t)t * DIN), v0, v1); s0 += v0; s1 += v1;
;             if (t > t0 && t - win >= 0) { f32x4 a, c; unpack8(*(const u32x4*)(vb + (size_t)(t - win) * DIN), a, c); s0 -= a; s1 -= c; }
;             const float inv = 1.f / (float)((t + 1) < win ? (t + 1) : win);
;             *(u32x4*)(zb + (size_t)t * DSS) = pack8(s0 * inv - v0, s1 * inv - v1);
	v_lshlrev_b32_e32 v172, 16, v68
	v_and_b32_e32 v173, 0xffff0000, v68
	v_lshlrev_b32_e32 v174, 16, v69
	v_and_b32_e32 v175, 0xffff0000, v69
	v_lshlrev_b32_e32 v176, 16, v70
	v_and_b32_e32 v177, 0xffff0000, v70
	v_lshlrev_b32_e32 v178, 16, v71
	v_and_b32_e32 v179, 0xffff0000, v71
	v_pk_add_f32 v[164:165], v[164:165], v[172:173]
	v_pk_add_f32 v[166:167], v[166:167], v[174:175]
	v_pk_add_f32 v[168:169], v[168:169], v[176:177]
	v_pk_add_f32 v[170:171], v[170:171], v[178:179]
	v_lshlrev_b32_e32 v180, 16, v52
	v_and_b32_e32 v181, 0xffff0000, v52
	v_lshlrev_b32_e32 v182, 16, v53
	v_and_b32_e32 v183, 0xffff0000, v53
	v_lshlrev_b32_e32 v184, 16, v54
	v_and_b32_e32 v185, 0xffff0000, v54
	v_lshlrev_b32_e32 v186, 16, v55
	v_and_b32_e32 v187, 0xffff0000, v55
	v_sub_f32_e32 v164, v164, v180
	v_sub_f32_e32 v165, v165, v181
	v_sub_f32_e32 v166, v166, v182
	v_sub_f32_e32 v167, v167, v183
	v_sub_f32_e32 v168, v168, v184
	v_sub_f32_e32 v169, v169, v185
	v_sub_f32_e32 v170, v170, v186
	v_sub_f32_e32 v171, v171, v187
	v_fma_f32 v188, v164, s72, -v172
	v_fma_f32 v189, v165, s72, -v173
	v_fma_f32 v190, v166, s72, -v174
	v_fma_f32 v191, v167, s72, -v175
	v_fma_f32 v192, v168, s72, -v176
	v_fma_f32 v193, v169, s72, -v177
	v_fma_f32 v194, v170, s72, -v178
	v_fma_f32 v195, v171, s72, -v179
	v_cvt_pk_bf16_f32 v196, v188, v189
	v_cvt_pk_bf16_f32 v197, v190, v191
	v_cvt_pk_bf16_f32 v198, v192, v193
	v_cvt_pk_bf16_f32 v199, v194, v195
	global_store_dwordx4 v39, v[196:199], s[36:37]
	s_add_u32 s36, s36, 0x1000
	s_addc_u32 s37, s37, 0
	s_waitcnt vmcnt(15)
	v_lshlrev_b32_e32 v172, 16, v72
	v_and_b32_e32 v173, 0xffff0000, v72
	v_lshlrev_b32_e32 v174, 16, v73
	v_and_b32_e32 v175, 0xffff0000, v73
	v_lshlrev_b32_e32 v176, 16, v74
	v_and_b32_e32 v177, 0xffff0000, v74
	v_lshlrev_b32_e32 v178, 16, v75
	v_and_b32_e32 v179, 0xffff0000, v75
	v_pk_add_f32 v[164:165], v[164:165], v[172:173]
	v_pk_add_f32 v[166:167], v[166:167], v[174:175]
	v_pk_add_f32 v[168:169], v[168:169], v[176:177]
	v_pk_add_f32 v[170:171], v[170:171], v[178:179]
	v_lshlrev_b32_e32 v180, 16, v56
	v_and_b32_e32 v181, 0xffff0000, v56
	v_lshlrev_b32_e32 v182, 16, v57
	v_and_b32_e32 v183, 0xffff0000, v57
	v_lshlrev_b32_e32 v184, 16, v58
	v_and_b32_e32 v185, 0xffff0000, v58
	v_lshlrev_b32_e32 v186, 16, v59
	v_and_b32_e32 v187, 0xffff0000, v59
	v_sub_f32_e32 v164, v164, v180
	v_sub_f32_e32 v165, v165, v181
	v_sub_f32_e32 v166, v166, v182
	v_sub_f32_e32 v167, v167, v183
	v_sub_f32_e32 v168, v168, v184
	v_sub_f32_e32 v169, v169, v185
	v_sub_f32_e32 v170, v170, v186
	v_sub_f32_e32 v171, v171, v187
	v_fma_f32 v188, v164, s72, -v172
	v_fma_f32 v189, v165, s72, -v173
	v_fma_f32 v190, v166, s72, -v174
	v_fma_f32 v191, v167, s72, -v175
	v_fma_f32 v192, v168, s72, -v176
	v_fma_f32 v193, v169, s72, -v177
	v_fma_f32 v194, v170, s72, -v178
	v_fma_f32 v195, v171, s72, -v179
	v_cvt_pk_bf16_f32 v196, v188, v189
	v_cvt_pk_bf16_f32 v197, v190, v191
	v_cvt_pk_bf16_f32 v198, v192, v193
	v_cvt_pk_bf16_f32 v199, v194, v195
	global_store_dwordx4 v39, v[196:199], s[36:37]
	s_add_u32 s36, s36, 0x1000
	s_addc_u32 s37, s37, 0
	s_waitcnt vmcnt(15)
	v_lshlrev_b32_e32 v172, 16, v76
	v_and_b32_e32 v173, 0xffff0000, v76
	v_lshlrev_b32_e32 v174, 16, v77
	v_and_b32_e32 v175, 0xffff0000, v77
	v_lshlrev_b32_e32 v176, 16, v78
	v_and_b32_e32 v177, 0xffff0000, v78
	v_lshlrev_b32_e32 v178, 16, v79
	v_and_b32_e32 v179, 0xffff0000, v79
	v_pk_add_f32 v[164:165], v[164:165], v[172:173]
	v_pk_add_f32 v[166:167], v[166:167], v[174:175]
	v_pk_add_f32 v[168:169], v[168:169], v[176:177]
	v_pk_add_f32 v[170:171], v[170:171], v[178:179]
	v_lshlrev_b32_e32 v180, 16, v60
	v_and_b32_e32 v181, 0xffff0000, v60
	v_lshlrev_b32_e32 v182, 16, v61
	v_and_b32_e32 v183, 0xffff0000, v61
	v_lshlrev_b32_e32 v184, 16, v62
	v_and_b32_e32 v185, 0xffff0000, v62
	v_lshlrev_b32_e32 v186, 16, v63
	v_and_b32_e32 v187, 0xffff0000, v63
	v_sub_f32_e32 v164, v164, v180
	v_sub_f32_e32 v165, v165, v181
	v_sub_f32_e32 v166, v166, v182
	v_sub_f32_e32 v167, v167, v183
	v_sub_f32_e32 v168, v168, v184
	v_sub_f32_e32 v169, v169, v185
	v_sub_f32_e32 v170, v170, v186
	v_sub_f32_e32 v171, v171, v187
	v_fma_f32 v188, v164, s72, -v172
	v_fma_f32 v189, v165, s72, -v173
	v_fma_f32 v190, v166, s72, -v174
	v_fma_f32 v191, v167, s72, -v175
	v_fma_f32 v192, v168, s72, -v176
	v_fma_f32 v193, v169, s72, -v177
	v_fma_f32 v194, v170, s72, -v178
	v_fma_f32 v195, v171, s72, -v179
	v_cvt_pk_bf16_f32 v196, v188, v189
	v_cvt_pk_bf16_f32 v197, v190, v191
	v_cvt_pk_bf16_f32 v198, v192, v193
	v_cvt_pk_bf16_f32 v199, v194, v195
	global_store_dwordx4 v39, v[196:199], s[36:37]
	s_add_u32 s36, s36, 0x1000
	s_addc_u32 s37, s37, 0
	s_waitcnt vmcnt(15)
	v_lshlrev_b32_e32 v172, 16, v80
	v_and_b32_e32 v173, 0xffff0000, v80
	v_lshlrev_b32_e32 v174, 16, v81
	v_and_b32_e32 v175, 0xffff0000, v81
	v_lshlrev_b32_e32 v176, 16, v82
	v_and_b32_e32 v177, 0xffff0000, v82
	v_lshlrev_b32_e32 v178, 16, v83
	v_and_b32_e32 v179, 0xffff0000, v83
	v_pk_add_f32 v[164:165], v[164:165], v[172:173]
	v_pk_add_f32 v[166:167], v[166:167], v[174:175]
	v_pk_add_f32 v[168:169], v[168:169], v[176:177]
	v_pk_add_f32 v[170:171], v[170:171], v[178:179]
	v_lshlrev_b32_e32 v180, 16, v64
	v_and_b32_e32 v181, 0xffff0000, v64
	v_lshlrev_b32_e32 v182, 16, v65
	v_and_b32_e32 v183, 0xffff0000, v65
	v_lshlrev_b32_e32 v184, 16, v66
	v_and_b32_e32 v185, 0xffff0000, v66
	v_lshlrev_b32_e32 v186, 16, v67
	v_and_b32_e32 v187, 0xffff0000, v67
	v_sub_f32_e32 v164, v164, v180
	v_sub_f32_e32 v165, v165, v181
	v_sub_f32_e32 v166, v166, v182
	v_sub_f32_e32 v167, v167, v183
	v_sub_f32_e32 v168, v168, v184
	v_sub_f32_e32 v169, v169, v185
	v_sub_f32_e32 v170, v170, v186
	v_sub_f32_e32 v171, v171, v187
	v_fma_f32 v188, v164, s72, -v172
	v_fma_f32 v189, v165, s72, -v173
	v_fma_f32 v190, v166, s72, -v174
	v_fma_f32 v191, v167, s72, -v175
	v_fma_f32 v192, v168, s72, -v176
	v_fma_f32 v193, v169, s72, -v177
	v_fma_f32 v194, v170, s72, -v178
	v_fma_f32 v195, v171, s72, -v179
	v_cvt_pk_bf16_f32 v196, v188, v189
	v_cvt_pk_bf16_f32 v197, v190, v191
	v_cvt_pk_bf16_f32 v198, v192, v193
	v_cvt_pk_bf16_f32 v199, v194, v195
	global_store_dwordx4 v39, v[196:199], s[36:37]
	s_add_u32 s36, s36, 0x1000
	s_addc_u32 s37, s37, 0
	s_waitcnt vmcnt(15)
; __device__ __forceinline__ u32x4 pack8(const f32x4 v0, const f32x4 v1) { u32x4 w; w.x = cvt_pk_bf16(v0[0], v0[1]); w.y = cvt_pk_bf16(v0[2], v0[3]); w.z = cvt_pk_bf16(v1[0], v1[1]); w.w = cvt_pk_bf16(v1[2], v1[3]); return w; }
; __device__ __forceinline__ void unpack8(const u32x4 w, f32x4& lo, f32x4& hi) { lo = (f32x4){bf_lo(w.x), bf_hi(w.x), bf_lo(w.y), bf_hi(w.y)}; hi = (f32x4){bf_lo(w.z), bf_hi(w.z), bf_lo(w.w), bf_hi(w.w)}; }
; __device__ __forceinline__ void phase_pool(const bf16_t* PROJ, bf16_t* Z, int gw, int NGW, int lane) {
;     ...
;         for (int t = t0; t < t0 + 16; ++t) {
;             f32x4 v0, v1; unpack8(*(const u32x4*)(vb + (size_t)t * DIN), v0, v1); s0 += v0; s1 += v1;
;             if (t > t0 && t - win >= 0) { f32x4 a, c; unpack8(*(const u32x4*)(vb + (size_t)(t - win) * DIN), a, c); s0 -= a; s1 -= c; }
;             const float inv = 1.f / (float)((t + 1) < win ? (t + 1) : win);
;             *(u32x4*)(zb + (size_t)t * DSS) = pack8(s0 * inv - v0, s1 * inv - v1);
	v_lshlrev_b32_e32 v172, 16, v84
	v_and_b32_e32 v173, 0xffff0000, v84
	v_lshlrev_b32_e32 v174, 16, v85
	v_and_b32_e32 v175, 0xffff0000, v85
	v_lshlrev_b32_e32 v176, 16, v86
	v_and_b32_e32 v177, 0xffff0000, v86
	v_lshlrev_b32_e32 v178, 16, v87
	v_and_b32_e32 v179, 0xffff0000, v87
	v_pk_add_f32 v[164:165], v[164:165], v[172:173]
	v_pk_add_f32 v[166:167], v[166:167], v[174:175]
	v_pk_add_f32 v[168:169], v[168:169], v[176:177]
	v_pk_add_f32 v[170:171], v[170:171], v[178:179]
	v_lshlrev_b32_e32 v180, 16, v68
	v_and_b32_e32 v181, 0xffff0000, v68
	v_lshlrev_b32_e32 v182, 16, v69
	v_and_b32_e32 v183, 0xffff0000, v69
	v_lshlrev_b32_e32 v184, 16, v70
	v_and_b32_e32 v185, 0xffff0000, v70
	v_lshlrev_b32_e32 v186, 16, v71
	v_and_b32_e32 v187, 0xffff0000, v71
	v_sub_f32_e32 v164, v164, v180
	v_sub_f32_e32 v165, v165, v181
	v_sub_f32_e32 v166, v166, v182
	v_sub_f32_e32 v167, v167, v183
	v_sub_f32_e32 v168, v168, v184
	v_sub_f32_e32 v169, v169, v185
	v_sub_f32_e32 v170, v170, v186
	v_sub_f32_e32 v171, v171, v187
	v_fma_f32 v188, v164, s72, -v172
	v_fma_f32 v189, v165, s72, -v173
	v_fma_f32 v190, v166, s72, -v174
	v_fma_f32 v191, v167, s72, -v175
	v_fma_f32 v192, v168, s72, -v176
	v_fma_f32 v193, v169, s72, -v177
	v_fma_f32 v194, v170, s72, -v178
	v_fma_f32 v195, v171, s72, -v179
	v_cvt_pk_bf16_f32 v196, v188, v189
	v_cvt_pk_bf16_f32 v197, v190, v191
	v_cvt_pk_bf16_f32 v198, v192, v193
	v_cvt_pk_bf16_f32 v199, v194, v195
	global_store_dwordx4 v39, v[196:199], s[36:37]
	s_add_u32 s36, s36, 0x1000
	s_addc_u32 s37, s37, 0
	s_waitcnt vmcnt(15)
	v_lshlrev_b32_e32 v172, 16, v88
	v_and_b32_e32 v173, 0xffff0000, v88
	v_lshlrev_b32_e32 v174, 16, v89
	v_and_b32_e32 v175, 0xffff0000, v89
	v_lshlrev_b32_e32 v176, 16, v90
	v_and_b32_e32 v177, 0xffff0000, v90
	v_lshlrev_b32_e32 v178, 16, v91
	v_and_b32_e32 v179, 0xffff0000, v91
	v_pk_add_f32 v[164:165], v[164:165], v[172:173]
	v_pk_add_f32 v[166:167], v[166:167], v[174:175]
	v_pk_add_f32 v[168:169], v[168:169], v[176:177]
	v_pk_add_f32 v[170:171], v[170:171], v[178:179]
	v_lshlrev_b32_e32 v180, 16, v72
	v_and_b32_e32 v181, 0xffff0000, v72
	v_lshlrev_b32_e32 v182, 16, v73
	v_and_b32_e32 v183, 0xffff0000, v73
	v_lshlrev_b32_e32 v184, 16, v74
	v_and_b32_e32 v185, 0xffff0000, v74
	v_lshlrev_b32_e32 v186, 16, v75
	v_and_b32_e32 v187, 0xffff0000, v75
	v_sub_f32_e32 v164, v164, v180
	v_sub_f32_e32 v165, v165, v181
	v_sub_f32_e32 v166, v166, v182
	v_sub_f32_e32 v167, v167, v183
	v_sub_f32_e32 v168, v168, v184
	v_sub_f32_e32 v169, v169, v185
	v_sub_f32_e32 v170, v170, v186
	v_sub_f32_e32 v171, v171, v187
	v_fma_f32 v188, v164, s72, -v172
	v_fma_f32 v189, v165, s72, -v173
	v_fma_f32 v190, v166, s72, -v174
	v_fma_f32 v191, v167, s72, -v175
	v_fma_f32 v192, v168, s72, -v176
	v_fma_f32 v193, v169, s72, -v177
	v_fma_f32 v194, v170, s72, -v178
	v_fma_f32 v195, v171, s72, -v179
	v_cvt_pk_bf16_f32 v196, v188, v189
	v_cvt_pk_bf16_f32 v197, v190, v191
	v_cvt_pk_bf16_f32 v198, v192, v193
	v_cvt_pk_bf16_f32 v199, v194, v195
	global_store_dwordx4 v39, v[196:199], s[36:37]
	s_add_u32 s36, s36, 0x1000
	s_addc_u32 s37, s37, 0
	s_waitcnt vmcnt(15)
	v_lshlrev_b32_e32 v172, 16, v92
	v_and_b32_e32 v173, 0xffff0000, v92
	v_lshlrev_b32_e32 v174, 16, v93
	v_and_b32_e32 v175, 0xffff0000, v93
	v_lshlrev_b32_e32 v176, 16, v94
	v_and_b32_e32 v177, 0xffff0000, v94
	v_lshlrev_b32_e32 v178, 16, v95
	v_and_b32_e32 v179, 0xffff0000, v95
	v_pk_add_f32 v[164:165], v[164:165], v[172:173]
	v_pk_add_f32 v[166:167], v[166:167], v[174:175]
	v_pk_add_f32 v[168:169], v[168:169], v[176:177]
	v_pk_add_f32 v[170:171], v[170:171], v[178:179]
	v_lshlrev_b32_e32 v180, 16, v76
	v_and_b32_e32 v181, 0xffff0000, v76
	v_lshlrev_b32_e32 v182, 16, v77
	v_and_b32_e32 v183, 0xffff0000, v77
	v_lshlrev_b32_e32 v184, 16, v78
	v_and_b32_e32 v185, 0xffff0000, v78
	v_lshlrev_b32_e32 v186, 16, v79
	v_and_b32_e32 v187, 0xffff0000, v79
	v_sub_f32_e32 v164, v164, v180
	v_sub_f32_e32 v165, v165, v181
	v_sub_f32_e32 v166, v166, v182
	v_sub_f32_e32 v167, v167, v183
	v_sub_f32_e32 v168, v168, v184
	v_sub_f32_e32 v169, v169, v185
	v_sub_f32_e32 v170, v170, v186
	v_sub_f32_e32 v171, v171, v187
	v_fma_f32 v188, v164, s72, -v172
	v_fma_f32 v189, v165, s72, -v173
	v_fma_f32 v190, v166, s72, -v174
	v_fma_f32 v191, v167, s72, -v175
	v_fma_f32 v192, v168, s72, -v176
	v_fma_f32 v193, v169, s72, -v177
	v_fma_f32 v194, v170, s72, -v178
	v_fma_f32 v195, v171, s72, -v179
	v_cvt_pk_bf16_f32 v196, v188, v189
	v_cvt_pk_bf16_f32 v197, v190, v191
	v_cvt_pk_bf16_f32 v198, v192, v193
	v_cvt_pk_bf16_f32 v199, v194, v195
	global_store_dwordx4 v39, v[196:199], s[36:37]
	s_add_u32 s36, s36, 0x1000
	s_addc_u32 s37, s37, 0
	s_waitcnt vmcnt(15)
	v_lshlrev_b32_e32 v172, 16, v96
	v_and_b32_e32 v173, 0xffff0000, v96
	v_lshlrev_b32_e32 v174, 16, v97
	v_and_b32_e32 v175, 0xffff0000, v97
	v_lshlrev_b32_e32 v176, 16, v98
	v_and_b32_e32 v177, 0xffff0000, v98
	v_lshlrev_b32_e32 v178, 16, v99
	v_and_b32_e32 v179, 0xffff0000, v99
	v_pk_add_f32 v[164:165], v[164:165], v[172:173]
	v_pk_add_f32 v[166:167], v[166:167], v[174:175]
	v_pk_add_f32 v[168:169], v[168:169], v[176:177]
	v_pk_add_f32 v[170:171], v[170:171], v[178:179]
	v_lshlrev_b32_e32 v180, 16, v80
	v_and_b32_e32 v181, 0xffff0000, v80
	v_lshlrev_b32_e32 v182, 16, v81
	v_and_b32_e32 v183, 0xffff0000, v81
	v_lshlrev_b32_e32 v184, 16, v82
	v_and_b32_e32 v185, 0xffff0000, v82
	v_lshlrev_b32_e32 v186, 16, v83
	v_and_b32_e32 v187, 0xffff0000, v83
	v_sub_f32_e32 v164, v164, v180
	v_sub_f32_e32 v165, v165, v181
	v_sub_f32_e32 v166, v166, v182
	v_sub_f32_e32 v167, v167, v183
	v_sub_f32_e32 v168, v168, v184
	v_sub_f32_e32 v169, v169, v185
	v_sub_f32_e32 v170, v170, v186
	v_sub_f32_e32 v171, v171, v187
	v_fma_f32 v188, v164, s72, -v172
	v_fma_f32 v189, v165, s72, -v173
	v_fma_f32 v190, v166, s72, -v174
	v_fma_f32 v191, v167, s72, -v175
	v_fma_f32 v192, v168, s72, -v176
	v_fma_f32 v193, v169, s72, -v177
	v_fma_f32 v194, v170, s72, -v178
	v_fma_f32 v195, v171, s72, -v179
	v_cvt_pk_bf16_f32 v196, v188, v189
	v_cvt_pk_bf16_f32 v197, v190, v191
	v_cvt_pk_bf16_f32 v198, v192, v193
	v_cvt_pk_bf16_f32 v199, v194, v195
	global_store_dwordx4 v39, v[196:199], s[36:37]
	s_add_u32 s36, s36, 0x1000
	s_addc_u32 s37, s37, 0
	s_waitcnt vmcnt(15)
; __device__ __forceinline__ u32x4 pack8(const f32x4 v0, const f32x4 v1) { u32x4 w; w.x = cvt_pk_bf16(v0[0], v0[1]); w.y = cvt_pk_bf16(v0[2], v0[3]); w.z = cvt_pk_bf16(v1[0], v1[1]); w.w = cvt_pk_bf16(v1[2], v1[3]); return w; }
; __device__ __forceinline__ void unpack8(const u32x4 w, f32x4& lo, f32x4& hi) { lo = (f32x4){bf_lo(w.x), bf_hi(w.x), bf_lo(w.y), bf_hi(w.y)}; hi = (f32x4){bf_lo(w.z), bf_hi(w.z), bf_lo(w.w), bf_hi(w.w)}; }
; __device__ __forceinline__ void phase_pool(const bf16_t* PROJ, bf16_t* Z, int gw, int NGW, int lane) {
;     ...
;         const int t0 = tseg * 16;
;         for (int tau = (t0 - win + 1 > 0 ? t0 - win + 1 : 0); tau < t0; ++tau) { f32x4 a, c; unpack8(*(const u32x4*)(vb + (size_t)tau * DIN), a, c); s0 += a; s1 += c; }
;         for (int t = t0; t < t0 + 16; ++t) {
;             f32x4 v0, v1; unpack8(*(const u32x4*)(vb + (size_t)t * DIN), v0, v1); s0 += v0; s1 += v1;
;             if (t > t0 && t - win >= 0) { f32x4 a, c; unpack8(*(const u32x4*)(vb + (size_t)(t - win) * DIN), a, c); s0 -= a; s1 -= c; }
;             const float inv = 1.f / (float)((t + 1) < win ? (t + 1) : win);
;             *(u32x4*)(zb + (size_t)t * DSS) = pack8(s0 * inv - v0, s1 * inv - v1);
	v_lshlrev_b32_e32 v172, 16, v100
	v_and_b32_e32 v173, 0xffff0000, v100
	v_lshlrev_b32_e32 v174, 16, v101
	v_and_b32_e32 v175, 0xffff0000, v101
	v_lshlrev_b32_e32 v176, 16, v102
	v_and_b32_e32 v177, 0xffff0000, v102
	v_lshlrev_b32_e32 v178, 16, v103
	v_and_b32_e32 v179, 0xffff0000, v103
	v_pk_add_f32 v[164:165], v[164:165], v[172:173]
	v_pk_add_f32 v[166:167], v[166:167], v[174:175]
	v_pk_add_f32 v[168:169], v[168:169], v[176:177]
	v_pk_add_f32 v[170:171], v[170:171], v[178:179]
	v_lshlrev_b32_e32 v180, 16, v84
	v_and_b32_e32 v181, 0xffff0000, v84
	v_lshlrev_b32_e32 v182, 16, v85
	v_and_b32_e32 v183, 0xffff0000, v85
	v_lshlrev_b32_e32 v184, 16, v86
	v_and_b32_e32 v185, 0xffff0000, v86
	v_lshlrev_b32_e32 v186, 16, v87
	v_and_b32_e32 v187, 0xffff0000, v87
	v_sub_f32_e32 v164, v164, v180
	v_sub_f32_e32 v165, v165, v181
	v_sub_f32_e32 v166, v166, v182
	v_sub_f32_e32 v167, v167, v183
	v_sub_f32_e32 v168, v168, v184
	v_sub_f32_e32 v169, v169, v185
	v_sub_f32_e32 v170, v170, v186
	v_sub_f32_e32 v171, v171, v187
	v_fma_f32 v188, v164, s72, -v172
	v_fma_f32 v189, v165, s72, -v173
	v_fma_f32 v190, v166, s72, -v174
	v_fma_f32 v191, v167, s72, -v175
	v_fma_f32 v192, v168, s72, -v176
	v_fma_f32 v193, v169, s72, -v177
	v_fma_f32 v194, v170, s72, -v178
	v_fma_f32 v195, v171, s72, -v179
	v_cvt_pk_bf16_f32 v196, v188, v189
	v_cvt_pk_bf16_f32 v197, v190, v191
	v_cvt_pk_bf16_f32 v198, v192, v193
	v_cvt_pk_bf16_f32 v199, v194, v195
	global_store_dwordx4 v39, v[196:199], s[36:37]
	s_branch .LBB0_300
.Lpool_w2:
	s_mov_b32 s72, 0x3f000000
	s_cmp_eq_u32 s65, 0
	s_cbranch_scc1 .Lpool_w2_zero
	s_sub_u32 s38, s70, 0x6000
	s_subb_u32 s39, s71, 0
	global_load_dwordx4 v[104:107], v39, s[38:39]
	s_branch .Lpool_w2_a
.Lpool_w2_zero:
	v_mov_b32_e32 v104, 0
	v_mov_b32_e32 v105, 0
	v_mov_b32_e32 v106, 0
	v_mov_b32_e32 v107, 0
.Lpool_w2_a:
	global_load_dwordx4 v[40:43], v39, s[70:71]
	s_add_u32 s70, s70, 0x6000
	s_addc_u32 s71, s71, 0
	global_load_dwordx4 v[44:47], v39, s[70:71]
	s_add_u32 s70, s70, 0x6000
	s_addc_u32 s71, s71, 0
	global_load_dwordx4 v[48:51], v39, s[70:71]
	s_add_u32 s70, s70, 0x6000
	s_addc_u32 s71, s71, 0
	global_load_dwordx4 v[52:55], v39, s[70:71]
	s_add_u32 s70, s70, 0x6000
	s_addc_u32 s71, s71, 0
	global_load_dwordx4 v[56:59], v39, s[70:71]
	s_add_u32 s70, s70, 0x6000
	s_addc_u32 s71, s71, 0
	global_load_dwordx4 v[60:63], v39, s[70:71]
	s_add_u32 s70, s70, 0x6000
	s_addc_u32 s71, s71, 0
	global_load_dwordx4 v[64:67], v39, s[70:71]
	s_add_u32 s70, s70, 0x6000
	s_addc_u32 s71, s71, 0
	global_load_dwordx4 v[68:71], v39, s[70:71]
	s_add_u32 s70, s70, 0x6000
	s_addc_u32 s71, s71, 0
	global_load_dwordx4 v[72:75], v39, s[70:71]
	s_add_u32 s70, s70, 0x6000
	s_addc_u32 s71, s71, 0
	global_load_dwordx4 v[76:79], v39, s[70:71]
	s_add_u32 s70, s70, 0x6000
	s_addc_u32 s71, s71, 0
	global_load_dwordx4 v[80:83], v39, s[70:71]
	s_add_u32 s70, s70, 0x6000
	s_addc_u32 s71, s71, 0
	global_load_dwordx4 v[84:87], v39, s[70:71]
	s_add_u32 s70, s70, 0x6000
	s_addc_u32 s71, s71, 0
	global_load_dwordx4 v[88:91], v39, s[70:71]
	s_add_u32 s70, s70, 0x6000
	s_addc_u32 s71, s71, 0
	global_load_dwordx4 v[92:95], v39, s[70:71]
	s_add_u32 s70, s70, 0x6000
	s_addc_u32 s71, s71, 0
	global_load_dwordx4 v[96:99], v39, s[70:71]
	s_add_u32 s70, s70, 0x6000
	s_addc_u32 s71, s71, 0
	global_load_dwordx4 v[100:103], v39, s[70:71]
	s_waitcnt vmcnt(15)
	v_lshlrev_b32_e32 v164, 16, v104
	v_and_b32_e32 v165, 0xffff0000, v104
	v_lshlrev_b32_e32 v166, 16, v105
	v_and_b32_e32 v167, 0xffff0000, v105
	v_lshlrev_b32_e32 v168, 16, v106
	v_and_b32_e32 v169, 0xffff0000, v106
	v_lshlrev_b32_e32 v170, 16, v107
	v_and_b32_e32 v171, 0xffff0000, v107
	v_lshlrev_b32_e32 v172, 16, v40
	v_and_b32_e32 v173, 0xffff0000, v40
	v_lshlrev_b32_e32 v174, 16, v41
	v_and_b32_e32 v175, 0xffff0000, v41
	v_lshlrev_b32_e32 v176, 16, v42
	v_and_b32_e32 v177, 0xffff0000, v42
	v_lshlrev_b32_e32 v178, 16, v43
	v_and_b32_e32 v179, 0xffff0000, v43
	v_pk_add_f32 v[164:165], v[164:165], v[172:173]
	v_pk_add_f32 v[166:167], v[166:167], v[174:175]
	v_pk_add_f32 v[168:169], v[168:169], v[176:177]
	v_pk_add_f32 v[170:171], v[170:171], v[178:179]
	s_cmp_eq_u32 s65, 0
	s_cselect_b32 s4, 0x3f800000, s72
	v_fma_f32 v188, v164, s4, -v172
	v_fma_f32 v189, v165, s4, -v173
	v_fma_f32 v190, v166, s4, -v174
	v_fma_f32 v191, v167, s4, -v175
	v_fma_f32 v192, v168, s4, -v176
	v_fma_f32 v193, v169, s4, -v177
	v_fma_f32 v194, v170, s4, -v178
	v_fma_f32 v195, v171, s4, -v179
	v_cvt_pk_bf16_f32 v196, v188, v189
	v_cvt_pk_bf16_f32 v197, v190, v191
	v_cvt_pk_bf16_f32 v198, v192, v193
	v_cvt_pk_bf16_f32 v199, v194, v195
	global_store_dwordx4 v39, v[196:199], s[36:37]
	s_add_u32 s36, s36, 0x1000
	s_addc_u32 s37, s37, 0
	s_waitcnt vmcnt(15)
	v_lshlrev_b32_e32 v172, 16, v44
	v_and_b32_e32 v173, 0xffff0000, v44
	v_lshlrev_b32_e32 v174, 16, v45
	v_and_b32_e32 v175, 0xffff0000, v45
	v_lshlrev_b32_e32 v176, 16, v46
	v_and_b32_e32 v177, 0xffff0000, v46
	v_lshlrev_b32_e32 v178, 16, v47
	v_and_b32_e32 v179, 0xffff0000, v47
	v_pk_add_f32 v[164:165], v[164:165], v[172:173]
	v_pk_add_f32 v[166:167], v[166:167], v[174:175]
	v_pk_add_f32 v[168:169], v[168:169], v[176:177]
	v_pk_add_f32 v[170:171], v[170:171], v[178:179]
	v_lshlrev_b32_e32 v180, 16, v104
	v_and_b32_e32 v181, 0xffff0000, v104
	v_lshlrev_b32_e32 v182, 16, v105
	v_and_b32_e32 v183, 0xffff0000, v105
	v_lshlrev_b32_e32 v184, 16, v106
	v_and_b32_e32 v185, 0xffff0000, v106
	v_lshlrev_b32_e32 v186, 16, v107
	v_and_b32_e32 v187, 0xffff0000, v107
	v_sub_f32_e32 v164, v164, v180
	v_sub_f32_e32 v165, v165, v181
	v_sub_f32_e32 v166, v166, v182
	v_sub_f32_e32 v167, v167, v183
	v_sub_f32_e32 v168, v168, v184
	v_sub_f32_e32 v169, v169, v185
	v_sub_f32_e32 v170, v170, v186
	v_sub_f32_e32 v171, v171, v187
	v_fma_f32 v188, v164, s72, -v172
	v_fma_f32 v189, v165, s72, -v173
	v_fma_f32 v190, v166, s72, -v174
	v_fma_f32 v191, v167, s72, -v175
	v_fma_f32 v192, v168, s72, -v176
	v_fma_f32 v193, v169, s72, -v177
	v_fma_f32 v194, v170, s72, -v178
	v_fma_f32 v195, v171, s72, -v179
	v_cvt_pk_bf16_f32 v196, v188, v189
	v_cvt_pk_bf16_f32 v197, v190, v191
	v_cvt_pk_bf16_f32 v198, v192, v193
	v_cvt_pk_bf16_f32 v199, v194, v195
	global_store_dwordx4 v39, v[196:199], s[36:37]
	s_add_u32 s36, s36, 0x1000
	s_addc_u32 s37, s37, 0
	s_waitcnt vmcnt(15)
; __device__ __forceinline__ u32x4 pack8(const f32x4 v0, const f32x4 v1) { u32x4 w; w.x = cvt_pk_bf16(v0[0], v0[1]); w.y = cvt_pk_bf16(v0[2], v0[3]); w.z = cvt_pk_bf16(v1[0], v1[1]); w.w = cvt_pk_bf16(v1[2], v1[3]); return w; }
; __device__ __forceinline__ void unpack8(const u32x4 w, f32x4& lo, f32x4& hi) { lo = (f32x4){bf_lo(w.x), bf_hi(w.x), bf_lo(w.y), bf_hi(w.y)}; hi = (f32x4){bf_lo(w.z), bf_hi(w.z), bf_lo(w.w), bf_hi(w.w)}; }
; __device__ __forceinline__ void phase_pool(const bf16_t* PROJ, bf16_t* Z, int gw, int NGW, int lane) {
;     ...
;         for (int t = t0; t < t0 + 16; ++t) {
;             f32x4 v0, v1; unpack8(*(const u32x4*)(vb + (size_t)t * DIN), v0, v1); s0 += v0; s1 += v1;
;             if (t > t0 && t - win >= 0) { f32x4 a, c; unpack8(*(const u32x4*)(vb + (size_t)(t - win) * DIN), a, c); s0 -= a; s1 -= c; }
;             const float inv = 1.f / (float)((t + 1) < win ? (t + 1) : win);
;             *(u32x4*)(zb + (size_t)t * DSS) = pack8(s0 * inv - v0, s1 * inv - v1);
	v_lshlrev_b32_e32 v172, 16, v48
	v_and_b32_e32 v173, 0xffff0000, v48
	v_lshlrev_b32_e32 v174, 16, v49
	v_and_b32_e32 v175, 0xffff0000, v49
	v_lshlrev_b32_e32 v176, 16, v50
	v_and_b32_e32 v177, 0xffff0000, v50
	v_lshlrev_b32_e32 v178, 16, v51
	v_and_b32_e32 v179, 0xffff0000, v51
	v_pk_add_f32 v[164:165], v[164:165], v[172:173]
	v_pk_add_f32 v[166:167], v[166:167], v[174:175]
	v_pk_add_f32 v[168:169], v[168:169], v[176:177]
	v_pk_add_f32 v[170:171], v[170:171], v[178:179]
	v_lshlrev_b32_e32 v180, 16, v40
	v_and_b32_e32 v181, 0xffff0000, v40
	v_lshlrev_b32_e32 v182, 16, v41
	v_and_b32_e32 v183, 0xffff0000, v41
	v_lshlrev_b32_e32 v184, 16, v42
	v_and_b32_e32 v185, 0xffff0000, v42
	v_lshlrev_b32_e32 v186, 16, v43
	v_and_b32_e32 v187, 0xffff0000, v43
	v_sub_f32_e32 v164, v164, v180
	v_sub_f32_e32 v165, v165, v181
	v_sub_f32_e32 v166, v166, v182
	v_sub_f32_e32 v167, v167, v183
	v_sub_f32_e32 v168, v168, v184
	v_sub_f32_e32 v169, v169, v185
	v_sub_f32_e32 v170, v170, v186
	v_sub_f32_e32 v171, v171, v187
	v_fma_f32 v188, v164, s72, -v172
	v_fma_f32 v189, v165, s72, -v173
	v_fma_f32 v190, v166, s72, -v174
	v_fma_f32 v191, v167, s72, -v175
	v_fma_f32 v192, v168, s72, -v176
	v_fma_f32 v193, v169, s72, -v177
	v_fma_f32 v194, v170, s72, -v178
	v_fma_f32 v195, v171, s72, -v179
	v_cvt_pk_bf16_f32 v196, v188, v189
	v_cvt_pk_bf16_f32 v197, v190, v191
	v_cvt_pk_bf16_f32 v198, v192, v193
	v_cvt_pk_bf16_f32 v199, v194, v195
	global_store_dwordx4 v39, v[196:199], s[36:37]
	s_add_u32 s36, s36, 0x1000
	s_addc_u32 s37, s37, 0
	s_waitcnt vmcnt(15)
	v_lshlrev_b32_e32 v172, 16, v52
	v_and_b32_e32 v173, 0xffff0000, v52
	v_lshlrev_b32_e32 v174, 16, v53
	v_and_b32_e32 v175, 0xffff0000, v53
	v_lshlrev_b32_e32 v176, 16, v54
	v_and_b32_e32 v177, 0xffff0000, v54
	v_lshlrev_b32_e32 v178, 16, v55
	v_and_b32_e32 v179, 0xffff0000, v55
	v_pk_add_f32 v[164:165], v[164:165], v[172:173]
	v_pk_add_f32 v[166:167], v[166:167], v[174:175]
	v_pk_add_f32 v[168:169], v[168:169], v[176:177]
	v_pk_add_f32 v[170:171], v[170:171], v[178:179]
	v_lshlrev_b32_e32 v180, 16, v44
	v_and_b32_e32 v181, 0xffff0000, v44
	v_lshlrev_b32_e32 v182, 16, v45
	v_and_b32_e32 v183, 0xffff0000, v45
	v_lshlrev_b32_e32 v184, 16, v46
	v_and_b32_e32 v185, 0xffff0000, v46
	v_lshlrev_b32_e32 v186, 16, v47
	v_and_b32_e32 v187, 0xffff0000, v47
	v_sub_f32_e32 v164, v164, v180
	v_sub_f32_e32 v165, v165, v181
	v_sub_f32_e32 v166, v166, v182
	v_sub_f32_e32 v167, v167, v183
	v_sub_f32_e32 v168, v168, v184
	v_sub_f32_e32 v169, v169, v185
	v_sub_f32_e32 v170, v170, v186
	v_sub_f32_e32 v171, v171, v187
	v_fma_f32 v188, v164, s72, -v172
	v_fma_f32 v189, v165, s72, -v173
	v_fma_f32 v190, v166, s72, -v174
	v_fma_f32 v191, v167, s72, -v175
	v_fma_f32 v192, v168, s72, -v176
	v_fma_f32 v193, v169, s72, -v177
	v_fma_f32 v194, v170, s72, -v178
	v_fma_f32 v195, v171, s72, -v179
	v_cvt_pk_bf16_f32 v196, v188, v189
	v_cvt_pk_bf16_f32 v197, v190, v191
	v_cvt_pk_bf16_f32 v198, v192, v193
	v_cvt_pk_bf16_f32 v199, v194, v195
	global_store_dwordx4 v39, v[196:199], s[36:37]
	s_add_u32 s36, s36, 0x1000
	s_addc_u32 s37, s37, 0
	s_waitcnt vmcnt(15)
	v_lshlrev_b32_e32 v172, 16, v56
	v_and_b32_e32 v173, 0xffff0000, v56
	v_lshlrev_b32_e32 v174, 16, v57
	v_and_b32_e32 v175, 0xffff0000, v57
	v_lshlrev_b32_e32 v176, 16, v58
	v_and_b32_e32 v177, 0xffff0000, v58
	v_lshlrev_b32_e32 v178, 16, v59
	v_and_b32_e32 v179, 0xffff0000, v59
	v_pk_add_f32 v[164:165], v[164:165], v[172:173]
	v_pk_add_f32 v[166:167], v[166:167], v[174:175]
	v_pk_add_f32 v[168:169], v[168:169], v[176:177]
	v_pk_add_f32 v[170:171], v[170:171], v[178:179]
	v_lshlrev_b32_e32 v180, 16, v48
	v_and_b32_e32 v181, 0xffff0000, v48
	v_lshlrev_b32_e32 v182, 16, v49
	v_and_b32_e32 v183, 0xffff0000, v49
	v_lshlrev_b32_e32 v184, 16, v50
	v_and_b32_e32 v185, 0xffff0000, v50
	v_lshlrev_b32_e32 v186, 16, v51
	v_and_b32_e32 v187, 0xffff0000, v51
	v_sub_f32_e32 v164, v164, v180
	v_sub_f32_e32 v165, v165, v181
	v_sub_f32_e32 v166, v166, v182
	v_sub_f32_e32 v167, v167, v183
	v_sub_f32_e32 v168, v168, v184
	v_sub_f32_e32 v169, v169, v185
	v_sub_f32_e32 v170, v170, v186
	v_sub_f32_e32 v171, v171, v187
	v_fma_f32 v188, v164, s72, -v172
	v_fma_f32 v189, v165, s72, -v173
	v_fma_f32 v190, v166, s72, -v174
	v_fma_f32 v191, v167, s72, -v175
	v_fma_f32 v192, v168, s72, -v176
	v_fma_f32 v193, v169, s72, -v177
	v_fma_f32 v194, v170, s72, -v178
	v_fma_f32 v195, v171, s72, -v179
	v_cvt_pk_bf16_f32 v196, v188, v189
	v_cvt_pk_bf16_f32 v197, v190, v191
	v_cvt_pk_bf16_f32 v198, v192, v193
	v_cvt_pk_bf16_f32 v199, v194, v195
	global_store_dwordx4 v39, v[196:199], s[36:37]
	s_add_u32 s36, s36, 0x1000
	s_addc_u32 s37, s37, 0
	s_waitcnt vmcnt(15)
	v_lshlrev_b32_e32 v172, 16, v60
	v_and_b32_e32 v173, 0xffff0000, v60
	v_lshlrev_b32_e32 v174, 16, v61
	v_and_b32_e32 v175, 0xffff0000, v61
	v_lshlrev_b32_e32 v176, 16, v62
	v_and_b32_e32 v177, 0xffff0000, v62
	v_lshlrev_b32_e32 v178, 16, v63
	v_and_b32_e32 v179, 0xffff0000, v63
	v_pk_add_f32 v[164:165], v[164:165], v[172:173]
	v_pk_add_f32 v[166:167], v[166:167], v[174:175]
	v_pk_add_f32 v[168:169], v[168:169], v[176:177]
	v_pk_add_f32 v[170:171], v[170:171], v[178:179]
	v_lshlrev_b32_e32 v180, 16, v52
	v_and_b32_e32 v181, 0xffff0000, v52
	v_lshlrev_b32_e32 v182, 16, v53
	v_and_b32_e32 v183, 0xffff0000, v53
	v_lshlrev_b32_e32 v184, 16, v54
	v_and_b32_e32 v185, 0xffff0000, v54
	v_lshlrev_b32_e32 v186, 16, v55
	v_and_b32_e32 v187, 0xffff0000, v55
	v_sub_f32_e32 v164, v164, v180
	v_sub_f32_e32 v165, v165, v181
	v_sub_f32_e32 v166, v166, v182
	v_sub_f32_e32 v167, v167, v183
	v_sub_f32_e32 v168, v168, v184
	v_sub_f32_e32 v169, v169, v185
	v_sub_f32_e32 v170, v170, v186
	v_sub_f32_e32 v171, v171, v187
	v_fma_f32 v188, v164, s72, -v172
	v_fma_f32 v189, v165, s72, -v173
	v_fma_f32 v190, v166, s72, -v174
	v_fma_f32 v191, v167, s72, -v175
	v_fma_f32 v192, v168, s72, -v176
	v_fma_f32 v193, v169, s72, -v177
	v_fma_f32 v194, v170, s72, -v178
	v_fma_f32 v195, v171, s72, -v179
	v_cvt_pk_bf16_f32 v196, v188, v189
	v_cvt_pk_bf16_f32 v197, v190, v191
	v_cvt_pk_bf16_f32 v198, v192, v193
	v_cvt_pk_bf16_f32 v199, v194, v195
	global_store_dwordx4 v39, v[196:199], s[36:37]
	s_add_u32 s36, s36, 0x1000
	s_addc_u32 s37, s37, 0
	s_waitcnt vmcnt(15)
; __device__ __forceinline__ u32x4 pack8(const f32x4 v0, const f32x4 v1) { u32x4 w; w.x = cvt_pk_bf16(v0[0], v0[1]); w.y = cvt_pk_bf16(v0[2], v0[3]); w.z = cvt_pk_bf16(v1[0], v1[1]); w.w = cvt_pk_bf16(v1[2], v1[3]); return w; }
; __device__ __forceinline__ void unpack8(const u32x4 w, f32x4& lo, f32x4& hi) { lo = (f32x4){bf_lo(w.x), bf_hi(w.x), bf_lo(w.y), bf_hi(w.y)}; hi = (f32x4){bf_lo(w.z), bf_hi(w.z), bf_lo(w.w), bf_hi(w.w)}; }
; __device__ __forceinline__ void phase_pool(const bf16_t* PROJ, bf16_t* Z, int gw, int NGW, int lane) {
;     ...
;         for (int t = t0; t < t0 + 16; ++t) {
;             f32x4 v0, v1; unpack8(*(const u32x4*)(vb + (size_t)t * DIN), v0, v1); s0 += v0; s1 += v1;
;             if (t > t0 && t - win >= 0) { f32x4 a, c; unpack8(*(const u32x4*)(vb + (size_t)(t - win) * DIN), a, c); s0 -= a; s1 -= c; }
;             const float inv = 1.f / (float)((t + 1) < win ? (t + 1) : win);
;             *(u32x4*)(zb + (size_t)t * DSS) = pack8(s0 * inv - v0, s1 * inv - v1);
	v_lshlrev_b32_e32 v172, 16, v64
	v_and_b32_e32 v173, 0xffff0000, v64
	v_lshlrev_b32_e32 v174, 16, v65
	v_and_b32_e32 v175, 0xffff0000, v65
	v_lshlrev_b32_e32 v176, 16, v66
	v_and_b32_e32 v177, 0xffff0000, v66
	v_lshlrev_b32_e32 v178, 16, v67
	v_and_b32_e32 v179, 0xffff0000, v67
	v_pk_add_f32 v[164:165], v[164:165], v[172:173]
	v_pk_add_f32 v[166:167], v[166:167], v[174:175]
	v_pk_add_f32 v[168:169], v[168:169], v[176:177]
	v_pk_add_f32 v[170:171], v[170:171], v[178:179]
	v_lshlrev_b32_e32 v180, 16, v56
	v_and_b32_e32 v181, 0xffff0000, v56
	v_lshlrev_b32_e32 v182, 16, v57
	v_and_b32_e32 v183, 0xffff0000, v57
	v_lshlrev_b32_e32 v184, 16, v58
	v_and_b32_e32 v185, 0xffff0000, v58
	v_lshlrev_b32_e32 v186, 16, v59
	v_and_b32_e32 v187, 0xffff0000, v59
	v_sub_f32_e32 v164, v164, v180
	v_sub_f32_e32 v165, v165, v181
	v_sub_f32_e32 v166, v166, v182
	v_sub_f32_e32 v167, v167, v183
	v_sub_f32_e32 v168, v168, v184
	v_sub_f32_e32 v169, v169, v185
	v_sub_f32_e32 v170, v170, v186
	v_sub_f32_e32 v171, v171, v187
	v_fma_f32 v188, v164, s72, -v172
	v_fma_f32 v189, v165, s72, -v173
	v_fma_f32 v190, v166, s72, -v174
	v_fma_f32 v191, v167, s72, -v175
	v_fma_f32 v192, v168, s72, -v176
	v_fma_f32 v193, v169, s72, -v177
	v_fma_f32 v194, v170, s72, -v178
	v_fma_f32 v195, v171, s72, -v179
	v_cvt_pk_bf16_f32 v196, v188, v189
	v_cvt_pk_bf16_f32 v197, v190, v191
	v_cvt_pk_bf16_f32 v198, v192, v193
	v_cvt_pk_bf16_f32 v199, v194, v195
	global_store_dwordx4 v39, v[196:199], s[36:37]
	s_add_u32 s36, s36, 0x1000
	s_addc_u32 s37, s37, 0
	s_waitcnt vmcnt(15)
	v_lshlrev_b32_e32 v172, 16, v68
	v_and_b32_e32 v173, 0xffff0000, v68
	v_lshlrev_b32_e32 v174, 16, v69
	v_and_b32_e32 v175, 0xffff0000, v69
	v_lshlrev_b32_e32 v176, 16, v70
	v_and_b32_e32 v177, 0xffff0000, v70
	v_lshlrev_b32_e32 v178, 16, v71
	v_and_b32_e32 v179, 0xffff0000, v71
	v_pk_add_f32 v[164:165], v[164:165], v[172:173]
	v_pk_add_f32 v[166:167], v[166:167], v[174:175]
	v_pk_add_f32 v[168:169], v[168:169], v[176:177]
	v_pk_add_f32 v[170:171], v[170:171], v[178:179]
	v_lshlrev_b32_e32 v180, 16, v60
	v_and_b32_e32 v181, 0xffff0000, v60
	v_lshlrev_b32_e32 v182, 16, v61
	v_and_b32_e32 v183, 0xffff0000, v61
	v_lshlrev_b32_e32 v184, 16, v62
	v_and_b32_e32 v185, 0xffff0000, v62
	v_lshlrev_b32_e32 v186, 16, v63
	v_and_b32_e32 v187, 0xffff0000, v63
	v_sub_f32_e32 v164, v164, v180
	v_sub_f32_e32 v165, v165, v181
	v_sub_f32_e32 v166, v166, v182
	v_sub_f32_e32 v167, v167, v183
	v_sub_f32_e32 v168, v168, v184
	v_sub_f32_e32 v169, v169, v185
	v_sub_f32_e32 v170, v170, v186
	v_sub_f32_e32 v171, v171, v187
	v_fma_f32 v188, v164, s72, -v172
	v_fma_f32 v189, v165, s72, -v173
	v_fma_f32 v190, v166, s72, -v174
	v_fma_f32 v191, v167, s72, -v175
	v_fma_f32 v192, v168, s72, -v176
	v_fma_f32 v193, v169, s72, -v177
	v_fma_f32 v194, v170, s72, -v178
	v_fma_f32 v195, v171, s72, -v179
	v_cvt_pk_bf16_f32 v196, v188, v189
	v_cvt_pk_bf16_f32 v197, v190, v191
	v_cvt_pk_bf16_f32 v198, v192, v193
	v_cvt_pk_bf16_f32 v199, v194, v195
	global_store_dwordx4 v39, v[196:199], s[36:37]
	s_add_u32 s36, s36, 0x1000
	s_addc_u32 s37, s37, 0
	s_waitcnt vmcnt(15)
	v_lshlrev_b32_e32 v172, 16, v72
	v_and_b32_e32 v173, 0xffff0000, v72
	v_lshlrev_b32_e32 v174, 16, v73
	v_and_b32_e32 v175, 0xffff0000, v73
	v_lshlrev_b32_e32 v176, 16, v74
	v_and_b32_e32 v177, 0xffff0000, v74
	v_lshlrev_b32_e32 v178, 16, v75
	v_and_b32_e32 v179, 0xffff0000, v75
	v_pk_add_f32 v[164:165], v[164:165], v[172:173]
	v_pk_add_f32 v[166:167], v[166:167], v[174:175]
	v_pk_add_f32 v[168:169], v[168:169], v[176:177]
	v_pk_add_f32 v[170:171], v[170:171], v[178:179]
	v_lshlrev_b32_e32 v180, 16, v64
	v_and_b32_e32 v181, 0xffff0000, v64
	v_lshlrev_b32_e32 v182, 16, v65
	v_and_b32_e32 v183, 0xffff0000, v65
	v_lshlrev_b32_e32 v184, 16, v66
	v_and_b32_e32 v185, 0xffff0000, v66
	v_lshlrev_b32_e32 v186, 16, v67
	v_and_b32_e32 v187, 0xffff0000, v67
	v_sub_f32_e32 v164, v164, v180
	v_sub_f32_e32 v165, v165, v181
	v_sub_f32_e32 v166, v166, v182
	v_sub_f32_e32 v167, v167, v183
	v_sub_f32_e32 v168, v168, v184
	v_sub_f32_e32 v169, v169, v185
	v_sub_f32_e32 v170, v170, v186
	v_sub_f32_e32 v171, v171, v187
	v_fma_f32 v188, v164, s72, -v172
	v_fma_f32 v189, v165, s72, -v173
	v_fma_f32 v190, v166, s72, -v174
	v_fma_f32 v191, v167, s72, -v175
	v_fma_f32 v192, v168, s72, -v176
	v_fma_f32 v193, v169, s72, -v177
	v_fma_f32 v194, v170, s72, -v178
	v_fma_f32 v195, v171, s72, -v179
	v_cvt_pk_bf16_f32 v196, v188, v189
	v_cvt_pk_bf16_f32 v197, v190, v191
	v_cvt_pk_bf16_f32 v198, v192, v193
	v_cvt_pk_bf16_f32 v199, v194, v195
	global_store_dwordx4 v39, v[196:199], s[36:37]
	s_add_u32 s36, s36, 0x1000
	s_addc_u32 s37, s37, 0
	s_waitcnt vmcnt(15)
	v_lshlrev_b32_e32 v172, 16, v76
	v_and_b32_e32 v173, 0xffff0000, v76
	v_lshlrev_b32_e32 v174, 16, v77
	v_and_b32_e32 v175, 0xffff0000, v77
	v_lshlrev_b32_e32 v176, 16, v78
	v_and_b32_e32 v177, 0xffff0000, v78
	v_lshlrev_b32_e32 v178, 16, v79
	v_and_b32_e32 v179, 0xffff0000, v79
	v_pk_add_f32 v[164:165], v[164:165], v[172:173]
	v_pk_add_f32 v[166:167], v[166:167], v[174:175]
	v_pk_add_f32 v[168:169], v[168:169], v[176:177]
	v_pk_add_f32 v[170:171], v[170:171], v[178:179]
	v_lshlrev_b32_e32 v180, 16, v68
	v_and_b32_e32 v181, 0xffff0000, v68
	v_lshlrev_b32_e32 v182, 16, v69
	v_and_b32_e32 v183, 0xffff0000, v69
	v_lshlrev_b32_e32 v184, 16, v70
	v_and_b32_e32 v185, 0xffff0000, v70
	v_lshlrev_b32_e32 v186, 16, v71
	v_and_b32_e32 v187, 0xffff0000, v71
	v_sub_f32_e32 v164, v164, v180
	v_sub_f32_e32 v165, v165, v181
	v_sub_f32_e32 v166, v166, v182
	v_sub_f32_e32 v167, v167, v183
	v_sub_f32_e32 v168, v168, v184
	v_sub_f32_e32 v169, v169, v185
	v_sub_f32_e32 v170, v170, v186
	v_sub_f32_e32 v171, v171, v187
	v_fma_f32 v188, v164, s72, -v172
	v_fma_f32 v189, v165, s72, -v173
	v_fma_f32 v190, v166, s72, -v174
	v_fma_f32 v191, v167, s72, -v175
	v_fma_f32 v192, v168, s72, -v176
	v_fma_f32 v193, v169, s72, -v177
	v_fma_f32 v194, v170, s72, -v178
	v_fma_f32 v195, v171, s72, -v179
	v_cvt_pk_bf16_f32 v196, v188, v189
	v_cvt_pk_bf16_f32 v197, v190, v191
	v_cvt_pk_bf16_f32 v198, v192, v193
	v_cvt_pk_bf16_f32 v199, v194, v195
	global_store_dwordx4 v39, v[196:199], s[36:37]
	s_add_u32 s36, s36, 0x1000
	s_addc_u32 s37, s37, 0
	s_waitcnt vmcnt(15)
; __device__ __forceinline__ u32x4 pack8(const f32x4 v0, const f32x4 v1) { u32x4 w; w.x = cvt_pk_bf16(v0[0], v0[1]); w.y = cvt_pk_bf16(v0[2], v0[3]); w.z = cvt_pk_bf16(v1[0], v1[1]); w.w = cvt_pk_bf16(v1[2], v1[3]); return w; }
; __device__ __forceinline__ void unpack8(const u32x4 w, f32x4& lo, f32x4& hi) { lo = (f32x4){bf_lo(w.x), bf_hi(w.x), bf_lo(w.y), bf_hi(w.y)}; hi = (f32x4){bf_lo(w.z), bf_hi(w.z), bf_lo(w.w), bf_hi(w.w)}; }
; __device__ __forceinline__ void phase_pool(const bf16_t* PROJ, bf16_t* Z, int gw, int NGW, int lane) {
;     ...
;         for (int t = t0; t < t0 + 16; ++t) {
;             f32x4 v0, v1; unpack8(*(const u32x4*)(vb + (size_t)t * DIN), v0, v1); s0 += v0; s1 += v1;
;             if (t > t0 && t - win >= 0) { f32x4 a, c; unpack8(*(const u32x4*)(vb + (size_t)(t - win) * DIN), a, c); s0 -= a; s1 -= c; }
;             const float inv = 1.f / (float)((t + 1) < win ? (t + 1) : win);
;             *(u32x4*)(zb + (size_t)t * DSS) = pack8(s0 * inv - v0, s1 * inv - v1);
	v_lshlrev_b32_e32 v172, 16, v80
	v_and_b32_e32 v173, 0xffff0000, v80
	v_lshlrev_b32_e32 v174, 16, v81
	v_and_b32_e32 v175, 0xffff0000, v81
	v_lshlrev_b32_e32 v176, 16, v82
	v_and_b32_e32 v177, 0xffff0000, v82
	v_lshlrev_b32_e32 v178, 16, v83
	v_and_b32_e32 v179, 0xffff0000, v83
	v_pk_add_f32 v[164:165], v[164:165], v[172:173]
	v_pk_add_f32 v[166:167], v[166:167], v[174:175]
	v_pk_add_f32 v[168:169], v[168:169], v[176:177]
	v_pk_add_f32 v[170:171], v[170:171], v[178:179]
	v_lshlrev_b32_e32 v180, 16, v72
	v_and_b32_e32 v181, 0xffff0000, v72
	v_lshlrev_b32_e32 v182, 16, v73
	v_and_b32_e32 v183, 0xffff0000, v73
	v_lshlrev_b32_e32 v184, 16, v74
	v_and_b32_e32 v185, 0xffff0000, v74
	v_lshlrev_b32_e32 v186, 16, v75
	v_and_b32_e32 v187, 0xffff0000, v75
	v_sub_f32_e32 v164, v164, v180
	v_sub_f32_e32 v165, v165, v181
	v_sub_f32_e32 v166, v166, v182
	v_sub_f32_e32 v167, v167, v183
	v_sub_f32_e32 v168, v168, v184
	v_sub_f32_e32 v169, v169, v185
	v_sub_f32_e32 v170, v170, v186
	v_sub_f32_e32 v171, v171, v187
	v_fma_f32 v188, v164, s72, -v172
	v_fma_f32 v189, v165, s72, -v173
	v_fma_f32 v190, v166, s72, -v174
	v_fma_f32 v191, v167, s72, -v175
	v_fma_f32 v192, v168, s72, -v176
	v_fma_f32 v193, v169, s72, -v177
	v_fma_f32 v194, v170, s72, -v178
	v_fma_f32 v195, v171, s72, -v179
	v_cvt_pk_bf16_f32 v196, v188, v189
	v_cvt_pk_bf16_f32 v197, v190, v191
	v_cvt_pk_bf16_f32 v198, v192, v193
	v_cvt_pk_bf16_f32 v199, v194, v195
	global_store_dwordx4 v39, v[196:199], s[36:37]
	s_add_u32 s36, s36, 0x1000
	s_addc_u32 s37, s37, 0
	s_waitcnt vmcnt(15)
	v_lshlrev_b32_e32 v172, 16, v84
	v_and_b32_e32 v173, 0xffff0000, v84
	v_lshlrev_b32_e32 v174, 16, v85
	v_and_b32_e32 v175, 0xffff0000, v85
	v_lshlrev_b32_e32 v176, 16, v86
	v_and_b32_e32 v177, 0xffff0000, v86
	v_lshlrev_b32_e32 v178, 16, v87
	v_and_b32_e32 v179, 0xffff0000, v87
	v_pk_add_f32 v[164:165], v[164:165], v[172:173]
	v_pk_add_f32 v[166:167], v[166:167], v[174:175]
	v_pk_add_f32 v[168:169], v[168:169], v[176:177]
	v_pk_add_f32 v[170:171], v[170:171], v[178:179]
	v_lshlrev_b32_e32 v180, 16, v76
	v_and_b32_e32 v181, 0xffff0000, v76
	v_lshlrev_b32_e32 v182, 16, v77
	v_and_b32_e32 v183, 0xffff0000, v77
	v_lshlrev_b32_e32 v184, 16, v78
	v_and_b32_e32 v185, 0xffff0000, v78
	v_lshlrev_b32_e32 v186, 16, v79
	v_and_b32_e32 v187, 0xffff0000, v79
	v_sub_f32_e32 v164, v164, v180
	v_sub_f32_e32 v165, v165, v181
	v_sub_f32_e32 v166, v166, v182
	v_sub_f32_e32 v167, v167, v183
	v_sub_f32_e32 v168, v168, v184
	v_sub_f32_e32 v169, v169, v185
	v_sub_f32_e32 v170, v170, v186
	v_sub_f32_e32 v171, v171, v187
	v_fma_f32 v188, v164, s72, -v172
	v_fma_f32 v189, v165, s72, -v173
	v_fma_f32 v190, v166, s72, -v174
	v_fma_f32 v191, v167, s72, -v175
	v_fma_f32 v192, v168, s72, -v176
	v_fma_f32 v193, v169, s72, -v177
	v_fma_f32 v194, v170, s72, -v178
	v_fma_f32 v195, v171, s72, -v179
	v_cvt_pk_bf16_f32 v196, v188, v189
	v_cvt_pk_bf16_f32 v197, v190, v191
	v_cvt_pk_bf16_f32 v198, v192, v193
	v_cvt_pk_bf16_f32 v199, v194, v195
	global_store_dwordx4 v39, v[196:199], s[36:37]
	s_add_u32 s36, s36, 0x1000
	s_addc_u32 s37, s37, 0
	s_waitcnt vmcnt(15)
	v_lshlrev_b32_e32 v172, 16, v88
	v_and_b32_e32 v173, 0xffff0000, v88
	v_lshlrev_b32_e32 v174, 16, v89
	v_and_b32_e32 v175, 0xffff0000, v89
	v_lshlrev_b32_e32 v176, 16, v90
	v_and_b32_e32 v177, 0xffff0000, v90
	v_lshlrev_b32_e32 v178, 16, v91
	v_and_b32_e32 v179, 0xffff0000, v91
	v_pk_add_f32 v[164:165], v[164:165], v[172:173]
	v_pk_add_f32 v[166:167], v[166:167], v[174:175]
	v_pk_add_f32 v[168:169], v[168:169], v[176:177]
	v_pk_add_f32 v[170:171], v[170:171], v[178:179]
	v_lshlrev_b32_e32 v180, 16, v80
	v_and_b32_e32 v181, 0xffff0000, v80
	v_lshlrev_b32_e32 v182, 16, v81
	v_and_b32_e32 v183, 0xffff0000, v81
	v_lshlrev_b32_e32 v184, 16, v82
	v_and_b32_e32 v185, 0xffff0000, v82
	v_lshlrev_b32_e32 v186, 16, v83
	v_and_b32_e32 v187, 0xffff0000, v83
	v_sub_f32_e32 v164, v164, v180
	v_sub_f32_e32 v165, v165, v181
	v_sub_f32_e32 v166, v166, v182
	v_sub_f32_e32 v167, v167, v183
	v_sub_f32_e32 v168, v168, v184
	v_sub_f32_e32 v169, v169, v185
	v_sub_f32_e32 v170, v170, v186
	v_sub_f32_e32 v171, v171, v187
	v_fma_f32 v188, v164, s72, -v172
	v_fma_f32 v189, v165, s72, -v173
	v_fma_f32 v190, v166, s72, -v174
	v_fma_f32 v191, v167, s72, -v175
	v_fma_f32 v192, v168, s72, -v176
	v_fma_f32 v193, v169, s72, -v177
	v_fma_f32 v194, v170, s72, -v178
	v_fma_f32 v195, v171, s72, -v179
	v_cvt_pk_bf16_f32 v196, v188, v189
	v_cvt_pk_bf16_f32 v197, v190, v191
	v_cvt_pk_bf16_f32 v198, v192, v193
	v_cvt_pk_bf16_f32 v199, v194, v195
	global_store_dwordx4 v39, v[196:199], s[36:37]
	s_add_u32 s36, s36, 0x1000
	s_addc_u32 s37, s37, 0
	s_waitcnt vmcnt(15)
; __device__ __forceinline__ u32x4 pack8(const f32x4 v0, const f32x4 v1) { u32x4 w; w.x = cvt_pk_bf16(v0[0], v0[1]); w.y = cvt_pk_bf16(v0[2], v0[3]); w.z = cvt_pk_bf16(v1[0], v1[1]); w.w = cvt_pk_bf16(v1[2], v1[3]); return w; }
; __device__ __forceinline__ void unpack8(const u32x4 w, f32x4& lo, f32x4& hi) { lo = (f32x4){bf_lo(w.x), bf_hi(w.x), bf_lo(w.y), bf_hi(w.y)}; hi = (f32x4){bf_lo(w.z), bf_hi(w.z), bf_lo(w.w), bf_hi(w.w)}; }
; __device__ __forceinline__ void phase_pool(const bf16_t* PROJ, bf16_t* Z, int gw, int NGW, int lane) {
;     ...
;         for (int t = t0; t < t0 + 16; ++t) {
;             f32x4 v0, v1; unpack8(*(const u32x4*)(vb + (size_t)t * DIN), v0, v1); s0 += v0; s1 += v1;
;             if (t > t0 && t - win >= 0) { f32x4 a, c; unpack8(*(const u32x4*)(vb + (size_t)(t - win) * DIN), a, c); s0 -= a; s1 -= c; }
;             const float inv = 1.f / (float)((t + 1) < win ? (t + 1) : win);
;             *(u32x4*)(zb + (size_t)t * DSS) = pack8(s0 * inv - v0, s1 * inv - v1);
;         }
	v_lshlrev_b32_e32 v172, 16, v92
	v_and_b32_e32 v173, 0xffff0000, v92
	v_lshlrev_b32_e32 v174, 16, v93
	v_and_b32_e32 v175, 0xffff0000, v93
	v_lshlrev_b32_e32 v176, 16, v94
	v_and_b32_e32 v177, 0xffff0000, v94
	v_lshlrev_b32_e32 v178, 16, v95
	v_and_b32_e32 v179, 0xffff0000, v95
	v_pk_add_f32 v[164:165], v[164:165], v[172:173]
	v_pk_add_f32 v[166:167], v[166:167], v[174:175]
	v_pk_add_f32 v[168:169], v[168:169], v[176:177]
	v_pk_add_f32 v[170:171], v[170:171], v[178:179]
	v_lshlrev_b32_e32 v180, 16, v84
	v_and_b32_e32 v181, 0xffff0000, v84
	v_lshlrev_b32_e32 v182, 16, v85
	v_and_b32_e32 v183, 0xffff0000, v85
	v_lshlrev_b32_e32 v184, 16, v86
	v_and_b32_e32 v185, 0xffff0000, v86
	v_lshlrev_b32_e32 v186, 16, v87
	v_and_b32_e32 v187, 0xffff0000, v87
	v_sub_f32_e32 v164, v164, v180
	v_sub_f32_e32 v165, v165, v181
	v_sub_f32_e32 v166, v166, v182
	v_sub_f32_e32 v167, v167, v183
	v_sub_f32_e32 v168, v168, v184
	v_sub_f32_e32 v169, v169, v185
	v_sub_f32_e32 v170, v170, v186
	v_sub_f32_e32 v171, v171, v187
	v_fma_f32 v188, v164, s72, -v172
	v_fma_f32 v189, v165, s72, -v173
	v_fma_f32 v190, v166, s72, -v174
	v_fma_f32 v191, v167, s72, -v175
	v_fma_f32 v192, v168, s72, -v176
	v_fma_f32 v193, v169, s72, -v177
	v_fma_f32 v194, v170, s72, -v178
	v_fma_f32 v195, v171, s72, -v179
	v_cvt_pk_bf16_f32 v196, v188, v189
	v_cvt_pk_bf16_f32 v197, v190, v191
	v_cvt_pk_bf16_f32 v198, v192, v193
	v_cvt_pk_bf16_f32 v199, v194, v195
	global_store_dwordx4 v39, v[196:199], s[36:37]
	s_add_u32 s36, s36, 0x1000
	s_addc_u32 s37, s37, 0
	s_waitcnt vmcnt(15)
	v_lshlrev_b32_e32 v172, 16, v96
	v_and_b32_e32 v173, 0xffff0000, v96
	v_lshlrev_b32_e32 v174, 16, v97
	v_and_b32_e32 v175, 0xffff0000, v97
	v_lshlrev_b32_e32 v176, 16, v98
	v_and_b32_e32 v177, 0xffff0000, v98
	v_lshlrev_b32_e32 v178, 16, v99
	v_and_b32_e32 v179, 0xffff0000, v99
	v_pk_add_f32 v[164:165], v[164:165], v[172:173]
	v_pk_add_f32 v[166:167], v[166:167], v[174:175]
	v_pk_add_f32 v[168:169], v[168:169], v[176:177]
	v_pk_add_f32 v[170:171], v[170:171], v[178:179]
	v_lshlrev_b32_e32 v180, 16, v88
	v_and_b32_e32 v181, 0xffff0000, v88
	v_lshlrev_b32_e32 v182, 16, v89
	v_and_b32_e32 v183, 0xffff0000, v89
	v_lshlrev_b32_e32 v184, 16, v90
	v_and_b32_e32 v185, 0xffff0000, v90
	v_lshlrev_b32_e32 v186, 16, v91
	v_and_b32_e32 v187, 0xffff0000, v91
	v_sub_f32_e32 v164, v164, v180
	v_sub_f32_e32 v165, v165, v181
	v_sub_f32_e32 v166, v166, v182
	v_sub_f32_e32 v167, v167, v183
	v_sub_f32_e32 v168, v168, v184
	v_sub_f32_e32 v169, v169, v185
	v_sub_f32_e32 v170, v170, v186
	v_sub_f32_e32 v171, v171, v187
	v_fma_f32 v188, v164, s72, -v172
	v_fma_f32 v189, v165, s72, -v173
	v_fma_f32 v190, v166, s72, -v174
	v_fma_f32 v191, v167, s72, -v175
	v_fma_f32 v192, v168, s72, -v176
	v_fma_f32 v193, v169, s72, -v177
	v_fma_f32 v194, v170, s72, -v178
	v_fma_f32 v195, v171, s72, -v179
	v_cvt_pk_bf16_f32 v196, v188, v189
	v_cvt_pk_bf16_f32 v197, v190, v191
	v_cvt_pk_bf16_f32 v198, v192, v193
	v_cvt_pk_bf16_f32 v199, v194, v195
	global_store_dwordx4 v39, v[196:199], s[36:37]
	s_add_u32 s36, s36, 0x1000
	s_addc_u32 s37, s37, 0
	s_waitcnt vmcnt(15)
	v_lshlrev_b32_e32 v172, 16, v100
	v_and_b32_e32 v173, 0xffff0000, v100
	v_lshlrev_b32_e32 v174, 16, v101
	v_and_b32_e32 v175, 0xffff0000, v101
	v_lshlrev_b32_e32 v176, 16, v102
	v_and_b32_e32 v177, 0xffff0000, v102
	v_lshlrev_b32_e32 v178, 16, v103
	v_and_b32_e32 v179, 0xffff0000, v103
	v_pk_add_f32 v[164:165], v[164:165], v[172:173]
	v_pk_add_f32 v[166:167], v[166:167], v[174:175]
	v_pk_add_f32 v[168:169], v[168:169], v[176:177]
	v_pk_add_f32 v[170:171], v[170:171], v[178:179]
	v_lshlrev_b32_e32 v180, 16, v92
	v_and_b32_e32 v181, 0xffff0000, v92
	v_lshlrev_b32_e32 v182, 16, v93
	v_and_b32_e32 v183, 0xffff0000, v93
	v_lshlrev_b32_e32 v184, 16, v94
	v_and_b32_e32 v185, 0xffff0000, v94
	v_lshlrev_b32_e32 v186, 16, v95
	v_and_b32_e32 v187, 0xffff0000, v95
	v_sub_f32_e32 v164, v164, v180
	v_sub_f32_e32 v165, v165, v181
	v_sub_f32_e32 v166, v166, v182
	v_sub_f32_e32 v167, v167, v183
	v_sub_f32_e32 v168, v168, v184
	v_sub_f32_e32 v169, v169, v185
	v_sub_f32_e32 v170, v170, v186
	v_sub_f32_e32 v171, v171, v187
	v_fma_f32 v188, v164, s72, -v172
	v_fma_f32 v189, v165, s72, -v173
	v_fma_f32 v190, v166, s72, -v174
	v_fma_f32 v191, v167, s72, -v175
	v_fma_f32 v192, v168, s72, -v176
	v_fma_f32 v193, v169, s72, -v177
	v_fma_f32 v194, v170, s72, -v178
	v_fma_f32 v195, v171, s72, -v179
	v_cvt_pk_bf16_f32 v196, v188, v189
	v_cvt_pk_bf16_f32 v197, v190, v191
	v_cvt_pk_bf16_f32 v198, v192, v193
	v_cvt_pk_bf16_f32 v199, v194, v195
	global_store_dwordx4 v39, v[196:199], s[36:37]
	s_branch .LBB0_300
